# baseline (speedup 1.0000x reference)
; #define STAGE(Pp, BASE, br, kt) do { const u16* _g = (BASE) + ((long)(br) * K + (long)(kt) * BK); \
;     __builtin_amdgcn_global_load_lds((const unsigned*)(_g + voff0), (unsigned*)((char*)(Pp) + tb16), 16, 0, 0); \
;     __builtin_amdgcn_global_load_lds((const unsigned*)(_g + voff1), (unsigned*)((char*)(Pp) + tb16 + 8192), 16, 0, 0); } while (0)
; #define LDA(dst, b, h) _Pragma("unroll") for (int m = 0; m < 4; ++m) _Pragma("unroll") for (int k = 0; k < 2; ++k) \
;     dst[m][k] = *reinterpret_cast<const bf16x8*>((const char*)shm + aB + (((b) * 2 + (h)) * 16384 + (m * 2 + k) * 1024))
; #define LDB(dst, b, h) _Pragma("unroll") for (int n = 0; n < 2; ++n) _Pragma("unroll") for (int k = 0; k < 2; ++k) \
;     dst[n][k] = *reinterpret_cast<const bf16x8*>((const char*)shm + bB + (((b) * 2 + (h)) * 16384 + (n * 2 + k) * 1024))
; #define WAIT_V(n) asm volatile("s_waitcnt vmcnt(" #n ")" ::: "memory")
; #define WAIT_L(n) asm volatile("s_waitcnt lgkmcnt(" #n ")" ::: "memory")
; #define BAR __builtin_amdgcn_s_barrier()
; #define SCHED __builtin_amdgcn_sched_barrier(0)
; template <int MODE> ...
;     ...
;       LDB(B0, 0, 0); LDB(B1, 0, 1); LDA(At, 0, 0); STAGE(SA(1, 1), A, brow + HALF, t + 1);
;       WAIT_L(0); BAR; MMA2(0, 0, 0, 1); BAR; SCHED;
;       LDA(At, 0, 1); STAGE(SB(0, 0), Bt, bcol, t + 2); STAGE(SB(0, 1), Bt, bcol + HALF, t + 2); STAGE(SA(0, 0), A, brow, t + 2);
;       WAIT_V(6); WAIT_L(0); BAR; MMA2(1, 0, 1, 1); BAR; SCHED;
.LBB0_154:
	s_add_u32 m0, s32, 0xc000
	ds_read_b128 v[170:173], v149
	ds_read_b128 v[174:177], v149 offset:1024
	ds_read_b128 v[178:181], v149 offset:2048
	ds_read_b128 v[182:185], v149 offset:3072
	ds_read_b128 v[186:189], v149 offset:16384
	ds_read_b128 v[190:193], v149 offset:17408
	ds_read_b128 v[194:197], v149 offset:18432
	ds_read_b128 v[198:201], v149 offset:19456
	ds_read_b128 v[202:205], v151
	ds_read_b128 v[206:209], v151 offset:1024
	ds_read_b128 v[210:213], v151 offset:2048
	ds_read_b128 v[214:217], v151 offset:3072
	ds_read_b128 v[218:221], v151 offset:4096
	ds_read_b128 v[222:225], v151 offset:5120
	ds_read_b128 v[226:229], v151 offset:6144
	ds_read_b128 v[230:233], v151 offset:7168
	s_add_u32 s88, s74, s40
	s_addc_u32 s89, s75, s41
	global_load_lds_dwordx4 v142, s[88:89]
	s_add_u32 m0, s32, 0xe000
	s_nop 0
	global_load_lds_dwordx4 v144, s[88:89]
	s_waitcnt lgkmcnt(0)
	s_barrier
	s_setprio 1
	s_waitcnt lgkmcnt(0)
	v_mfma_f32_16x16x32_bf16 v[124:127], v[202:205], v[170:173], v[124:127]
	v_mfma_f32_16x16x32_bf16 v[120:123], v[202:205], v[178:181], v[120:123]
	v_mfma_f32_16x16x32_bf16 v[116:119], v[210:213], v[170:173], v[116:119]
	v_mfma_f32_16x16x32_bf16 v[112:115], v[210:213], v[178:181], v[112:115]
	v_mfma_f32_16x16x32_bf16 v[108:111], v[218:221], v[170:173], v[108:111]
	v_mfma_f32_16x16x32_bf16 v[104:107], v[218:221], v[178:181], v[104:107]
	v_mfma_f32_16x16x32_bf16 v[100:103], v[226:229], v[170:173], v[100:103]
	v_mfma_f32_16x16x32_bf16 v[96:99], v[226:229], v[178:181], v[96:99]
	v_mfma_f32_16x16x32_bf16 v[92:95], v[202:205], v[186:189], v[92:95]
	v_mfma_f32_16x16x32_bf16 v[88:91], v[202:205], v[194:197], v[88:91]
	v_mfma_f32_16x16x32_bf16 v[84:87], v[210:213], v[186:189], v[84:87]
	v_mfma_f32_16x16x32_bf16 v[80:83], v[210:213], v[194:197], v[80:83]
	v_mfma_f32_16x16x32_bf16 v[76:79], v[218:221], v[186:189], v[76:79]
	v_mfma_f32_16x16x32_bf16 v[72:75], v[218:221], v[194:197], v[72:75]
	v_mfma_f32_16x16x32_bf16 v[68:71], v[226:229], v[186:189], v[68:71]
	v_mfma_f32_16x16x32_bf16 v[64:67], v[226:229], v[194:197], v[64:67]
	v_mfma_f32_16x16x32_bf16 v[124:127], v[206:209], v[174:177], v[124:127]
	v_mfma_f32_16x16x32_bf16 v[120:123], v[206:209], v[182:185], v[120:123]
	v_mfma_f32_16x16x32_bf16 v[116:119], v[214:217], v[174:177], v[116:119]
	v_mfma_f32_16x16x32_bf16 v[112:115], v[214:217], v[182:185], v[112:115]
	v_mfma_f32_16x16x32_bf16 v[108:111], v[222:225], v[174:177], v[108:111]
	v_mfma_f32_16x16x32_bf16 v[104:107], v[222:225], v[182:185], v[104:107]
	v_mfma_f32_16x16x32_bf16 v[100:103], v[230:233], v[174:177], v[100:103]
	v_mfma_f32_16x16x32_bf16 v[96:99], v[230:233], v[182:185], v[96:99]
	v_mfma_f32_16x16x32_bf16 v[92:95], v[206:209], v[190:193], v[92:95]
	v_mfma_f32_16x16x32_bf16 v[88:91], v[206:209], v[198:201], v[88:91]
	v_mfma_f32_16x16x32_bf16 v[84:87], v[214:217], v[190:193], v[84:87]
	v_mfma_f32_16x16x32_bf16 v[80:83], v[214:217], v[198:201], v[80:83]
	v_mfma_f32_16x16x32_bf16 v[76:79], v[222:225], v[190:193], v[76:79]
	v_mfma_f32_16x16x32_bf16 v[72:75], v[222:225], v[198:201], v[72:75]
	v_mfma_f32_16x16x32_bf16 v[68:71], v[230:233], v[190:193], v[68:71]
	v_mfma_f32_16x16x32_bf16 v[64:67], v[230:233], v[198:201], v[64:67]
	s_setprio 0
	s_barrier
	s_add_u32 m0, s32, 0x10000
	ds_read_b128 v[202:205], v151 offset:16384
	ds_read_b128 v[206:209], v151 offset:17408
	ds_read_b128 v[210:213], v151 offset:18432
	ds_read_b128 v[214:217], v151 offset:19456
	ds_read_b128 v[218:221], v151 offset:20480
	ds_read_b128 v[222:225], v151 offset:21504
	ds_read_b128 v[226:229], v151 offset:22528
	ds_read_b128 v[230:233], v151 offset:23552
	s_add_u32 s88, s74, s42
	s_addc_u32 s89, s75, s43
	global_load_lds_dwordx4 v138, s[88:89]
	s_add_u32 m0, s32, 0x12000
	s_add_u32 s90, s74, s44
	s_addc_u32 s91, s75, s45
	global_load_lds_dwordx4 v140, s[88:89]
	s_add_u32 m0, s32, 0x14000
	s_add_u32 s92, s74, s48
	s_addc_u32 s93, s75, s49
	global_load_lds_dwordx4 v138, s[90:91]
	s_add_u32 m0, s32, 0x16000
	s_nop 0
	global_load_lds_dwordx4 v140, s[90:91]
	s_mov_b32 m0, s32
	s_nop 0
	global_load_lds_dwordx4 v142, s[92:93]
	s_add_u32 m0, s32, 0x2000
	s_nop 0
	global_load_lds_dwordx4 v144, s[92:93]
	s_waitcnt vmcnt(6)
	s_waitcnt lgkmcnt(0)
	s_barrier
	s_setprio 1
	s_waitcnt lgkmcnt(0)
	v_mfma_f32_16x16x32_bf16 v[60:63], v[202:205], v[170:173], v[60:63]
	v_mfma_f32_16x16x32_bf16 v[56:59], v[202:205], v[178:181], v[56:59]
	v_mfma_f32_16x16x32_bf16 v[52:55], v[210:213], v[170:173], v[52:55]
	v_mfma_f32_16x16x32_bf16 v[48:51], v[210:213], v[178:181], v[48:51]
	v_mfma_f32_16x16x32_bf16 v[44:47], v[218:221], v[170:173], v[44:47]
	v_mfma_f32_16x16x32_bf16 v[40:43], v[218:221], v[178:181], v[40:43]
	v_mfma_f32_16x16x32_bf16 v[36:39], v[226:229], v[170:173], v[36:39]
	v_mfma_f32_16x16x32_bf16 v[32:35], v[226:229], v[178:181], v[32:35]
	v_mfma_f32_16x16x32_bf16 v[28:31], v[202:205], v[186:189], v[28:31]
	v_mfma_f32_16x16x32_bf16 v[24:27], v[202:205], v[194:197], v[24:27]
	v_mfma_f32_16x16x32_bf16 v[20:23], v[210:213], v[186:189], v[20:23]
	v_mfma_f32_16x16x32_bf16 v[16:19], v[210:213], v[194:197], v[16:19]
	v_mfma_f32_16x16x32_bf16 v[12:15], v[218:221], v[186:189], v[12:15]
	v_mfma_f32_16x16x32_bf16 v[8:11], v[218:221], v[194:197], v[8:11]
	v_mfma_f32_16x16x32_bf16 v[4:7], v[226:229], v[186:189], v[4:7]
	v_mfma_f32_16x16x32_bf16 v[0:3], v[226:229], v[194:197], v[0:3]
	v_mfma_f32_16x16x32_bf16 v[60:63], v[206:209], v[174:177], v[60:63]
	v_mfma_f32_16x16x32_bf16 v[56:59], v[206:209], v[182:185], v[56:59]
	v_mfma_f32_16x16x32_bf16 v[52:55], v[214:217], v[174:177], v[52:55]
	v_mfma_f32_16x16x32_bf16 v[48:51], v[214:217], v[182:185], v[48:51]
	v_mfma_f32_16x16x32_bf16 v[44:47], v[222:225], v[174:177], v[44:47]
	v_mfma_f32_16x16x32_bf16 v[40:43], v[222:225], v[182:185], v[40:43]
	v_mfma_f32_16x16x32_bf16 v[36:39], v[230:233], v[174:177], v[36:39]
	v_mfma_f32_16x16x32_bf16 v[32:35], v[230:233], v[182:185], v[32:35]
	v_mfma_f32_16x16x32_bf16 v[28:31], v[206:209], v[190:193], v[28:31]
	v_mfma_f32_16x16x32_bf16 v[24:27], v[206:209], v[198:201], v[24:27]
	v_mfma_f32_16x16x32_bf16 v[20:23], v[214:217], v[190:193], v[20:23]
	v_mfma_f32_16x16x32_bf16 v[16:19], v[214:217], v[198:201], v[16:19]
	v_mfma_f32_16x16x32_bf16 v[12:15], v[222:225], v[190:193], v[12:15]
	v_mfma_f32_16x16x32_bf16 v[8:11], v[222:225], v[198:201], v[8:11]
	v_mfma_f32_16x16x32_bf16 v[4:7], v[230:233], v[190:193], v[4:7]
	v_mfma_f32_16x16x32_bf16 v[0:3], v[230:233], v[198:201], v[0:3]
	s_setprio 0
	s_barrier
; #define STAGE(Pp, BASE, br, kt) do { const u16* _g = (BASE) + ((long)(br) * K + (long)(kt) * BK); \
;     __builtin_amdgcn_global_load_lds((const unsigned*)(_g + voff0), (unsigned*)((char*)(Pp) + tb16), 16, 0, 0); \
;     __builtin_amdgcn_global_load_lds((const unsigned*)(_g + voff1), (unsigned*)((char*)(Pp) + tb16 + 8192), 16, 0, 0); } while (0)
; #define LDA(dst, b, h) _Pragma("unroll") for (int m = 0; m < 4; ++m) _Pragma("unroll") for (int k = 0; k < 2; ++k) \
;     dst[m][k] = *reinterpret_cast<const bf16x8*>((const char*)shm + aB + (((b) * 2 + (h)) * 16384 + (m * 2 + k) * 1024))
; #define LDB(dst, b, h) _Pragma("unroll") for (int n = 0; n < 2; ++n) _Pragma("unroll") for (int k = 0; k < 2; ++k) \
;     dst[n][k] = *reinterpret_cast<const bf16x8*>((const char*)shm + bB + (((b) * 2 + (h)) * 16384 + (n * 2 + k) * 1024))
; #define WAIT_V(n) asm volatile("s_waitcnt vmcnt(" #n ")" ::: "memory")
; #define WAIT_L(n) asm volatile("s_waitcnt lgkmcnt(" #n ")" ::: "memory")
; #define BAR __builtin_amdgcn_s_barrier()
; #define SCHED __builtin_amdgcn_sched_barrier(0)
; template <int MODE> ...
;     ...
;       LDB(B0, 1, 0); LDB(B1, 1, 1); LDA(At, 1, 0); STAGE(SA(0, 1), A, brow + HALF, t + 2);
;       WAIT_L(0); BAR; MMA2(0, 0, 0, 1); BAR; SCHED;
;       LDA(At, 1, 1); STAGE(SB(1, 0), Bt, bcol, t + 3); STAGE(SB(1, 1), Bt, bcol + HALF, t + 3); STAGE(SA(1, 0), A, brow, t + 3);
;       WAIT_V(6); WAIT_L(0); BAR; MMA2(1, 0, 1, 1); BAR; SCHED;
	s_add_u32 m0, s32, 0x4000
	ds_read_b128 v[170:173], v149 offset:32768
	ds_read_b128 v[174:177], v149 offset:33792
	ds_read_b128 v[178:181], v149 offset:34816
	ds_read_b128 v[182:185], v149 offset:35840
	ds_read_b128 v[186:189], v149 offset:49152
	ds_read_b128 v[190:193], v149 offset:50176
	ds_read_b128 v[194:197], v149 offset:51200
	ds_read_b128 v[198:201], v149 offset:52224
	ds_read_b128 v[202:205], v151 offset:32768
	ds_read_b128 v[206:209], v151 offset:33792
	ds_read_b128 v[210:213], v151 offset:34816
	ds_read_b128 v[214:217], v151 offset:35840
	ds_read_b128 v[218:221], v151 offset:36864
	ds_read_b128 v[222:225], v151 offset:37888
	ds_read_b128 v[226:229], v151 offset:38912
	ds_read_b128 v[230:233], v151 offset:39936
	s_add_u32 s88, s74, s50
	s_addc_u32 s89, s75, s51
	global_load_lds_dwordx4 v142, s[88:89]
	s_add_u32 m0, s32, 0x6000
	s_nop 0
	global_load_lds_dwordx4 v144, s[88:89]
	s_waitcnt lgkmcnt(0)
	s_barrier
	s_setprio 1
	s_waitcnt lgkmcnt(0)
	v_mfma_f32_16x16x32_bf16 v[124:127], v[202:205], v[170:173], v[124:127]
	v_mfma_f32_16x16x32_bf16 v[120:123], v[202:205], v[178:181], v[120:123]
	v_mfma_f32_16x16x32_bf16 v[116:119], v[210:213], v[170:173], v[116:119]
	v_mfma_f32_16x16x32_bf16 v[112:115], v[210:213], v[178:181], v[112:115]
	v_mfma_f32_16x16x32_bf16 v[108:111], v[218:221], v[170:173], v[108:111]
	v_mfma_f32_16x16x32_bf16 v[104:107], v[218:221], v[178:181], v[104:107]
	v_mfma_f32_16x16x32_bf16 v[100:103], v[226:229], v[170:173], v[100:103]
	v_mfma_f32_16x16x32_bf16 v[96:99], v[226:229], v[178:181], v[96:99]
	v_mfma_f32_16x16x32_bf16 v[92:95], v[202:205], v[186:189], v[92:95]
	v_mfma_f32_16x16x32_bf16 v[88:91], v[202:205], v[194:197], v[88:91]
	v_mfma_f32_16x16x32_bf16 v[84:87], v[210:213], v[186:189], v[84:87]
	v_mfma_f32_16x16x32_bf16 v[80:83], v[210:213], v[194:197], v[80:83]
	v_mfma_f32_16x16x32_bf16 v[76:79], v[218:221], v[186:189], v[76:79]
	v_mfma_f32_16x16x32_bf16 v[72:75], v[218:221], v[194:197], v[72:75]
	v_mfma_f32_16x16x32_bf16 v[68:71], v[226:229], v[186:189], v[68:71]
	v_mfma_f32_16x16x32_bf16 v[64:67], v[226:229], v[194:197], v[64:67]
	v_mfma_f32_16x16x32_bf16 v[124:127], v[206:209], v[174:177], v[124:127]
	v_mfma_f32_16x16x32_bf16 v[120:123], v[206:209], v[182:185], v[120:123]
	v_mfma_f32_16x16x32_bf16 v[116:119], v[214:217], v[174:177], v[116:119]
	v_mfma_f32_16x16x32_bf16 v[112:115], v[214:217], v[182:185], v[112:115]
	v_mfma_f32_16x16x32_bf16 v[108:111], v[222:225], v[174:177], v[108:111]
	v_mfma_f32_16x16x32_bf16 v[104:107], v[222:225], v[182:185], v[104:107]
	v_mfma_f32_16x16x32_bf16 v[100:103], v[230:233], v[174:177], v[100:103]
	v_mfma_f32_16x16x32_bf16 v[96:99], v[230:233], v[182:185], v[96:99]
	v_mfma_f32_16x16x32_bf16 v[92:95], v[206:209], v[190:193], v[92:95]
	v_mfma_f32_16x16x32_bf16 v[88:91], v[206:209], v[198:201], v[88:91]
	v_mfma_f32_16x16x32_bf16 v[84:87], v[214:217], v[190:193], v[84:87]
	v_mfma_f32_16x16x32_bf16 v[80:83], v[214:217], v[198:201], v[80:83]
	v_mfma_f32_16x16x32_bf16 v[76:79], v[222:225], v[190:193], v[76:79]
	v_mfma_f32_16x16x32_bf16 v[72:75], v[222:225], v[198:201], v[72:75]
	v_mfma_f32_16x16x32_bf16 v[68:71], v[230:233], v[190:193], v[68:71]
	v_mfma_f32_16x16x32_bf16 v[64:67], v[230:233], v[198:201], v[64:67]
	s_setprio 0
	s_barrier
	s_add_u32 m0, s32, 0x18000
	ds_read_b128 v[202:205], v151 offset:49152
	ds_read_b128 v[206:209], v151 offset:50176
	ds_read_b128 v[210:213], v151 offset:51200
	ds_read_b128 v[214:217], v151 offset:52224
	ds_read_b128 v[218:221], v151 offset:53248
	ds_read_b128 v[222:225], v151 offset:54272
	ds_read_b128 v[226:229], v151 offset:55296
	ds_read_b128 v[230:233], v151 offset:56320
	s_add_u32 s88, s74, s60
	s_addc_u32 s89, s75, s61
	global_load_lds_dwordx4 v138, s[88:89]
	s_add_u32 m0, s32, 0x1a000
	s_add_u32 s90, s74, s62
	s_addc_u32 s91, s75, s63
	global_load_lds_dwordx4 v140, s[88:89]
	s_add_u32 m0, s32, 0x1c000
	s_add_u32 s92, s74, s64
	s_addc_u32 s93, s75, s65
	global_load_lds_dwordx4 v138, s[90:91]
	s_add_u32 m0, s32, 0x1e000
	s_nop 0
	global_load_lds_dwordx4 v140, s[90:91]
	s_add_u32 m0, s32, 0x8000
	s_nop 0
	global_load_lds_dwordx4 v142, s[92:93]
	s_add_u32 m0, s32, 0xa000
	s_nop 0
	global_load_lds_dwordx4 v144, s[92:93]
	s_waitcnt vmcnt(6)
	s_waitcnt lgkmcnt(0)
	s_barrier
	s_setprio 1
	s_waitcnt lgkmcnt(0)
	v_mfma_f32_16x16x32_bf16 v[60:63], v[202:205], v[170:173], v[60:63]
	v_mfma_f32_16x16x32_bf16 v[56:59], v[202:205], v[178:181], v[56:59]
	v_mfma_f32_16x16x32_bf16 v[52:55], v[210:213], v[170:173], v[52:55]
	v_mfma_f32_16x16x32_bf16 v[48:51], v[210:213], v[178:181], v[48:51]
	v_mfma_f32_16x16x32_bf16 v[44:47], v[218:221], v[170:173], v[44:47]
	v_mfma_f32_16x16x32_bf16 v[40:43], v[218:221], v[178:181], v[40:43]
	v_mfma_f32_16x16x32_bf16 v[36:39], v[226:229], v[170:173], v[36:39]
	v_mfma_f32_16x16x32_bf16 v[32:35], v[226:229], v[178:181], v[32:35]
	v_mfma_f32_16x16x32_bf16 v[28:31], v[202:205], v[186:189], v[28:31]
	v_mfma_f32_16x16x32_bf16 v[24:27], v[202:205], v[194:197], v[24:27]
	v_mfma_f32_16x16x32_bf16 v[20:23], v[210:213], v[186:189], v[20:23]
	v_mfma_f32_16x16x32_bf16 v[16:19], v[210:213], v[194:197], v[16:19]
	v_mfma_f32_16x16x32_bf16 v[12:15], v[218:221], v[186:189], v[12:15]
	v_mfma_f32_16x16x32_bf16 v[8:11], v[218:221], v[194:197], v[8:11]
	v_mfma_f32_16x16x32_bf16 v[4:7], v[226:229], v[186:189], v[4:7]
	v_mfma_f32_16x16x32_bf16 v[0:3], v[226:229], v[194:197], v[0:3]
	v_mfma_f32_16x16x32_bf16 v[60:63], v[206:209], v[174:177], v[60:63]
	v_mfma_f32_16x16x32_bf16 v[56:59], v[206:209], v[182:185], v[56:59]
	v_mfma_f32_16x16x32_bf16 v[52:55], v[214:217], v[174:177], v[52:55]
	v_mfma_f32_16x16x32_bf16 v[48:51], v[214:217], v[182:185], v[48:51]
	v_mfma_f32_16x16x32_bf16 v[44:47], v[222:225], v[174:177], v[44:47]
	v_mfma_f32_16x16x32_bf16 v[40:43], v[222:225], v[182:185], v[40:43]
	v_mfma_f32_16x16x32_bf16 v[36:39], v[230:233], v[174:177], v[36:39]
	v_mfma_f32_16x16x32_bf16 v[32:35], v[230:233], v[182:185], v[32:35]
	v_mfma_f32_16x16x32_bf16 v[28:31], v[206:209], v[190:193], v[28:31]
	v_mfma_f32_16x16x32_bf16 v[24:27], v[206:209], v[198:201], v[24:27]
	v_mfma_f32_16x16x32_bf16 v[20:23], v[214:217], v[190:193], v[20:23]
	v_mfma_f32_16x16x32_bf16 v[16:19], v[214:217], v[198:201], v[16:19]
	v_mfma_f32_16x16x32_bf16 v[12:15], v[222:225], v[190:193], v[12:15]
	v_mfma_f32_16x16x32_bf16 v[8:11], v[222:225], v[198:201], v[8:11]
	v_mfma_f32_16x16x32_bf16 v[4:7], v[230:233], v[190:193], v[4:7]
	v_mfma_f32_16x16x32_bf16 v[0:3], v[230:233], v[198:201], v[0:3]
	s_setprio 0
	s_barrier
; #define STAGE(Pp, BASE, br, kt) do { const u16* _g = (BASE) + ((long)(br) * K + (long)(kt) * BK); \
;     __builtin_amdgcn_global_load_lds((const unsigned*)(_g + voff0), (unsigned*)((char*)(Pp) + tb16), 16, 0, 0); \
;     __builtin_amdgcn_global_load_lds((const unsigned*)(_g + voff1), (unsigned*)((char*)(Pp) + tb16 + 8192), 16, 0, 0); } while (0)
; #define LDA(dst, b, h) _Pragma("unroll") for (int m = 0; m < 4; ++m) _Pragma("unroll") for (int k = 0; k < 2; ++k) \
;     dst[m][k] = *reinterpret_cast<const bf16x8*>((const char*)shm + aB + (((b) * 2 + (h)) * 16384 + (m * 2 + k) * 1024))
; #define LDB(dst, b, h) _Pragma("unroll") for (int n = 0; n < 2; ++n) _Pragma("unroll") for (int k = 0; k < 2; ++k) \
;     dst[n][k] = *reinterpret_cast<const bf16x8*>((const char*)shm + bB + (((b) * 2 + (h)) * 16384 + (n * 2 + k) * 1024))
; #define WAIT_V(n) asm volatile("s_waitcnt vmcnt(" #n ")" ::: "memory")
; #define WAIT_L(n) asm volatile("s_waitcnt lgkmcnt(" #n ")" ::: "memory")
; #define BAR __builtin_amdgcn_s_barrier()
; #define SCHED __builtin_amdgcn_sched_barrier(0)
; template <int MODE> ...
;     ...
;     }
;     {
;       LDB(B0, 0, 0); LDB(B1, 0, 1); LDA(At, 0, 0); STAGE(SA(1, 1), A, brow + HALF, nt - 1);
;       WAIT_L(0); BAR; MMA2(0, 0, 0, 1); BAR; SCHED;
;       LDA(At, 0, 1); WAIT_V(0); WAIT_L(0); BAR; MMA2(1, 0, 1, 1); BAR; SCHED;
	s_add_i32 s69, s69, 2
	s_add_u32 s74, s74, 0x100
	s_addc_u32 s75, s75, 0
	s_cmp_lt_u32 s69, 60
	s_cbranch_scc1 .LBB0_154
	s_add_u32 s72, s72, 0x1f80
	v_readfirstlane_b32 s69, v167
	s_addc_u32 s73, s73, 0
	s_mov_b32 m0, s69
	v_readfirstlane_b32 s69, v168
	ds_read_b128 v[138:141], v149
	ds_read_b128 v[142:145], v149 offset:1024
	ds_read_b128 v[170:173], v149 offset:2048
	ds_read_b128 v[174:177], v149 offset:3072
	ds_read_b128 v[178:181], v149 offset:16384
	ds_read_b128 v[182:185], v149 offset:17408
	ds_read_b128 v[186:189], v149 offset:18432
	ds_read_b128 v[190:193], v149 offset:19456
	ds_read_b128 v[194:197], v151
	ds_read_b128 v[198:201], v151 offset:1024
	ds_read_b128 v[202:205], v151 offset:2048
	ds_read_b128 v[206:209], v151 offset:3072
	ds_read_b128 v[210:213], v151 offset:4096
	ds_read_b128 v[214:217], v151 offset:5120
	ds_read_b128 v[218:221], v151 offset:6144
	ds_read_b128 v[222:225], v151 offset:7168
	global_load_lds_dwordx4 v134, s[72:73]
	s_mov_b32 m0, s69
	s_nop 0
	global_load_lds_dwordx4 v136, s[72:73]
	s_waitcnt lgkmcnt(0)
	s_barrier
	s_setprio 1
	s_waitcnt lgkmcnt(0)
	v_mfma_f32_16x16x32_bf16 v[124:127], v[194:197], v[138:141], v[124:127]
	v_mfma_f32_16x16x32_bf16 v[120:123], v[194:197], v[170:173], v[120:123]
	v_mfma_f32_16x16x32_bf16 v[116:119], v[202:205], v[138:141], v[116:119]
	v_mfma_f32_16x16x32_bf16 v[112:115], v[202:205], v[170:173], v[112:115]
	v_mfma_f32_16x16x32_bf16 v[108:111], v[210:213], v[138:141], v[108:111]
	v_mfma_f32_16x16x32_bf16 v[104:107], v[210:213], v[170:173], v[104:107]
	v_mfma_f32_16x16x32_bf16 v[100:103], v[218:221], v[138:141], v[100:103]
	v_mfma_f32_16x16x32_bf16 v[96:99], v[218:221], v[170:173], v[96:99]
	v_mfma_f32_16x16x32_bf16 v[92:95], v[194:197], v[178:181], v[92:95]
	v_mfma_f32_16x16x32_bf16 v[88:91], v[194:197], v[186:189], v[88:91]
	v_mfma_f32_16x16x32_bf16 v[84:87], v[202:205], v[178:181], v[84:87]
	v_mfma_f32_16x16x32_bf16 v[80:83], v[202:205], v[186:189], v[80:83]
	v_mfma_f32_16x16x32_bf16 v[76:79], v[210:213], v[178:181], v[76:79]
	v_mfma_f32_16x16x32_bf16 v[72:75], v[210:213], v[186:189], v[72:75]
	v_mfma_f32_16x16x32_bf16 v[68:71], v[218:221], v[178:181], v[68:71]
	v_mfma_f32_16x16x32_bf16 v[64:67], v[218:221], v[186:189], v[64:67]
	v_mfma_f32_16x16x32_bf16 v[124:127], v[198:201], v[142:145], v[124:127]
	v_mfma_f32_16x16x32_bf16 v[120:123], v[198:201], v[174:177], v[120:123]
	v_mfma_f32_16x16x32_bf16 v[116:119], v[206:209], v[142:145], v[116:119]
	v_mfma_f32_16x16x32_bf16 v[112:115], v[206:209], v[174:177], v[112:115]
	v_mfma_f32_16x16x32_bf16 v[108:111], v[214:217], v[142:145], v[108:111]
	v_mfma_f32_16x16x32_bf16 v[104:107], v[214:217], v[174:177], v[104:107]
	v_mfma_f32_16x16x32_bf16 v[100:103], v[222:225], v[142:145], v[100:103]
	v_mfma_f32_16x16x32_bf16 v[96:99], v[222:225], v[174:177], v[96:99]
	v_mfma_f32_16x16x32_bf16 v[92:95], v[198:201], v[182:185], v[92:95]
	v_mfma_f32_16x16x32_bf16 v[88:91], v[198:201], v[190:193], v[88:91]
	v_mfma_f32_16x16x32_bf16 v[84:87], v[206:209], v[182:185], v[84:87]
	v_mfma_f32_16x16x32_bf16 v[80:83], v[206:209], v[190:193], v[80:83]
	v_mfma_f32_16x16x32_bf16 v[76:79], v[214:217], v[182:185], v[76:79]
	v_mfma_f32_16x16x32_bf16 v[72:75], v[214:217], v[190:193], v[72:75]
	v_mfma_f32_16x16x32_bf16 v[68:71], v[222:225], v[182:185], v[68:71]
	v_mfma_f32_16x16x32_bf16 v[64:67], v[222:225], v[190:193], v[64:67]
	s_setprio 0
	s_barrier
	ds_read_b128 v[194:197], v151 offset:16384
	ds_read_b128 v[198:201], v151 offset:17408
	ds_read_b128 v[202:205], v151 offset:18432
	ds_read_b128 v[206:209], v151 offset:19456
	ds_read_b128 v[210:213], v151 offset:20480
	ds_read_b128 v[214:217], v151 offset:21504
	ds_read_b128 v[218:221], v151 offset:22528
	ds_read_b128 v[222:225], v151 offset:23552
	s_waitcnt vmcnt(0)
	s_waitcnt lgkmcnt(0)
	s_barrier
	s_setprio 1
	s_waitcnt lgkmcnt(0)
	v_mfma_f32_16x16x32_bf16 v[56:59], v[194:197], v[170:173], v[56:59]
	v_mfma_f32_16x16x32_bf16 v[52:55], v[202:205], v[138:141], v[52:55]
	v_mfma_f32_16x16x32_bf16 v[48:51], v[202:205], v[170:173], v[48:51]
	v_mfma_f32_16x16x32_bf16 v[44:47], v[210:213], v[138:141], v[44:47]
	v_mfma_f32_16x16x32_bf16 v[40:43], v[210:213], v[170:173], v[40:43]
	v_mfma_f32_16x16x32_bf16 v[36:39], v[218:221], v[138:141], v[36:39]
	v_mfma_f32_16x16x32_bf16 v[32:35], v[218:221], v[170:173], v[32:35]
	v_mfma_f32_16x16x32_bf16 v[28:31], v[194:197], v[178:181], v[28:31]
	v_mfma_f32_16x16x32_bf16 v[24:27], v[194:197], v[186:189], v[24:27]
	v_mfma_f32_16x16x32_bf16 v[20:23], v[202:205], v[178:181], v[20:23]
	v_mfma_f32_16x16x32_bf16 v[16:19], v[202:205], v[186:189], v[16:19]
	v_mfma_f32_16x16x32_bf16 v[12:15], v[210:213], v[178:181], v[12:15]
	v_mfma_f32_16x16x32_bf16 v[8:11], v[210:213], v[186:189], v[8:11]
	v_mfma_f32_16x16x32_bf16 v[4:7], v[218:221], v[178:181], v[4:7]
	v_mfma_f32_16x16x32_bf16 v[0:3], v[218:221], v[186:189], v[0:3]
	v_mfma_f32_16x16x32_bf16 v[60:63], v[194:197], v[138:141], v[60:63]
	v_mfma_f32_16x16x32_bf16 v[56:59], v[198:201], v[174:177], v[56:59]
	v_mfma_f32_16x16x32_bf16 v[52:55], v[206:209], v[142:145], v[52:55]
	v_mfma_f32_16x16x32_bf16 v[48:51], v[206:209], v[174:177], v[48:51]
	v_mfma_f32_16x16x32_bf16 v[44:47], v[214:217], v[142:145], v[44:47]
	v_mfma_f32_16x16x32_bf16 v[40:43], v[214:217], v[174:177], v[40:43]
	v_mfma_f32_16x16x32_bf16 v[36:39], v[222:225], v[142:145], v[36:39]
	v_mfma_f32_16x16x32_bf16 v[32:35], v[222:225], v[174:177], v[32:35]
	v_mfma_f32_16x16x32_bf16 v[28:31], v[198:201], v[182:185], v[28:31]
	v_mfma_f32_16x16x32_bf16 v[24:27], v[198:201], v[190:193], v[24:27]
	v_mfma_f32_16x16x32_bf16 v[20:23], v[206:209], v[182:185], v[20:23]
	v_mfma_f32_16x16x32_bf16 v[16:19], v[206:209], v[190:193], v[16:19]
	v_mfma_f32_16x16x32_bf16 v[12:15], v[214:217], v[182:185], v[12:15]
	v_mfma_f32_16x16x32_bf16 v[8:11], v[214:217], v[190:193], v[8:11]
	v_mfma_f32_16x16x32_bf16 v[4:7], v[222:225], v[182:185], v[4:7]
	v_mfma_f32_16x16x32_bf16 v[0:3], v[222:225], v[190:193], v[0:3]
	v_mfma_f32_16x16x32_bf16 v[226:229], v[198:201], v[142:145], v[60:63]
	s_setprio 0
	s_barrier
; #define LDA(dst, b, h) _Pragma("unroll") for (int m = 0; m < 4; ++m) _Pragma("unroll") for (int k = 0; k < 2; ++k) \
;     dst[m][k] = *reinterpret_cast<const bf16x8*>((const char*)shm + aB + (((b) * 2 + (h)) * 16384 + (m * 2 + k) * 1024))
; #define LDB(dst, b, h) _Pragma("unroll") for (int n = 0; n < 2; ++n) _Pragma("unroll") for (int k = 0; k < 2; ++k) \
;     dst[n][k] = *reinterpret_cast<const bf16x8*>((const char*)shm + bB + (((b) * 2 + (h)) * 16384 + (n * 2 + k) * 1024))
; #define WAIT_L(n) asm volatile("s_waitcnt lgkmcnt(" #n ")" ::: "memory")
; #define BAR __builtin_amdgcn_s_barrier()
; #define SCHED __builtin_amdgcn_sched_barrier(0)
; template <int MODE> ...
;     ...
;       LDB(B0, 1, 0); LDB(B1, 1, 1); LDA(At, 1, 0); WAIT_L(0); BAR; MMA2(0, 0, 0, 1); BAR; SCHED;
;       LDA(At, 1, 1); WAIT_L(0); BAR; MMA2(1, 0, 1, 1); BAR; SCHED;
;     }
;     ...
;     if (wr == 0) BAR;
	ds_read_b128 v[138:141], v149 offset:32768
	ds_read_b128 v[142:145], v149 offset:33792
	ds_read_b128 v[170:173], v149 offset:34816
	ds_read_b128 v[174:177], v149 offset:35840
	ds_read_b128 v[178:181], v149 offset:49152
	ds_read_b128 v[182:185], v149 offset:50176
	ds_read_b128 v[186:189], v149 offset:51200
	ds_read_b128 v[190:193], v149 offset:52224
	ds_read_b128 v[60:63], v151 offset:32768
	ds_read_b128 v[194:197], v151 offset:33792
	ds_read_b128 v[198:201], v151 offset:34816
	ds_read_b128 v[202:205], v151 offset:35840
	ds_read_b128 v[206:209], v151 offset:36864
	ds_read_b128 v[210:213], v151 offset:37888
	ds_read_b128 v[214:217], v151 offset:38912
	ds_read_b128 v[218:221], v151 offset:39936
	s_waitcnt lgkmcnt(0)
	s_barrier
	s_setprio 1
	s_waitcnt lgkmcnt(0)
	v_mfma_f32_16x16x32_bf16 v[124:127], v[60:63], v[138:141], v[124:127]
	v_mfma_f32_16x16x32_bf16 v[120:123], v[60:63], v[170:173], v[120:123]
	v_mfma_f32_16x16x32_bf16 v[92:95], v[60:63], v[178:181], v[92:95]
	v_mfma_f32_16x16x32_bf16 v[60:63], v[60:63], v[186:189], v[88:91]
	v_mfma_f32_16x16x32_bf16 v[88:91], v[194:197], v[190:193], v[60:63]
	v_mfma_f32_16x16x32_bf16 v[60:63], v[198:201], v[178:181], v[84:87]
	v_mfma_f32_16x16x32_bf16 v[84:87], v[202:205], v[182:185], v[60:63]
	v_mfma_f32_16x16x32_bf16 v[60:63], v[198:201], v[186:189], v[80:83]
	v_mfma_f32_16x16x32_bf16 v[80:83], v[202:205], v[190:193], v[60:63]
	v_mfma_f32_16x16x32_bf16 v[60:63], v[206:209], v[178:181], v[76:79]
	v_mfma_f32_16x16x32_bf16 v[76:79], v[210:213], v[182:185], v[60:63]
	v_mfma_f32_16x16x32_bf16 v[60:63], v[206:209], v[186:189], v[72:75]
	v_mfma_f32_16x16x32_bf16 v[72:75], v[210:213], v[190:193], v[60:63]
	v_mfma_f32_16x16x32_bf16 v[60:63], v[214:217], v[178:181], v[68:71]
	v_mfma_f32_16x16x32_bf16 v[116:119], v[198:201], v[138:141], v[116:119]
	v_mfma_f32_16x16x32_bf16 v[112:115], v[198:201], v[170:173], v[112:115]
	v_mfma_f32_16x16x32_bf16 v[108:111], v[206:209], v[138:141], v[108:111]
	v_mfma_f32_16x16x32_bf16 v[104:107], v[206:209], v[170:173], v[104:107]
	v_mfma_f32_16x16x32_bf16 v[100:103], v[214:217], v[138:141], v[100:103]
	v_mfma_f32_16x16x32_bf16 v[96:99], v[214:217], v[170:173], v[96:99]
	v_mfma_f32_16x16x32_bf16 v[68:71], v[218:221], v[182:185], v[60:63]
	v_mfma_f32_16x16x32_bf16 v[60:63], v[214:217], v[186:189], v[64:67]
	v_mfma_f32_16x16x32_bf16 v[124:127], v[194:197], v[142:145], v[124:127]
	v_mfma_f32_16x16x32_bf16 v[120:123], v[194:197], v[174:177], v[120:123]
	v_mfma_f32_16x16x32_bf16 v[116:119], v[202:205], v[142:145], v[116:119]
	v_mfma_f32_16x16x32_bf16 v[112:115], v[202:205], v[174:177], v[112:115]
	v_mfma_f32_16x16x32_bf16 v[108:111], v[210:213], v[142:145], v[108:111]
	v_mfma_f32_16x16x32_bf16 v[104:107], v[210:213], v[174:177], v[104:107]
	v_mfma_f32_16x16x32_bf16 v[100:103], v[218:221], v[142:145], v[100:103]
	v_mfma_f32_16x16x32_bf16 v[96:99], v[218:221], v[174:177], v[96:99]
	v_mfma_f32_16x16x32_bf16 v[92:95], v[194:197], v[182:185], v[92:95]
	v_mfma_f32_16x16x32_bf16 v[60:63], v[218:221], v[190:193], v[60:63]
	s_setprio 0
	s_barrier
	ds_read_b128 v[194:197], v151 offset:49152
	ds_read_b128 v[198:201], v151 offset:50176
	ds_read_b128 v[202:205], v151 offset:51200
	ds_read_b128 v[206:209], v151 offset:52224
	ds_read_b128 v[210:213], v151 offset:53248
	ds_read_b128 v[214:217], v151 offset:54272
	ds_read_b128 v[218:221], v151 offset:55296
	ds_read_b128 v[222:225], v151 offset:56320
	s_waitcnt lgkmcnt(0)
	s_barrier
	s_setprio 1
	s_waitcnt lgkmcnt(0)
	v_mfma_f32_16x16x32_bf16 v[64:67], v[194:197], v[138:141], v[226:229]
	v_mfma_f32_16x16x32_bf16 v[56:59], v[194:197], v[170:173], v[56:59]
	v_mfma_f32_16x16x32_bf16 v[52:55], v[202:205], v[138:141], v[52:55]
	v_mfma_f32_16x16x32_bf16 v[48:51], v[202:205], v[170:173], v[48:51]
	v_mfma_f32_16x16x32_bf16 v[44:47], v[210:213], v[138:141], v[44:47]
	v_mfma_f32_16x16x32_bf16 v[40:43], v[210:213], v[170:173], v[40:43]
	v_mfma_f32_16x16x32_bf16 v[36:39], v[218:221], v[138:141], v[36:39]
	v_mfma_f32_16x16x32_bf16 v[32:35], v[218:221], v[170:173], v[32:35]
	v_mfma_f32_16x16x32_bf16 v[28:31], v[194:197], v[178:181], v[28:31]
	v_mfma_f32_16x16x32_bf16 v[24:27], v[194:197], v[186:189], v[24:27]
	v_mfma_f32_16x16x32_bf16 v[20:23], v[202:205], v[178:181], v[20:23]
	v_mfma_f32_16x16x32_bf16 v[16:19], v[202:205], v[186:189], v[16:19]
	v_mfma_f32_16x16x32_bf16 v[12:15], v[210:213], v[178:181], v[12:15]
	v_mfma_f32_16x16x32_bf16 v[8:11], v[210:213], v[186:189], v[8:11]
	v_mfma_f32_16x16x32_bf16 v[4:7], v[218:221], v[178:181], v[4:7]
	v_mfma_f32_16x16x32_bf16 v[0:3], v[218:221], v[186:189], v[0:3]
	v_mfma_f32_16x16x32_bf16 v[64:67], v[198:201], v[142:145], v[64:67]
	v_mfma_f32_16x16x32_bf16 v[56:59], v[198:201], v[174:177], v[56:59]
	v_mfma_f32_16x16x32_bf16 v[52:55], v[206:209], v[142:145], v[52:55]
	v_mfma_f32_16x16x32_bf16 v[48:51], v[206:209], v[174:177], v[48:51]
	v_mfma_f32_16x16x32_bf16 v[44:47], v[214:217], v[142:145], v[44:47]
	v_mfma_f32_16x16x32_bf16 v[40:43], v[214:217], v[174:177], v[40:43]
	v_mfma_f32_16x16x32_bf16 v[36:39], v[222:225], v[142:145], v[36:39]
	v_mfma_f32_16x16x32_bf16 v[32:35], v[222:225], v[174:177], v[32:35]
	v_mfma_f32_16x16x32_bf16 v[28:31], v[198:201], v[182:185], v[28:31]
	v_mfma_f32_16x16x32_bf16 v[24:27], v[198:201], v[190:193], v[24:27]
	v_mfma_f32_16x16x32_bf16 v[20:23], v[206:209], v[182:185], v[20:23]
	v_mfma_f32_16x16x32_bf16 v[16:19], v[206:209], v[190:193], v[16:19]
	v_mfma_f32_16x16x32_bf16 v[12:15], v[214:217], v[182:185], v[12:15]
	v_mfma_f32_16x16x32_bf16 v[8:11], v[214:217], v[190:193], v[8:11]
	v_mfma_f32_16x16x32_bf16 v[4:7], v[222:225], v[182:185], v[4:7]
	v_mfma_f32_16x16x32_bf16 v[0:3], v[222:225], v[190:193], v[0:3]
	s_setprio 0
	s_barrier
	s_and_saveexec_b64 s[72:73], s[6:7]
	s_cbranch_execz .LBB0_157
	s_barrier

; #define STAGE(Pp, BASE, br, kt) do { const u16* _g = (BASE) + ((long)(br) * K + (long)(kt) * BK); \
;     __builtin_amdgcn_global_load_lds((const unsigned*)(_g + voff0), (unsigned*)((char*)(Pp) + tb16), 16, 0, 0); \
;     __builtin_amdgcn_global_load_lds((const unsigned*)(_g + voff1), (unsigned*)((char*)(Pp) + tb16 + 8192), 16, 0, 0); } while (0)
; #define LDA(dst, b, h) _Pragma("unroll") for (int m = 0; m < 4; ++m) _Pragma("unroll") for (int k = 0; k < 2; ++k) \
;     dst[m][k] = *reinterpret_cast<const bf16x8*>((const char*)shm + aB + (((b) * 2 + (h)) * 16384 + (m * 2 + k) * 1024))
; #define LDB(dst, b, h) _Pragma("unroll") for (int n = 0; n < 2; ++n) _Pragma("unroll") for (int k = 0; k < 2; ++k) \
;     dst[n][k] = *reinterpret_cast<const bf16x8*>((const char*)shm + bB + (((b) * 2 + (h)) * 16384 + (n * 2 + k) * 1024))
; #define WAIT_V(n) asm volatile("s_waitcnt vmcnt(" #n ")" ::: "memory")
; #define WAIT_L(n) asm volatile("s_waitcnt lgkmcnt(" #n ")" ::: "memory")
; #define BAR __builtin_amdgcn_s_barrier()
; #define SCHED __builtin_amdgcn_sched_barrier(0)
; template <int MODE> ...
;     ...
;       LDB(B0, 0, 0); LDB(B1, 0, 1); LDA(At, 0, 0); STAGE(SA(1, 1), A, brow + HALF, t + 1);
;       WAIT_L(0); BAR; MMA2(0, 0, 0, 1); BAR; SCHED;
;       LDA(At, 0, 1); STAGE(SB(0, 0), Bt, bcol, t + 2); STAGE(SB(0, 1), Bt, bcol + HALF, t + 2); STAGE(SA(0, 0), A, brow, t + 2);
;       WAIT_V(6); WAIT_L(0); BAR; MMA2(1, 0, 1, 1); BAR; SCHED;
.LBB0_177:
	s_add_u32 m0, s32, 0xc000
	ds_read_b128 v[168:171], v148
	ds_read_b128 v[172:175], v148 offset:1024
	ds_read_b128 v[176:179], v148 offset:2048
	ds_read_b128 v[180:183], v148 offset:3072
	ds_read_b128 v[184:187], v148 offset:16384
	ds_read_b128 v[188:191], v148 offset:17408
	ds_read_b128 v[192:195], v148 offset:18432
	ds_read_b128 v[196:199], v148 offset:19456
	ds_read_b128 v[200:203], v147
	ds_read_b128 v[204:207], v147 offset:1024
	ds_read_b128 v[208:211], v147 offset:2048
	ds_read_b128 v[212:215], v147 offset:3072
	ds_read_b128 v[216:219], v147 offset:4096
	ds_read_b128 v[220:223], v147 offset:5120
	ds_read_b128 v[224:227], v147 offset:6144
	ds_read_b128 v[228:231], v147 offset:7168
	s_add_u32 s88, s68, s12
	s_addc_u32 s89, s69, s13
	global_load_lds_dwordx4 v142, s[88:89]
	s_add_u32 m0, s32, 0xe000
	s_nop 0
	global_load_lds_dwordx4 v144, s[88:89]
	s_waitcnt lgkmcnt(0)
	s_barrier
	s_setprio 1
	s_waitcnt lgkmcnt(0)
	v_mfma_f32_16x16x32_bf16 v[124:127], v[200:203], v[168:171], v[124:127]
	v_mfma_f32_16x16x32_bf16 v[120:123], v[200:203], v[176:179], v[120:123]
	v_mfma_f32_16x16x32_bf16 v[116:119], v[208:211], v[168:171], v[116:119]
	v_mfma_f32_16x16x32_bf16 v[112:115], v[208:211], v[176:179], v[112:115]
	v_mfma_f32_16x16x32_bf16 v[108:111], v[216:219], v[168:171], v[108:111]
	v_mfma_f32_16x16x32_bf16 v[104:107], v[216:219], v[176:179], v[104:107]
	v_mfma_f32_16x16x32_bf16 v[100:103], v[224:227], v[168:171], v[100:103]
	v_mfma_f32_16x16x32_bf16 v[96:99], v[224:227], v[176:179], v[96:99]
	v_mfma_f32_16x16x32_bf16 v[92:95], v[200:203], v[184:187], v[92:95]
	v_mfma_f32_16x16x32_bf16 v[88:91], v[200:203], v[192:195], v[88:91]
	v_mfma_f32_16x16x32_bf16 v[84:87], v[208:211], v[184:187], v[84:87]
	v_mfma_f32_16x16x32_bf16 v[80:83], v[208:211], v[192:195], v[80:83]
	v_mfma_f32_16x16x32_bf16 v[76:79], v[216:219], v[184:187], v[76:79]
	v_mfma_f32_16x16x32_bf16 v[72:75], v[216:219], v[192:195], v[72:75]
	v_mfma_f32_16x16x32_bf16 v[68:71], v[224:227], v[184:187], v[68:71]
	v_mfma_f32_16x16x32_bf16 v[64:67], v[224:227], v[192:195], v[64:67]
	v_mfma_f32_16x16x32_bf16 v[124:127], v[204:207], v[172:175], v[124:127]
	v_mfma_f32_16x16x32_bf16 v[120:123], v[204:207], v[180:183], v[120:123]
	v_mfma_f32_16x16x32_bf16 v[116:119], v[212:215], v[172:175], v[116:119]
	v_mfma_f32_16x16x32_bf16 v[112:115], v[212:215], v[180:183], v[112:115]
	v_mfma_f32_16x16x32_bf16 v[108:111], v[220:223], v[172:175], v[108:111]
	v_mfma_f32_16x16x32_bf16 v[104:107], v[220:223], v[180:183], v[104:107]
	v_mfma_f32_16x16x32_bf16 v[100:103], v[228:231], v[172:175], v[100:103]
	v_mfma_f32_16x16x32_bf16 v[96:99], v[228:231], v[180:183], v[96:99]
	v_mfma_f32_16x16x32_bf16 v[92:95], v[204:207], v[188:191], v[92:95]
	v_mfma_f32_16x16x32_bf16 v[88:91], v[204:207], v[196:199], v[88:91]
	v_mfma_f32_16x16x32_bf16 v[84:87], v[212:215], v[188:191], v[84:87]
	v_mfma_f32_16x16x32_bf16 v[80:83], v[212:215], v[196:199], v[80:83]
	v_mfma_f32_16x16x32_bf16 v[76:79], v[220:223], v[188:191], v[76:79]
	v_mfma_f32_16x16x32_bf16 v[72:75], v[220:223], v[196:199], v[72:75]
	v_mfma_f32_16x16x32_bf16 v[68:71], v[228:231], v[188:191], v[68:71]
	v_mfma_f32_16x16x32_bf16 v[64:67], v[228:231], v[196:199], v[64:67]
	s_setprio 0
	s_barrier
	s_add_u32 m0, s32, 0x10000
	ds_read_b128 v[200:203], v147 offset:16384
	ds_read_b128 v[204:207], v147 offset:17408
	ds_read_b128 v[208:211], v147 offset:18432
	ds_read_b128 v[212:215], v147 offset:19456
	ds_read_b128 v[216:219], v147 offset:20480
	ds_read_b128 v[220:223], v147 offset:21504
	ds_read_b128 v[224:227], v147 offset:22528
	ds_read_b128 v[228:231], v147 offset:23552
	s_add_u32 s88, s68, s38
	s_addc_u32 s89, s69, s39
	global_load_lds_dwordx4 v138, s[88:89]
	s_add_u32 m0, s32, 0x12000
	s_add_u32 s90, s68, s40
	s_addc_u32 s91, s69, s41
	global_load_lds_dwordx4 v140, s[88:89]
	s_add_u32 m0, s32, 0x14000
	s_add_u32 s92, s68, s42
	s_addc_u32 s93, s69, s43
	global_load_lds_dwordx4 v138, s[90:91]
	s_add_u32 m0, s32, 0x16000
	s_nop 0
	global_load_lds_dwordx4 v140, s[90:91]
	s_mov_b32 m0, s32
	s_nop 0
	global_load_lds_dwordx4 v142, s[92:93]
	s_add_u32 m0, s32, 0x2000
	s_nop 0
	global_load_lds_dwordx4 v144, s[92:93]
	s_waitcnt vmcnt(6)
	s_waitcnt lgkmcnt(0)
	s_barrier
	s_setprio 1
	s_waitcnt lgkmcnt(0)
	v_mfma_f32_16x16x32_bf16 v[60:63], v[200:203], v[168:171], v[60:63]
	v_mfma_f32_16x16x32_bf16 v[56:59], v[200:203], v[176:179], v[56:59]
	v_mfma_f32_16x16x32_bf16 v[52:55], v[208:211], v[168:171], v[52:55]
	v_mfma_f32_16x16x32_bf16 v[48:51], v[208:211], v[176:179], v[48:51]
	v_mfma_f32_16x16x32_bf16 v[44:47], v[216:219], v[168:171], v[44:47]
	v_mfma_f32_16x16x32_bf16 v[40:43], v[216:219], v[176:179], v[40:43]
	v_mfma_f32_16x16x32_bf16 v[36:39], v[224:227], v[168:171], v[36:39]
	v_mfma_f32_16x16x32_bf16 v[32:35], v[224:227], v[176:179], v[32:35]
	v_mfma_f32_16x16x32_bf16 v[28:31], v[200:203], v[184:187], v[28:31]
	v_mfma_f32_16x16x32_bf16 v[24:27], v[200:203], v[192:195], v[24:27]
	v_mfma_f32_16x16x32_bf16 v[20:23], v[208:211], v[184:187], v[20:23]
	v_mfma_f32_16x16x32_bf16 v[16:19], v[208:211], v[192:195], v[16:19]
	v_mfma_f32_16x16x32_bf16 v[12:15], v[216:219], v[184:187], v[12:15]
	v_mfma_f32_16x16x32_bf16 v[8:11], v[216:219], v[192:195], v[8:11]
	v_mfma_f32_16x16x32_bf16 v[4:7], v[224:227], v[184:187], v[4:7]
	v_mfma_f32_16x16x32_bf16 v[0:3], v[224:227], v[192:195], v[0:3]
	v_mfma_f32_16x16x32_bf16 v[60:63], v[204:207], v[172:175], v[60:63]
	v_mfma_f32_16x16x32_bf16 v[56:59], v[204:207], v[180:183], v[56:59]
	v_mfma_f32_16x16x32_bf16 v[52:55], v[212:215], v[172:175], v[52:55]
	v_mfma_f32_16x16x32_bf16 v[48:51], v[212:215], v[180:183], v[48:51]
	v_mfma_f32_16x16x32_bf16 v[44:47], v[220:223], v[172:175], v[44:47]
	v_mfma_f32_16x16x32_bf16 v[40:43], v[220:223], v[180:183], v[40:43]
	v_mfma_f32_16x16x32_bf16 v[36:39], v[228:231], v[172:175], v[36:39]
	v_mfma_f32_16x16x32_bf16 v[32:35], v[228:231], v[180:183], v[32:35]
	v_mfma_f32_16x16x32_bf16 v[28:31], v[204:207], v[188:191], v[28:31]
	v_mfma_f32_16x16x32_bf16 v[24:27], v[204:207], v[196:199], v[24:27]
	v_mfma_f32_16x16x32_bf16 v[20:23], v[212:215], v[188:191], v[20:23]
	v_mfma_f32_16x16x32_bf16 v[16:19], v[212:215], v[196:199], v[16:19]
	v_mfma_f32_16x16x32_bf16 v[12:15], v[220:223], v[188:191], v[12:15]
	v_mfma_f32_16x16x32_bf16 v[8:11], v[220:223], v[196:199], v[8:11]
	v_mfma_f32_16x16x32_bf16 v[4:7], v[228:231], v[188:191], v[4:7]
	v_mfma_f32_16x16x32_bf16 v[0:3], v[228:231], v[196:199], v[0:3]
	s_setprio 0
	s_barrier
; #define STAGE(Pp, BASE, br, kt) do { const u16* _g = (BASE) + ((long)(br) * K + (long)(kt) * BK); \
;     __builtin_amdgcn_global_load_lds((const unsigned*)(_g + voff0), (unsigned*)((char*)(Pp) + tb16), 16, 0, 0); \
;     __builtin_amdgcn_global_load_lds((const unsigned*)(_g + voff1), (unsigned*)((char*)(Pp) + tb16 + 8192), 16, 0, 0); } while (0)
; #define LDA(dst, b, h) _Pragma("unroll") for (int m = 0; m < 4; ++m) _Pragma("unroll") for (int k = 0; k < 2; ++k) \
;     dst[m][k] = *reinterpret_cast<const bf16x8*>((const char*)shm + aB + (((b) * 2 + (h)) * 16384 + (m * 2 + k) * 1024))
; #define LDB(dst, b, h) _Pragma("unroll") for (int n = 0; n < 2; ++n) _Pragma("unroll") for (int k = 0; k < 2; ++k) \
;     dst[n][k] = *reinterpret_cast<const bf16x8*>((const char*)shm + bB + (((b) * 2 + (h)) * 16384 + (n * 2 + k) * 1024))
; #define WAIT_V(n) asm volatile("s_waitcnt vmcnt(" #n ")" ::: "memory")
; #define WAIT_L(n) asm volatile("s_waitcnt lgkmcnt(" #n ")" ::: "memory")
; #define BAR __builtin_amdgcn_s_barrier()
; #define SCHED __builtin_amdgcn_sched_barrier(0)
; template <int MODE> ...
;     ...
;       LDB(B0, 1, 0); LDB(B1, 1, 1); LDA(At, 1, 0); STAGE(SA(0, 1), A, brow + HALF, t + 2);
;       WAIT_L(0); BAR; MMA2(0, 0, 0, 1); BAR; SCHED;
;       LDA(At, 1, 1); STAGE(SB(1, 0), Bt, bcol, t + 3); STAGE(SB(1, 1), Bt, bcol + HALF, t + 3); STAGE(SA(1, 0), A, brow, t + 3);
;       WAIT_V(6); WAIT_L(0); BAR; MMA2(1, 0, 1, 1); BAR; SCHED;
	s_add_u32 m0, s32, 0x4000
	ds_read_b128 v[168:171], v148 offset:32768
	ds_read_b128 v[172:175], v148 offset:33792
	ds_read_b128 v[176:179], v148 offset:34816
	ds_read_b128 v[180:183], v148 offset:35840
	ds_read_b128 v[184:187], v148 offset:49152
	ds_read_b128 v[188:191], v148 offset:50176
	ds_read_b128 v[192:195], v148 offset:51200
	ds_read_b128 v[196:199], v148 offset:52224
	ds_read_b128 v[200:203], v147 offset:32768
	ds_read_b128 v[204:207], v147 offset:33792
	ds_read_b128 v[208:211], v147 offset:34816
	ds_read_b128 v[212:215], v147 offset:35840
	ds_read_b128 v[216:219], v147 offset:36864
	ds_read_b128 v[220:223], v147 offset:37888
	ds_read_b128 v[224:227], v147 offset:38912
	ds_read_b128 v[228:231], v147 offset:39936
	s_add_u32 s88, s68, s44
	s_addc_u32 s89, s69, s45
	global_load_lds_dwordx4 v142, s[88:89]
	s_add_u32 m0, s32, 0x6000
	s_nop 0
	global_load_lds_dwordx4 v144, s[88:89]
	s_waitcnt lgkmcnt(0)
	s_barrier
	s_setprio 1
	s_waitcnt lgkmcnt(0)
	v_mfma_f32_16x16x32_bf16 v[124:127], v[200:203], v[168:171], v[124:127]
	v_mfma_f32_16x16x32_bf16 v[120:123], v[200:203], v[176:179], v[120:123]
	v_mfma_f32_16x16x32_bf16 v[116:119], v[208:211], v[168:171], v[116:119]
	v_mfma_f32_16x16x32_bf16 v[112:115], v[208:211], v[176:179], v[112:115]
	v_mfma_f32_16x16x32_bf16 v[108:111], v[216:219], v[168:171], v[108:111]
	v_mfma_f32_16x16x32_bf16 v[104:107], v[216:219], v[176:179], v[104:107]
	v_mfma_f32_16x16x32_bf16 v[100:103], v[224:227], v[168:171], v[100:103]
	v_mfma_f32_16x16x32_bf16 v[96:99], v[224:227], v[176:179], v[96:99]
	v_mfma_f32_16x16x32_bf16 v[92:95], v[200:203], v[184:187], v[92:95]
	v_mfma_f32_16x16x32_bf16 v[88:91], v[200:203], v[192:195], v[88:91]
	v_mfma_f32_16x16x32_bf16 v[84:87], v[208:211], v[184:187], v[84:87]
	v_mfma_f32_16x16x32_bf16 v[80:83], v[208:211], v[192:195], v[80:83]
	v_mfma_f32_16x16x32_bf16 v[76:79], v[216:219], v[184:187], v[76:79]
	v_mfma_f32_16x16x32_bf16 v[72:75], v[216:219], v[192:195], v[72:75]
	v_mfma_f32_16x16x32_bf16 v[68:71], v[224:227], v[184:187], v[68:71]
	v_mfma_f32_16x16x32_bf16 v[64:67], v[224:227], v[192:195], v[64:67]
	v_mfma_f32_16x16x32_bf16 v[124:127], v[204:207], v[172:175], v[124:127]
	v_mfma_f32_16x16x32_bf16 v[120:123], v[204:207], v[180:183], v[120:123]
	v_mfma_f32_16x16x32_bf16 v[116:119], v[212:215], v[172:175], v[116:119]
	v_mfma_f32_16x16x32_bf16 v[112:115], v[212:215], v[180:183], v[112:115]
	v_mfma_f32_16x16x32_bf16 v[108:111], v[220:223], v[172:175], v[108:111]
	v_mfma_f32_16x16x32_bf16 v[104:107], v[220:223], v[180:183], v[104:107]
	v_mfma_f32_16x16x32_bf16 v[100:103], v[228:231], v[172:175], v[100:103]
	v_mfma_f32_16x16x32_bf16 v[96:99], v[228:231], v[180:183], v[96:99]
	v_mfma_f32_16x16x32_bf16 v[92:95], v[204:207], v[188:191], v[92:95]
	v_mfma_f32_16x16x32_bf16 v[88:91], v[204:207], v[196:199], v[88:91]
	v_mfma_f32_16x16x32_bf16 v[84:87], v[212:215], v[188:191], v[84:87]
	v_mfma_f32_16x16x32_bf16 v[80:83], v[212:215], v[196:199], v[80:83]
	v_mfma_f32_16x16x32_bf16 v[76:79], v[220:223], v[188:191], v[76:79]
	v_mfma_f32_16x16x32_bf16 v[72:75], v[220:223], v[196:199], v[72:75]
	v_mfma_f32_16x16x32_bf16 v[68:71], v[228:231], v[188:191], v[68:71]
	v_mfma_f32_16x16x32_bf16 v[64:67], v[228:231], v[196:199], v[64:67]
	s_setprio 0
	s_barrier
	s_add_u32 m0, s32, 0x18000
	ds_read_b128 v[200:203], v147 offset:49152
	ds_read_b128 v[204:207], v147 offset:50176
	ds_read_b128 v[208:211], v147 offset:51200
	ds_read_b128 v[212:215], v147 offset:52224
	ds_read_b128 v[216:219], v147 offset:53248
	ds_read_b128 v[220:223], v147 offset:54272
	ds_read_b128 v[224:227], v147 offset:55296
	ds_read_b128 v[228:231], v147 offset:56320
	s_add_u32 s88, s68, s48
	s_addc_u32 s89, s69, s49
	global_load_lds_dwordx4 v138, s[88:89]
	s_add_u32 m0, s32, 0x1a000
	s_add_u32 s90, s68, s50
	s_addc_u32 s91, s69, s51
	global_load_lds_dwordx4 v140, s[88:89]
	s_add_u32 m0, s32, 0x1c000
	s_add_u32 s92, s68, s60
	s_addc_u32 s93, s69, s61
	global_load_lds_dwordx4 v138, s[90:91]
	s_add_u32 m0, s32, 0x1e000
	s_nop 0
	global_load_lds_dwordx4 v140, s[90:91]
	s_add_u32 m0, s32, 0x8000
	s_nop 0
	global_load_lds_dwordx4 v142, s[92:93]
	s_add_u32 m0, s32, 0xa000
	s_nop 0
	global_load_lds_dwordx4 v144, s[92:93]
	s_waitcnt vmcnt(6)
	s_waitcnt lgkmcnt(0)
	s_barrier
	s_setprio 1
	s_waitcnt lgkmcnt(0)
	v_mfma_f32_16x16x32_bf16 v[60:63], v[200:203], v[168:171], v[60:63]
	v_mfma_f32_16x16x32_bf16 v[56:59], v[200:203], v[176:179], v[56:59]
	v_mfma_f32_16x16x32_bf16 v[52:55], v[208:211], v[168:171], v[52:55]
	v_mfma_f32_16x16x32_bf16 v[48:51], v[208:211], v[176:179], v[48:51]
	v_mfma_f32_16x16x32_bf16 v[44:47], v[216:219], v[168:171], v[44:47]
	v_mfma_f32_16x16x32_bf16 v[40:43], v[216:219], v[176:179], v[40:43]
	v_mfma_f32_16x16x32_bf16 v[36:39], v[224:227], v[168:171], v[36:39]
	v_mfma_f32_16x16x32_bf16 v[32:35], v[224:227], v[176:179], v[32:35]
	v_mfma_f32_16x16x32_bf16 v[28:31], v[200:203], v[184:187], v[28:31]
	v_mfma_f32_16x16x32_bf16 v[24:27], v[200:203], v[192:195], v[24:27]
	v_mfma_f32_16x16x32_bf16 v[20:23], v[208:211], v[184:187], v[20:23]
	v_mfma_f32_16x16x32_bf16 v[16:19], v[208:211], v[192:195], v[16:19]
	v_mfma_f32_16x16x32_bf16 v[12:15], v[216:219], v[184:187], v[12:15]
	v_mfma_f32_16x16x32_bf16 v[8:11], v[216:219], v[192:195], v[8:11]
	v_mfma_f32_16x16x32_bf16 v[4:7], v[224:227], v[184:187], v[4:7]
	v_mfma_f32_16x16x32_bf16 v[0:3], v[224:227], v[192:195], v[0:3]
	v_mfma_f32_16x16x32_bf16 v[60:63], v[204:207], v[172:175], v[60:63]
	v_mfma_f32_16x16x32_bf16 v[56:59], v[204:207], v[180:183], v[56:59]
	v_mfma_f32_16x16x32_bf16 v[52:55], v[212:215], v[172:175], v[52:55]
	v_mfma_f32_16x16x32_bf16 v[48:51], v[212:215], v[180:183], v[48:51]
	v_mfma_f32_16x16x32_bf16 v[44:47], v[220:223], v[172:175], v[44:47]
	v_mfma_f32_16x16x32_bf16 v[40:43], v[220:223], v[180:183], v[40:43]
	v_mfma_f32_16x16x32_bf16 v[36:39], v[228:231], v[172:175], v[36:39]
	v_mfma_f32_16x16x32_bf16 v[32:35], v[228:231], v[180:183], v[32:35]
	v_mfma_f32_16x16x32_bf16 v[28:31], v[204:207], v[188:191], v[28:31]
	v_mfma_f32_16x16x32_bf16 v[24:27], v[204:207], v[196:199], v[24:27]
	v_mfma_f32_16x16x32_bf16 v[20:23], v[212:215], v[188:191], v[20:23]
	v_mfma_f32_16x16x32_bf16 v[16:19], v[212:215], v[196:199], v[16:19]
	v_mfma_f32_16x16x32_bf16 v[12:15], v[220:223], v[188:191], v[12:15]
	v_mfma_f32_16x16x32_bf16 v[8:11], v[220:223], v[196:199], v[8:11]
	v_mfma_f32_16x16x32_bf16 v[4:7], v[228:231], v[188:191], v[4:7]
	v_mfma_f32_16x16x32_bf16 v[0:3], v[228:231], v[196:199], v[0:3]
	s_setprio 0
	s_barrier
; #define STAGE(Pp, BASE, br, kt) do { const u16* _g = (BASE) + ((long)(br) * K + (long)(kt) * BK); \
;     __builtin_amdgcn_global_load_lds((const unsigned*)(_g + voff0), (unsigned*)((char*)(Pp) + tb16), 16, 0, 0); \
;     __builtin_amdgcn_global_load_lds((const unsigned*)(_g + voff1), (unsigned*)((char*)(Pp) + tb16 + 8192), 16, 0, 0); } while (0)
; #define LDA(dst, b, h) _Pragma("unroll") for (int m = 0; m < 4; ++m) _Pragma("unroll") for (int k = 0; k < 2; ++k) \
;     dst[m][k] = *reinterpret_cast<const bf16x8*>((const char*)shm + aB + (((b) * 2 + (h)) * 16384 + (m * 2 + k) * 1024))
; #define LDB(dst, b, h) _Pragma("unroll") for (int n = 0; n < 2; ++n) _Pragma("unroll") for (int k = 0; k < 2; ++k) \
;     dst[n][k] = *reinterpret_cast<const bf16x8*>((const char*)shm + bB + (((b) * 2 + (h)) * 16384 + (n * 2 + k) * 1024))
; #define WAIT_V(n) asm volatile("s_waitcnt vmcnt(" #n ")" ::: "memory")
; #define WAIT_L(n) asm volatile("s_waitcnt lgkmcnt(" #n ")" ::: "memory")
; #define BAR __builtin_amdgcn_s_barrier()
; #define SCHED __builtin_amdgcn_sched_barrier(0)
; template <int MODE> ...
;     ...
;     }
;     {
;       LDB(B0, 0, 0); LDB(B1, 0, 1); LDA(At, 0, 0); STAGE(SA(1, 1), A, brow + HALF, nt - 1);
;       WAIT_L(0); BAR; MMA2(0, 0, 0, 1); BAR; SCHED;
;       LDA(At, 0, 1); WAIT_V(0); WAIT_L(0); BAR; MMA2(1, 0, 1, 1); BAR; SCHED;
	s_add_i32 s70, s70, 2
	s_add_u32 s68, s68, 0x100
	s_addc_u32 s69, s69, 0
	s_cmp_lt_u32 s70, 60
	s_cbranch_scc1 .LBB0_177
	s_add_u32 s66, s66, 0x1f80
	v_readfirstlane_b32 s68, v165
	s_addc_u32 s67, s67, 0
	s_mov_b32 m0, s68
	v_readfirstlane_b32 s68, v166
	ds_read_b128 v[138:141], v148
	ds_read_b128 v[142:145], v148 offset:1024
	ds_read_b128 v[168:171], v148 offset:2048
	ds_read_b128 v[172:175], v148 offset:3072
	ds_read_b128 v[176:179], v148 offset:16384
	ds_read_b128 v[180:183], v148 offset:17408
	ds_read_b128 v[184:187], v148 offset:18432
	ds_read_b128 v[188:191], v148 offset:19456
	ds_read_b128 v[192:195], v147
	ds_read_b128 v[196:199], v147 offset:1024
	ds_read_b128 v[200:203], v147 offset:2048
	ds_read_b128 v[204:207], v147 offset:3072
	ds_read_b128 v[208:211], v147 offset:4096
	ds_read_b128 v[212:215], v147 offset:5120
	ds_read_b128 v[216:219], v147 offset:6144
	ds_read_b128 v[220:223], v147 offset:7168
	global_load_lds_dwordx4 v134, s[66:67]
	s_mov_b32 m0, s68
	s_nop 0
	global_load_lds_dwordx4 v136, s[66:67]
	s_waitcnt lgkmcnt(0)
	s_barrier
	s_setprio 1
	s_waitcnt lgkmcnt(0)
	v_mfma_f32_16x16x32_bf16 v[124:127], v[192:195], v[138:141], v[124:127]
	v_mfma_f32_16x16x32_bf16 v[120:123], v[192:195], v[168:171], v[120:123]
	v_mfma_f32_16x16x32_bf16 v[116:119], v[200:203], v[138:141], v[116:119]
	v_mfma_f32_16x16x32_bf16 v[112:115], v[200:203], v[168:171], v[112:115]
	v_mfma_f32_16x16x32_bf16 v[108:111], v[208:211], v[138:141], v[108:111]
	v_mfma_f32_16x16x32_bf16 v[104:107], v[208:211], v[168:171], v[104:107]
	v_mfma_f32_16x16x32_bf16 v[100:103], v[216:219], v[138:141], v[100:103]
	v_mfma_f32_16x16x32_bf16 v[96:99], v[216:219], v[168:171], v[96:99]
	v_mfma_f32_16x16x32_bf16 v[92:95], v[192:195], v[176:179], v[92:95]
	v_mfma_f32_16x16x32_bf16 v[88:91], v[192:195], v[184:187], v[88:91]
	v_mfma_f32_16x16x32_bf16 v[84:87], v[200:203], v[176:179], v[84:87]
	v_mfma_f32_16x16x32_bf16 v[80:83], v[200:203], v[184:187], v[80:83]
	v_mfma_f32_16x16x32_bf16 v[76:79], v[208:211], v[176:179], v[76:79]
	v_mfma_f32_16x16x32_bf16 v[72:75], v[208:211], v[184:187], v[72:75]
	v_mfma_f32_16x16x32_bf16 v[68:71], v[216:219], v[176:179], v[68:71]
	v_mfma_f32_16x16x32_bf16 v[64:67], v[216:219], v[184:187], v[64:67]
	v_mfma_f32_16x16x32_bf16 v[124:127], v[196:199], v[142:145], v[124:127]
	v_mfma_f32_16x16x32_bf16 v[120:123], v[196:199], v[172:175], v[120:123]
	v_mfma_f32_16x16x32_bf16 v[116:119], v[204:207], v[142:145], v[116:119]
	v_mfma_f32_16x16x32_bf16 v[112:115], v[204:207], v[172:175], v[112:115]
	v_mfma_f32_16x16x32_bf16 v[108:111], v[212:215], v[142:145], v[108:111]
	v_mfma_f32_16x16x32_bf16 v[104:107], v[212:215], v[172:175], v[104:107]
	v_mfma_f32_16x16x32_bf16 v[100:103], v[220:223], v[142:145], v[100:103]
	v_mfma_f32_16x16x32_bf16 v[96:99], v[220:223], v[172:175], v[96:99]
	v_mfma_f32_16x16x32_bf16 v[92:95], v[196:199], v[180:183], v[92:95]
	v_mfma_f32_16x16x32_bf16 v[88:91], v[196:199], v[188:191], v[88:91]
	v_mfma_f32_16x16x32_bf16 v[84:87], v[204:207], v[180:183], v[84:87]
	v_mfma_f32_16x16x32_bf16 v[80:83], v[204:207], v[188:191], v[80:83]
	v_mfma_f32_16x16x32_bf16 v[76:79], v[212:215], v[180:183], v[76:79]
	v_mfma_f32_16x16x32_bf16 v[72:75], v[212:215], v[188:191], v[72:75]
	v_mfma_f32_16x16x32_bf16 v[68:71], v[220:223], v[180:183], v[68:71]
	v_mfma_f32_16x16x32_bf16 v[64:67], v[220:223], v[188:191], v[64:67]
	s_setprio 0
	s_barrier
	ds_read_b128 v[192:195], v147 offset:16384
	ds_read_b128 v[196:199], v147 offset:17408
	ds_read_b128 v[200:203], v147 offset:18432
	ds_read_b128 v[204:207], v147 offset:19456
	ds_read_b128 v[208:211], v147 offset:20480
	ds_read_b128 v[212:215], v147 offset:21504
	ds_read_b128 v[216:219], v147 offset:22528
	ds_read_b128 v[220:223], v147 offset:23552
	s_waitcnt vmcnt(0)
	s_waitcnt lgkmcnt(0)
	s_barrier
	s_setprio 1
	s_waitcnt lgkmcnt(0)
	v_mfma_f32_16x16x32_bf16 v[56:59], v[192:195], v[168:171], v[56:59]
	v_mfma_f32_16x16x32_bf16 v[52:55], v[200:203], v[138:141], v[52:55]
	v_mfma_f32_16x16x32_bf16 v[48:51], v[200:203], v[168:171], v[48:51]
	v_mfma_f32_16x16x32_bf16 v[44:47], v[208:211], v[138:141], v[44:47]
	v_mfma_f32_16x16x32_bf16 v[40:43], v[208:211], v[168:171], v[40:43]
	v_mfma_f32_16x16x32_bf16 v[36:39], v[216:219], v[138:141], v[36:39]
	v_mfma_f32_16x16x32_bf16 v[32:35], v[216:219], v[168:171], v[32:35]
	v_mfma_f32_16x16x32_bf16 v[28:31], v[192:195], v[176:179], v[28:31]
	v_mfma_f32_16x16x32_bf16 v[24:27], v[192:195], v[184:187], v[24:27]
	v_mfma_f32_16x16x32_bf16 v[20:23], v[200:203], v[176:179], v[20:23]
	v_mfma_f32_16x16x32_bf16 v[16:19], v[200:203], v[184:187], v[16:19]
	v_mfma_f32_16x16x32_bf16 v[12:15], v[208:211], v[176:179], v[12:15]
	v_mfma_f32_16x16x32_bf16 v[8:11], v[208:211], v[184:187], v[8:11]
	v_mfma_f32_16x16x32_bf16 v[4:7], v[216:219], v[176:179], v[4:7]
	v_mfma_f32_16x16x32_bf16 v[0:3], v[216:219], v[184:187], v[0:3]
	v_mfma_f32_16x16x32_bf16 v[60:63], v[192:195], v[138:141], v[60:63]
	v_mfma_f32_16x16x32_bf16 v[56:59], v[196:199], v[172:175], v[56:59]
	v_mfma_f32_16x16x32_bf16 v[52:55], v[204:207], v[142:145], v[52:55]
	v_mfma_f32_16x16x32_bf16 v[48:51], v[204:207], v[172:175], v[48:51]
	v_mfma_f32_16x16x32_bf16 v[44:47], v[212:215], v[142:145], v[44:47]
	v_mfma_f32_16x16x32_bf16 v[40:43], v[212:215], v[172:175], v[40:43]
	v_mfma_f32_16x16x32_bf16 v[36:39], v[220:223], v[142:145], v[36:39]
	v_mfma_f32_16x16x32_bf16 v[32:35], v[220:223], v[172:175], v[32:35]
	v_mfma_f32_16x16x32_bf16 v[28:31], v[196:199], v[180:183], v[28:31]
	v_mfma_f32_16x16x32_bf16 v[24:27], v[196:199], v[188:191], v[24:27]
	v_mfma_f32_16x16x32_bf16 v[20:23], v[204:207], v[180:183], v[20:23]
	v_mfma_f32_16x16x32_bf16 v[16:19], v[204:207], v[188:191], v[16:19]
	v_mfma_f32_16x16x32_bf16 v[12:15], v[212:215], v[180:183], v[12:15]
	v_mfma_f32_16x16x32_bf16 v[8:11], v[212:215], v[188:191], v[8:11]
	v_mfma_f32_16x16x32_bf16 v[4:7], v[220:223], v[180:183], v[4:7]
	v_mfma_f32_16x16x32_bf16 v[0:3], v[220:223], v[188:191], v[0:3]
	v_mfma_f32_16x16x32_bf16 v[224:227], v[196:199], v[142:145], v[60:63]
	s_setprio 0
	s_barrier
; #define LDA(dst, b, h) _Pragma("unroll") for (int m = 0; m < 4; ++m) _Pragma("unroll") for (int k = 0; k < 2; ++k) \
;     dst[m][k] = *reinterpret_cast<const bf16x8*>((const char*)shm + aB + (((b) * 2 + (h)) * 16384 + (m * 2 + k) * 1024))
; #define LDB(dst, b, h) _Pragma("unroll") for (int n = 0; n < 2; ++n) _Pragma("unroll") for (int k = 0; k < 2; ++k) \
;     dst[n][k] = *reinterpret_cast<const bf16x8*>((const char*)shm + bB + (((b) * 2 + (h)) * 16384 + (n * 2 + k) * 1024))
; #define WAIT_L(n) asm volatile("s_waitcnt lgkmcnt(" #n ")" ::: "memory")
; #define BAR __builtin_amdgcn_s_barrier()
; #define SCHED __builtin_amdgcn_sched_barrier(0)
; template <int MODE> ...
;     ...
;       LDB(B0, 1, 0); LDB(B1, 1, 1); LDA(At, 1, 0); WAIT_L(0); BAR; MMA2(0, 0, 0, 1); BAR; SCHED;
;       LDA(At, 1, 1); WAIT_L(0); BAR; MMA2(1, 0, 1, 1); BAR; SCHED;
;     }
;     ...
;     if (wr == 0) BAR;
	ds_read_b128 v[138:141], v148 offset:32768
	ds_read_b128 v[142:145], v148 offset:33792
	ds_read_b128 v[168:171], v148 offset:34816
	ds_read_b128 v[172:175], v148 offset:35840
	ds_read_b128 v[176:179], v148 offset:49152
	ds_read_b128 v[180:183], v148 offset:50176
	ds_read_b128 v[184:187], v148 offset:51200
	ds_read_b128 v[188:191], v148 offset:52224
	ds_read_b128 v[60:63], v147 offset:32768
	ds_read_b128 v[192:195], v147 offset:33792
	ds_read_b128 v[196:199], v147 offset:34816
	ds_read_b128 v[200:203], v147 offset:35840
	ds_read_b128 v[204:207], v147 offset:36864
	ds_read_b128 v[208:211], v147 offset:37888
	ds_read_b128 v[212:215], v147 offset:38912
	ds_read_b128 v[216:219], v147 offset:39936
	s_waitcnt lgkmcnt(0)
	s_barrier
	s_setprio 1
	s_waitcnt lgkmcnt(0)
	v_mfma_f32_16x16x32_bf16 v[124:127], v[60:63], v[138:141], v[124:127]
	v_mfma_f32_16x16x32_bf16 v[120:123], v[60:63], v[168:171], v[120:123]
	v_mfma_f32_16x16x32_bf16 v[92:95], v[60:63], v[176:179], v[92:95]
	v_mfma_f32_16x16x32_bf16 v[60:63], v[60:63], v[184:187], v[88:91]
	v_mfma_f32_16x16x32_bf16 v[88:91], v[192:195], v[188:191], v[60:63]
	v_mfma_f32_16x16x32_bf16 v[60:63], v[196:199], v[176:179], v[84:87]
	v_mfma_f32_16x16x32_bf16 v[84:87], v[200:203], v[180:183], v[60:63]
	v_mfma_f32_16x16x32_bf16 v[60:63], v[196:199], v[184:187], v[80:83]
	v_mfma_f32_16x16x32_bf16 v[80:83], v[200:203], v[188:191], v[60:63]
	v_mfma_f32_16x16x32_bf16 v[60:63], v[204:207], v[176:179], v[76:79]
	v_mfma_f32_16x16x32_bf16 v[76:79], v[208:211], v[180:183], v[60:63]
	v_mfma_f32_16x16x32_bf16 v[60:63], v[204:207], v[184:187], v[72:75]
	v_mfma_f32_16x16x32_bf16 v[72:75], v[208:211], v[188:191], v[60:63]
	v_mfma_f32_16x16x32_bf16 v[60:63], v[212:215], v[176:179], v[68:71]
	v_mfma_f32_16x16x32_bf16 v[116:119], v[196:199], v[138:141], v[116:119]
	v_mfma_f32_16x16x32_bf16 v[112:115], v[196:199], v[168:171], v[112:115]
	v_mfma_f32_16x16x32_bf16 v[108:111], v[204:207], v[138:141], v[108:111]
	v_mfma_f32_16x16x32_bf16 v[104:107], v[204:207], v[168:171], v[104:107]
	v_mfma_f32_16x16x32_bf16 v[100:103], v[212:215], v[138:141], v[100:103]
	v_mfma_f32_16x16x32_bf16 v[96:99], v[212:215], v[168:171], v[96:99]
	v_mfma_f32_16x16x32_bf16 v[68:71], v[216:219], v[180:183], v[60:63]
	v_mfma_f32_16x16x32_bf16 v[60:63], v[212:215], v[184:187], v[64:67]
	v_mfma_f32_16x16x32_bf16 v[124:127], v[192:195], v[142:145], v[124:127]
	v_mfma_f32_16x16x32_bf16 v[120:123], v[192:195], v[172:175], v[120:123]
	v_mfma_f32_16x16x32_bf16 v[116:119], v[200:203], v[142:145], v[116:119]
	v_mfma_f32_16x16x32_bf16 v[112:115], v[200:203], v[172:175], v[112:115]
	v_mfma_f32_16x16x32_bf16 v[108:111], v[208:211], v[142:145], v[108:111]
	v_mfma_f32_16x16x32_bf16 v[104:107], v[208:211], v[172:175], v[104:107]
	v_mfma_f32_16x16x32_bf16 v[100:103], v[216:219], v[142:145], v[100:103]
	v_mfma_f32_16x16x32_bf16 v[96:99], v[216:219], v[172:175], v[96:99]
	v_mfma_f32_16x16x32_bf16 v[92:95], v[192:195], v[180:183], v[92:95]
	v_mfma_f32_16x16x32_bf16 v[60:63], v[216:219], v[188:191], v[60:63]
	s_setprio 0
	s_barrier
	ds_read_b128 v[192:195], v147 offset:49152
	ds_read_b128 v[196:199], v147 offset:50176
	ds_read_b128 v[200:203], v147 offset:51200
	ds_read_b128 v[204:207], v147 offset:52224
	ds_read_b128 v[208:211], v147 offset:53248
	ds_read_b128 v[212:215], v147 offset:54272
	ds_read_b128 v[216:219], v147 offset:55296
	ds_read_b128 v[220:223], v147 offset:56320
	s_waitcnt lgkmcnt(0)
	s_barrier
	s_setprio 1
	s_waitcnt lgkmcnt(0)
	v_mfma_f32_16x16x32_bf16 v[64:67], v[192:195], v[138:141], v[224:227]
	v_mfma_f32_16x16x32_bf16 v[56:59], v[192:195], v[168:171], v[56:59]
	v_mfma_f32_16x16x32_bf16 v[52:55], v[200:203], v[138:141], v[52:55]
	v_mfma_f32_16x16x32_bf16 v[48:51], v[200:203], v[168:171], v[48:51]
	v_mfma_f32_16x16x32_bf16 v[44:47], v[208:211], v[138:141], v[44:47]
	v_mfma_f32_16x16x32_bf16 v[40:43], v[208:211], v[168:171], v[40:43]
	v_mfma_f32_16x16x32_bf16 v[36:39], v[216:219], v[138:141], v[36:39]
	v_mfma_f32_16x16x32_bf16 v[32:35], v[216:219], v[168:171], v[32:35]
	v_mfma_f32_16x16x32_bf16 v[28:31], v[192:195], v[176:179], v[28:31]
	v_mfma_f32_16x16x32_bf16 v[24:27], v[192:195], v[184:187], v[24:27]
	v_mfma_f32_16x16x32_bf16 v[20:23], v[200:203], v[176:179], v[20:23]
	v_mfma_f32_16x16x32_bf16 v[16:19], v[200:203], v[184:187], v[16:19]
	v_mfma_f32_16x16x32_bf16 v[12:15], v[208:211], v[176:179], v[12:15]
	v_mfma_f32_16x16x32_bf16 v[8:11], v[208:211], v[184:187], v[8:11]
	v_mfma_f32_16x16x32_bf16 v[4:7], v[216:219], v[176:179], v[4:7]
	v_mfma_f32_16x16x32_bf16 v[0:3], v[216:219], v[184:187], v[0:3]
	v_mfma_f32_16x16x32_bf16 v[64:67], v[196:199], v[142:145], v[64:67]
	v_mfma_f32_16x16x32_bf16 v[56:59], v[196:199], v[172:175], v[56:59]
	v_mfma_f32_16x16x32_bf16 v[52:55], v[204:207], v[142:145], v[52:55]
	v_mfma_f32_16x16x32_bf16 v[48:51], v[204:207], v[172:175], v[48:51]
	v_mfma_f32_16x16x32_bf16 v[44:47], v[212:215], v[142:145], v[44:47]
	v_mfma_f32_16x16x32_bf16 v[40:43], v[212:215], v[172:175], v[40:43]
	v_mfma_f32_16x16x32_bf16 v[36:39], v[220:223], v[142:145], v[36:39]
	v_mfma_f32_16x16x32_bf16 v[32:35], v[220:223], v[172:175], v[32:35]
	v_mfma_f32_16x16x32_bf16 v[28:31], v[196:199], v[180:183], v[28:31]
	v_mfma_f32_16x16x32_bf16 v[24:27], v[196:199], v[188:191], v[24:27]
	v_mfma_f32_16x16x32_bf16 v[20:23], v[204:207], v[180:183], v[20:23]
	v_mfma_f32_16x16x32_bf16 v[16:19], v[204:207], v[188:191], v[16:19]
	v_mfma_f32_16x16x32_bf16 v[12:15], v[212:215], v[180:183], v[12:15]
	v_mfma_f32_16x16x32_bf16 v[8:11], v[212:215], v[188:191], v[8:11]
	v_mfma_f32_16x16x32_bf16 v[4:7], v[220:223], v[180:183], v[4:7]
	v_mfma_f32_16x16x32_bf16 v[0:3], v[220:223], v[188:191], v[0:3]
	s_setprio 0
	s_barrier
	s_and_saveexec_b64 s[66:67], s[6:7]
	s_cbranch_execz .LBB0_180
	s_barrier

; #define STAGE(Pp, BASE, br, kt) do { const u16* _g = (BASE) + ((long)(br) * K + (long)(kt) * BK); \
;     __builtin_amdgcn_global_load_lds((const unsigned*)(_g + voff0), (unsigned*)((char*)(Pp) + tb16), 16, 0, 0); \
;     __builtin_amdgcn_global_load_lds((const unsigned*)(_g + voff1), (unsigned*)((char*)(Pp) + tb16 + 8192), 16, 0, 0); } while (0)
; #define LDA(dst, b, h) _Pragma("unroll") for (int m = 0; m < 4; ++m) _Pragma("unroll") for (int k = 0; k < 2; ++k) \
;     dst[m][k] = *reinterpret_cast<const bf16x8*>((const char*)shm + aB + (((b) * 2 + (h)) * 16384 + (m * 2 + k) * 1024))
; #define LDB(dst, b, h) _Pragma("unroll") for (int n = 0; n < 2; ++n) _Pragma("unroll") for (int k = 0; k < 2; ++k) \
;     dst[n][k] = *reinterpret_cast<const bf16x8*>((const char*)shm + bB + (((b) * 2 + (h)) * 16384 + (n * 2 + k) * 1024))
; #define WAIT_V(n) asm volatile("s_waitcnt vmcnt(" #n ")" ::: "memory")
; #define WAIT_L(n) asm volatile("s_waitcnt lgkmcnt(" #n ")" ::: "memory")
; #define BAR __builtin_amdgcn_s_barrier()
; #define SCHED __builtin_amdgcn_sched_barrier(0)
; template <int MODE> ...
;     ...
;       LDB(B0, 0, 0); LDB(B1, 0, 1); LDA(At, 0, 0); STAGE(SA(1, 1), A, brow + HALF, t + 1);
;       WAIT_L(0); BAR; MMA2(0, 0, 0, 1); BAR; SCHED;
;       LDA(At, 0, 1); STAGE(SB(0, 0), Bt, bcol, t + 2); STAGE(SB(0, 1), Bt, bcol + HALF, t + 2); STAGE(SA(0, 0), A, brow, t + 2);
;       WAIT_V(6); WAIT_L(0); BAR; MMA2(1, 0, 1, 1); BAR; SCHED;
.LBB0_486:
	s_add_u32 m0, s32, 0xc000
	ds_read_b128 v[166:169], v145
	ds_read_b128 v[170:173], v145 offset:1024
	ds_read_b128 v[174:177], v145 offset:2048
	ds_read_b128 v[178:181], v145 offset:3072
	ds_read_b128 v[182:185], v145 offset:16384
	ds_read_b128 v[186:189], v145 offset:17408
	ds_read_b128 v[190:193], v145 offset:18432
	ds_read_b128 v[194:197], v145 offset:19456
	ds_read_b128 v[198:201], v144
	ds_read_b128 v[202:205], v144 offset:1024
	ds_read_b128 v[206:209], v144 offset:2048
	ds_read_b128 v[210:213], v144 offset:3072
	ds_read_b128 v[214:217], v144 offset:4096
	ds_read_b128 v[218:221], v144 offset:5120
	ds_read_b128 v[222:225], v144 offset:6144
	ds_read_b128 v[226:229], v144 offset:7168
	s_add_u32 s88, s72, s16
	s_addc_u32 s89, s73, s17
	global_load_lds_dwordx4 v140, s[88:89]
	s_add_u32 m0, s32, 0xe000
	s_nop 0
	global_load_lds_dwordx4 v142, s[88:89]
	s_waitcnt lgkmcnt(0)
	s_barrier
	s_setprio 1
	s_waitcnt lgkmcnt(0)
	v_mfma_f32_16x16x32_bf16 v[124:127], v[198:201], v[166:169], v[124:127]
	v_mfma_f32_16x16x32_bf16 v[120:123], v[198:201], v[174:177], v[120:123]
	v_mfma_f32_16x16x32_bf16 v[116:119], v[206:209], v[166:169], v[116:119]
	v_mfma_f32_16x16x32_bf16 v[112:115], v[206:209], v[174:177], v[112:115]
	v_mfma_f32_16x16x32_bf16 v[108:111], v[214:217], v[166:169], v[108:111]
	v_mfma_f32_16x16x32_bf16 v[104:107], v[214:217], v[174:177], v[104:107]
	v_mfma_f32_16x16x32_bf16 v[100:103], v[222:225], v[166:169], v[100:103]
	v_mfma_f32_16x16x32_bf16 v[96:99], v[222:225], v[174:177], v[96:99]
	v_mfma_f32_16x16x32_bf16 v[92:95], v[198:201], v[182:185], v[92:95]
	v_mfma_f32_16x16x32_bf16 v[88:91], v[198:201], v[190:193], v[88:91]
	v_mfma_f32_16x16x32_bf16 v[84:87], v[206:209], v[182:185], v[84:87]
	v_mfma_f32_16x16x32_bf16 v[80:83], v[206:209], v[190:193], v[80:83]
	v_mfma_f32_16x16x32_bf16 v[76:79], v[214:217], v[182:185], v[76:79]
	v_mfma_f32_16x16x32_bf16 v[72:75], v[214:217], v[190:193], v[72:75]
	v_mfma_f32_16x16x32_bf16 v[68:71], v[222:225], v[182:185], v[68:71]
	v_mfma_f32_16x16x32_bf16 v[64:67], v[222:225], v[190:193], v[64:67]
	v_mfma_f32_16x16x32_bf16 v[124:127], v[202:205], v[170:173], v[124:127]
	v_mfma_f32_16x16x32_bf16 v[120:123], v[202:205], v[178:181], v[120:123]
	v_mfma_f32_16x16x32_bf16 v[116:119], v[210:213], v[170:173], v[116:119]
	v_mfma_f32_16x16x32_bf16 v[112:115], v[210:213], v[178:181], v[112:115]
	v_mfma_f32_16x16x32_bf16 v[108:111], v[218:221], v[170:173], v[108:111]
	v_mfma_f32_16x16x32_bf16 v[104:107], v[218:221], v[178:181], v[104:107]
	v_mfma_f32_16x16x32_bf16 v[100:103], v[226:229], v[170:173], v[100:103]
	v_mfma_f32_16x16x32_bf16 v[96:99], v[226:229], v[178:181], v[96:99]
	v_mfma_f32_16x16x32_bf16 v[92:95], v[202:205], v[186:189], v[92:95]
	v_mfma_f32_16x16x32_bf16 v[88:91], v[202:205], v[194:197], v[88:91]
	v_mfma_f32_16x16x32_bf16 v[84:87], v[210:213], v[186:189], v[84:87]
	v_mfma_f32_16x16x32_bf16 v[80:83], v[210:213], v[194:197], v[80:83]
	v_mfma_f32_16x16x32_bf16 v[76:79], v[218:221], v[186:189], v[76:79]
	v_mfma_f32_16x16x32_bf16 v[72:75], v[218:221], v[194:197], v[72:75]
	v_mfma_f32_16x16x32_bf16 v[68:71], v[226:229], v[186:189], v[68:71]
	v_mfma_f32_16x16x32_bf16 v[64:67], v[226:229], v[194:197], v[64:67]
	s_setprio 0
	s_barrier
	s_add_u32 m0, s32, 0x10000
	ds_read_b128 v[198:201], v144 offset:16384
	ds_read_b128 v[202:205], v144 offset:17408
	ds_read_b128 v[206:209], v144 offset:18432
	ds_read_b128 v[210:213], v144 offset:19456
	ds_read_b128 v[214:217], v144 offset:20480
	ds_read_b128 v[218:221], v144 offset:21504
	ds_read_b128 v[222:225], v144 offset:22528
	ds_read_b128 v[226:229], v144 offset:23552
	s_add_u32 s88, s72, s38
	s_addc_u32 s89, s73, s39
	global_load_lds_dwordx4 v136, s[88:89]
	s_add_u32 m0, s32, 0x12000
	s_add_u32 s90, s72, s40
	s_addc_u32 s91, s73, s41
	global_load_lds_dwordx4 v138, s[88:89]
	s_add_u32 m0, s32, 0x14000
	s_add_u32 s92, s72, s42
	s_addc_u32 s93, s73, s43
	global_load_lds_dwordx4 v136, s[90:91]
	s_add_u32 m0, s32, 0x16000
	s_nop 0
	global_load_lds_dwordx4 v138, s[90:91]
	s_mov_b32 m0, s32
	s_nop 0
	global_load_lds_dwordx4 v140, s[92:93]
	s_add_u32 m0, s32, 0x2000
	s_nop 0
	global_load_lds_dwordx4 v142, s[92:93]
	s_waitcnt vmcnt(6)
	s_waitcnt lgkmcnt(0)
	s_barrier
	s_setprio 1
	s_waitcnt lgkmcnt(0)
	v_mfma_f32_16x16x32_bf16 v[60:63], v[198:201], v[166:169], v[60:63]
	v_mfma_f32_16x16x32_bf16 v[56:59], v[198:201], v[174:177], v[56:59]
	v_mfma_f32_16x16x32_bf16 v[52:55], v[206:209], v[166:169], v[52:55]
	v_mfma_f32_16x16x32_bf16 v[48:51], v[206:209], v[174:177], v[48:51]
	v_mfma_f32_16x16x32_bf16 v[44:47], v[214:217], v[166:169], v[44:47]
	v_mfma_f32_16x16x32_bf16 v[40:43], v[214:217], v[174:177], v[40:43]
	v_mfma_f32_16x16x32_bf16 v[36:39], v[222:225], v[166:169], v[36:39]
	v_mfma_f32_16x16x32_bf16 v[32:35], v[222:225], v[174:177], v[32:35]
	v_mfma_f32_16x16x32_bf16 v[28:31], v[198:201], v[182:185], v[28:31]
	v_mfma_f32_16x16x32_bf16 v[24:27], v[198:201], v[190:193], v[24:27]
	v_mfma_f32_16x16x32_bf16 v[20:23], v[206:209], v[182:185], v[20:23]
	v_mfma_f32_16x16x32_bf16 v[16:19], v[206:209], v[190:193], v[16:19]
	v_mfma_f32_16x16x32_bf16 v[12:15], v[214:217], v[182:185], v[12:15]
	v_mfma_f32_16x16x32_bf16 v[8:11], v[214:217], v[190:193], v[8:11]
	v_mfma_f32_16x16x32_bf16 v[4:7], v[222:225], v[182:185], v[4:7]
	v_mfma_f32_16x16x32_bf16 v[0:3], v[222:225], v[190:193], v[0:3]
	v_mfma_f32_16x16x32_bf16 v[60:63], v[202:205], v[170:173], v[60:63]
	v_mfma_f32_16x16x32_bf16 v[56:59], v[202:205], v[178:181], v[56:59]
	v_mfma_f32_16x16x32_bf16 v[52:55], v[210:213], v[170:173], v[52:55]
	v_mfma_f32_16x16x32_bf16 v[48:51], v[210:213], v[178:181], v[48:51]
	v_mfma_f32_16x16x32_bf16 v[44:47], v[218:221], v[170:173], v[44:47]
	v_mfma_f32_16x16x32_bf16 v[40:43], v[218:221], v[178:181], v[40:43]
	v_mfma_f32_16x16x32_bf16 v[36:39], v[226:229], v[170:173], v[36:39]
	v_mfma_f32_16x16x32_bf16 v[32:35], v[226:229], v[178:181], v[32:35]
	v_mfma_f32_16x16x32_bf16 v[28:31], v[202:205], v[186:189], v[28:31]
	v_mfma_f32_16x16x32_bf16 v[24:27], v[202:205], v[194:197], v[24:27]
	v_mfma_f32_16x16x32_bf16 v[20:23], v[210:213], v[186:189], v[20:23]
	v_mfma_f32_16x16x32_bf16 v[16:19], v[210:213], v[194:197], v[16:19]
	v_mfma_f32_16x16x32_bf16 v[12:15], v[218:221], v[186:189], v[12:15]
	v_mfma_f32_16x16x32_bf16 v[8:11], v[218:221], v[194:197], v[8:11]
	v_mfma_f32_16x16x32_bf16 v[4:7], v[226:229], v[186:189], v[4:7]
	v_mfma_f32_16x16x32_bf16 v[0:3], v[226:229], v[194:197], v[0:3]
	s_setprio 0
	s_barrier
; #define STAGE(Pp, BASE, br, kt) do { const u16* _g = (BASE) + ((long)(br) * K + (long)(kt) * BK); \
;     __builtin_amdgcn_global_load_lds((const unsigned*)(_g + voff0), (unsigned*)((char*)(Pp) + tb16), 16, 0, 0); \
;     __builtin_amdgcn_global_load_lds((const unsigned*)(_g + voff1), (unsigned*)((char*)(Pp) + tb16 + 8192), 16, 0, 0); } while (0)
; #define LDA(dst, b, h) _Pragma("unroll") for (int m = 0; m < 4; ++m) _Pragma("unroll") for (int k = 0; k < 2; ++k) \
;     dst[m][k] = *reinterpret_cast<const bf16x8*>((const char*)shm + aB + (((b) * 2 + (h)) * 16384 + (m * 2 + k) * 1024))
; #define LDB(dst, b, h) _Pragma("unroll") for (int n = 0; n < 2; ++n) _Pragma("unroll") for (int k = 0; k < 2; ++k) \
;     dst[n][k] = *reinterpret_cast<const bf16x8*>((const char*)shm + bB + (((b) * 2 + (h)) * 16384 + (n * 2 + k) * 1024))
; #define WAIT_V(n) asm volatile("s_waitcnt vmcnt(" #n ")" ::: "memory")
; #define WAIT_L(n) asm volatile("s_waitcnt lgkmcnt(" #n ")" ::: "memory")
; #define BAR __builtin_amdgcn_s_barrier()
; #define SCHED __builtin_amdgcn_sched_barrier(0)
; template <int MODE> ...
;     ...
;       LDB(B0, 1, 0); LDB(B1, 1, 1); LDA(At, 1, 0); STAGE(SA(0, 1), A, brow + HALF, t + 2);
;       WAIT_L(0); BAR; MMA2(0, 0, 0, 1); BAR; SCHED;
;       LDA(At, 1, 1); STAGE(SB(1, 0), Bt, bcol, t + 3); STAGE(SB(1, 1), Bt, bcol + HALF, t + 3); STAGE(SA(1, 0), A, brow, t + 3);
;       WAIT_V(6); WAIT_L(0); BAR; MMA2(1, 0, 1, 1); BAR; SCHED;
	s_add_u32 m0, s32, 0x4000
	ds_read_b128 v[166:169], v145 offset:32768
	ds_read_b128 v[170:173], v145 offset:33792
	ds_read_b128 v[174:177], v145 offset:34816
	ds_read_b128 v[178:181], v145 offset:35840
	ds_read_b128 v[182:185], v145 offset:49152
	ds_read_b128 v[186:189], v145 offset:50176
	ds_read_b128 v[190:193], v145 offset:51200
	ds_read_b128 v[194:197], v145 offset:52224
	ds_read_b128 v[198:201], v144 offset:32768
	ds_read_b128 v[202:205], v144 offset:33792
	ds_read_b128 v[206:209], v144 offset:34816
	ds_read_b128 v[210:213], v144 offset:35840
	ds_read_b128 v[214:217], v144 offset:36864
	ds_read_b128 v[218:221], v144 offset:37888
	ds_read_b128 v[222:225], v144 offset:38912
	ds_read_b128 v[226:229], v144 offset:39936
	s_add_u32 s88, s72, s44
	s_addc_u32 s89, s73, s45
	global_load_lds_dwordx4 v140, s[88:89]
	s_add_u32 m0, s32, 0x6000
	s_nop 0
	global_load_lds_dwordx4 v142, s[88:89]
	s_waitcnt lgkmcnt(0)
	s_barrier
	s_setprio 1
	s_waitcnt lgkmcnt(0)
	v_mfma_f32_16x16x32_bf16 v[124:127], v[198:201], v[166:169], v[124:127]
	v_mfma_f32_16x16x32_bf16 v[120:123], v[198:201], v[174:177], v[120:123]
	v_mfma_f32_16x16x32_bf16 v[116:119], v[206:209], v[166:169], v[116:119]
	v_mfma_f32_16x16x32_bf16 v[112:115], v[206:209], v[174:177], v[112:115]
	v_mfma_f32_16x16x32_bf16 v[108:111], v[214:217], v[166:169], v[108:111]
	v_mfma_f32_16x16x32_bf16 v[104:107], v[214:217], v[174:177], v[104:107]
	v_mfma_f32_16x16x32_bf16 v[100:103], v[222:225], v[166:169], v[100:103]
	v_mfma_f32_16x16x32_bf16 v[96:99], v[222:225], v[174:177], v[96:99]
	v_mfma_f32_16x16x32_bf16 v[92:95], v[198:201], v[182:185], v[92:95]
	v_mfma_f32_16x16x32_bf16 v[88:91], v[198:201], v[190:193], v[88:91]
	v_mfma_f32_16x16x32_bf16 v[84:87], v[206:209], v[182:185], v[84:87]
	v_mfma_f32_16x16x32_bf16 v[80:83], v[206:209], v[190:193], v[80:83]
	v_mfma_f32_16x16x32_bf16 v[76:79], v[214:217], v[182:185], v[76:79]
	v_mfma_f32_16x16x32_bf16 v[72:75], v[214:217], v[190:193], v[72:75]
	v_mfma_f32_16x16x32_bf16 v[68:71], v[222:225], v[182:185], v[68:71]
	v_mfma_f32_16x16x32_bf16 v[64:67], v[222:225], v[190:193], v[64:67]
	v_mfma_f32_16x16x32_bf16 v[124:127], v[202:205], v[170:173], v[124:127]
	v_mfma_f32_16x16x32_bf16 v[120:123], v[202:205], v[178:181], v[120:123]
	v_mfma_f32_16x16x32_bf16 v[116:119], v[210:213], v[170:173], v[116:119]
	v_mfma_f32_16x16x32_bf16 v[112:115], v[210:213], v[178:181], v[112:115]
	v_mfma_f32_16x16x32_bf16 v[108:111], v[218:221], v[170:173], v[108:111]
	v_mfma_f32_16x16x32_bf16 v[104:107], v[218:221], v[178:181], v[104:107]
	v_mfma_f32_16x16x32_bf16 v[100:103], v[226:229], v[170:173], v[100:103]
	v_mfma_f32_16x16x32_bf16 v[96:99], v[226:229], v[178:181], v[96:99]
	v_mfma_f32_16x16x32_bf16 v[92:95], v[202:205], v[186:189], v[92:95]
	v_mfma_f32_16x16x32_bf16 v[88:91], v[202:205], v[194:197], v[88:91]
	v_mfma_f32_16x16x32_bf16 v[84:87], v[210:213], v[186:189], v[84:87]
	v_mfma_f32_16x16x32_bf16 v[80:83], v[210:213], v[194:197], v[80:83]
	v_mfma_f32_16x16x32_bf16 v[76:79], v[218:221], v[186:189], v[76:79]
	v_mfma_f32_16x16x32_bf16 v[72:75], v[218:221], v[194:197], v[72:75]
	v_mfma_f32_16x16x32_bf16 v[68:71], v[226:229], v[186:189], v[68:71]
	v_mfma_f32_16x16x32_bf16 v[64:67], v[226:229], v[194:197], v[64:67]
	s_setprio 0
	s_barrier
	s_add_u32 m0, s32, 0x18000
	ds_read_b128 v[198:201], v144 offset:49152
	ds_read_b128 v[202:205], v144 offset:50176
	ds_read_b128 v[206:209], v144 offset:51200
	ds_read_b128 v[210:213], v144 offset:52224
	ds_read_b128 v[214:217], v144 offset:53248
	ds_read_b128 v[218:221], v144 offset:54272
	ds_read_b128 v[222:225], v144 offset:55296
	ds_read_b128 v[226:229], v144 offset:56320
	s_add_u32 s88, s72, s48
	s_addc_u32 s89, s73, s49
	global_load_lds_dwordx4 v136, s[88:89]
	s_add_u32 m0, s32, 0x1a000
	s_add_u32 s90, s72, s50
	s_addc_u32 s91, s73, s51
	global_load_lds_dwordx4 v138, s[88:89]
	s_add_u32 m0, s32, 0x1c000
	s_add_u32 s92, s72, s60
	s_addc_u32 s93, s73, s61
	global_load_lds_dwordx4 v136, s[90:91]
	s_add_u32 m0, s32, 0x1e000
	s_nop 0
	global_load_lds_dwordx4 v138, s[90:91]
	s_add_u32 m0, s32, 0x8000
	s_nop 0
	global_load_lds_dwordx4 v140, s[92:93]
	s_add_u32 m0, s32, 0xa000
	s_nop 0
	global_load_lds_dwordx4 v142, s[92:93]
	s_waitcnt vmcnt(6)
	s_waitcnt lgkmcnt(0)
	s_barrier
	s_setprio 1
	s_waitcnt lgkmcnt(0)
	v_mfma_f32_16x16x32_bf16 v[60:63], v[198:201], v[166:169], v[60:63]
	v_mfma_f32_16x16x32_bf16 v[56:59], v[198:201], v[174:177], v[56:59]
	v_mfma_f32_16x16x32_bf16 v[52:55], v[206:209], v[166:169], v[52:55]
	v_mfma_f32_16x16x32_bf16 v[48:51], v[206:209], v[174:177], v[48:51]
	v_mfma_f32_16x16x32_bf16 v[44:47], v[214:217], v[166:169], v[44:47]
	v_mfma_f32_16x16x32_bf16 v[40:43], v[214:217], v[174:177], v[40:43]
	v_mfma_f32_16x16x32_bf16 v[36:39], v[222:225], v[166:169], v[36:39]
	v_mfma_f32_16x16x32_bf16 v[32:35], v[222:225], v[174:177], v[32:35]
	v_mfma_f32_16x16x32_bf16 v[28:31], v[198:201], v[182:185], v[28:31]
	v_mfma_f32_16x16x32_bf16 v[24:27], v[198:201], v[190:193], v[24:27]
	v_mfma_f32_16x16x32_bf16 v[20:23], v[206:209], v[182:185], v[20:23]
	v_mfma_f32_16x16x32_bf16 v[16:19], v[206:209], v[190:193], v[16:19]
	v_mfma_f32_16x16x32_bf16 v[12:15], v[214:217], v[182:185], v[12:15]
	v_mfma_f32_16x16x32_bf16 v[8:11], v[214:217], v[190:193], v[8:11]
	v_mfma_f32_16x16x32_bf16 v[4:7], v[222:225], v[182:185], v[4:7]
	v_mfma_f32_16x16x32_bf16 v[0:3], v[222:225], v[190:193], v[0:3]
	v_mfma_f32_16x16x32_bf16 v[60:63], v[202:205], v[170:173], v[60:63]
	v_mfma_f32_16x16x32_bf16 v[56:59], v[202:205], v[178:181], v[56:59]
	v_mfma_f32_16x16x32_bf16 v[52:55], v[210:213], v[170:173], v[52:55]
	v_mfma_f32_16x16x32_bf16 v[48:51], v[210:213], v[178:181], v[48:51]
	v_mfma_f32_16x16x32_bf16 v[44:47], v[218:221], v[170:173], v[44:47]
	v_mfma_f32_16x16x32_bf16 v[40:43], v[218:221], v[178:181], v[40:43]
	v_mfma_f32_16x16x32_bf16 v[36:39], v[226:229], v[170:173], v[36:39]
	v_mfma_f32_16x16x32_bf16 v[32:35], v[226:229], v[178:181], v[32:35]
	v_mfma_f32_16x16x32_bf16 v[28:31], v[202:205], v[186:189], v[28:31]
	v_mfma_f32_16x16x32_bf16 v[24:27], v[202:205], v[194:197], v[24:27]
	v_mfma_f32_16x16x32_bf16 v[20:23], v[210:213], v[186:189], v[20:23]
	v_mfma_f32_16x16x32_bf16 v[16:19], v[210:213], v[194:197], v[16:19]
	v_mfma_f32_16x16x32_bf16 v[12:15], v[218:221], v[186:189], v[12:15]
	v_mfma_f32_16x16x32_bf16 v[8:11], v[218:221], v[194:197], v[8:11]
	v_mfma_f32_16x16x32_bf16 v[4:7], v[226:229], v[186:189], v[4:7]
	v_mfma_f32_16x16x32_bf16 v[0:3], v[226:229], v[194:197], v[0:3]
	s_setprio 0
	s_barrier
; #define STAGE(Pp, BASE, br, kt) do { const u16* _g = (BASE) + ((long)(br) * K + (long)(kt) * BK); \
;     __builtin_amdgcn_global_load_lds((const unsigned*)(_g + voff0), (unsigned*)((char*)(Pp) + tb16), 16, 0, 0); \
;     __builtin_amdgcn_global_load_lds((const unsigned*)(_g + voff1), (unsigned*)((char*)(Pp) + tb16 + 8192), 16, 0, 0); } while (0)
; #define LDA(dst, b, h) _Pragma("unroll") for (int m = 0; m < 4; ++m) _Pragma("unroll") for (int k = 0; k < 2; ++k) \
;     dst[m][k] = *reinterpret_cast<const bf16x8*>((const char*)shm + aB + (((b) * 2 + (h)) * 16384 + (m * 2 + k) * 1024))
; #define LDB(dst, b, h) _Pragma("unroll") for (int n = 0; n < 2; ++n) _Pragma("unroll") for (int k = 0; k < 2; ++k) \
;     dst[n][k] = *reinterpret_cast<const bf16x8*>((const char*)shm + bB + (((b) * 2 + (h)) * 16384 + (n * 2 + k) * 1024))
; #define WAIT_V(n) asm volatile("s_waitcnt vmcnt(" #n ")" ::: "memory")
; #define WAIT_L(n) asm volatile("s_waitcnt lgkmcnt(" #n ")" ::: "memory")
; #define BAR __builtin_amdgcn_s_barrier()
; #define SCHED __builtin_amdgcn_sched_barrier(0)
; template <int MODE> ...
;     ...
;     for (int t = 0; t < nt - 2; t += 2) {
;       LDB(B0, 0, 0); LDB(B1, 0, 1); LDA(At, 0, 0); STAGE(SA(1, 1), A, brow + HALF, t + 1);
;       WAIT_L(0); BAR; MMA2(0, 0, 0, 1); BAR; SCHED;
;       LDA(At, 0, 1); STAGE(SB(0, 0), Bt, bcol, t + 2); STAGE(SB(0, 1), Bt, bcol + HALF, t + 2); STAGE(SA(0, 0), A, brow, t + 2);
;       WAIT_V(6); WAIT_L(0); BAR; MMA2(1, 0, 1, 1); BAR; SCHED;
;       LDB(B0, 1, 0); LDB(B1, 1, 1); LDA(At, 1, 0); STAGE(SA(0, 1), A, brow + HALF, t + 2);
;       WAIT_L(0); BAR; MMA2(0, 0, 0, 1); BAR; SCHED;
;       LDA(At, 1, 1); STAGE(SB(1, 0), Bt, bcol, t + 3); STAGE(SB(1, 1), Bt, bcol + HALF, t + 3); STAGE(SA(1, 0), A, brow, t + 3);
;       WAIT_V(6); WAIT_L(0); BAR; MMA2(1, 0, 1, 1); BAR; SCHED;
;     }
;     {
;       LDB(B0, 0, 0); LDB(B1, 0, 1); LDA(At, 0, 0); STAGE(SA(1, 1), A, brow + HALF, nt - 1);
;       WAIT_L(0); BAR; MMA2(0, 0, 0, 1); BAR; SCHED;
;       LDA(At, 0, 1); WAIT_V(0); WAIT_L(0); BAR; MMA2(1, 0, 1, 1); BAR; SCHED;
	s_add_i32 s63, s63, 2
	s_add_u32 s72, s72, 0x100
	s_addc_u32 s73, s73, 0
	s_cmp_lt_u32 s63, 60
	s_cbranch_scc1 .LBB0_486
	s_add_u32 s70, s70, 0x1f80
	v_readfirstlane_b32 s63, v160
	s_addc_u32 s71, s71, 0
	s_mov_b32 m0, s63
	v_readfirstlane_b32 s63, v161
	ds_read_b128 v[136:139], v145
	ds_read_b128 v[140:143], v145 offset:1024
	ds_read_b128 v[166:169], v145 offset:2048
	ds_read_b128 v[170:173], v145 offset:3072
	ds_read_b128 v[174:177], v145 offset:16384
	ds_read_b128 v[178:181], v145 offset:17408
	ds_read_b128 v[182:185], v145 offset:18432
	ds_read_b128 v[186:189], v145 offset:19456
	ds_read_b128 v[190:193], v144
	ds_read_b128 v[194:197], v144 offset:1024
	ds_read_b128 v[198:201], v144 offset:2048
	ds_read_b128 v[202:205], v144 offset:3072
	ds_read_b128 v[206:209], v144 offset:4096
	ds_read_b128 v[210:213], v144 offset:5120
	ds_read_b128 v[214:217], v144 offset:6144
	ds_read_b128 v[218:221], v144 offset:7168
	global_load_lds_dwordx4 v132, s[70:71]
	s_mov_b32 m0, s63
	s_nop 0
	global_load_lds_dwordx4 v134, s[70:71]
	s_waitcnt lgkmcnt(0)
	s_barrier
	s_setprio 1
	s_waitcnt lgkmcnt(0)
	v_mfma_f32_16x16x32_bf16 v[124:127], v[190:193], v[136:139], v[124:127]
	v_mfma_f32_16x16x32_bf16 v[116:119], v[198:201], v[136:139], v[116:119]
	v_mfma_f32_16x16x32_bf16 v[108:111], v[206:209], v[136:139], v[108:111]
	v_mfma_f32_16x16x32_bf16 v[100:103], v[214:217], v[136:139], v[100:103]
	v_mfma_f32_16x16x32_bf16 v[96:99], v[214:217], v[166:169], v[96:99]
	v_mfma_f32_16x16x32_bf16 v[92:95], v[190:193], v[174:177], v[92:95]
	v_mfma_f32_16x16x32_bf16 v[88:91], v[190:193], v[182:185], v[88:91]
	v_mfma_f32_16x16x32_bf16 v[80:83], v[198:201], v[182:185], v[80:83]
	v_mfma_f32_16x16x32_bf16 v[76:79], v[206:209], v[174:177], v[76:79]
	v_mfma_f32_16x16x32_bf16 v[124:127], v[194:197], v[140:143], v[124:127]
	v_mfma_f32_16x16x32_bf16 v[120:123], v[190:193], v[166:169], v[120:123]
	v_mfma_f32_16x16x32_bf16 v[116:119], v[202:205], v[140:143], v[116:119]
	v_mfma_f32_16x16x32_bf16 v[112:115], v[198:201], v[166:169], v[112:115]
	v_mfma_f32_16x16x32_bf16 v[108:111], v[210:213], v[140:143], v[108:111]
	v_mfma_f32_16x16x32_bf16 v[104:107], v[206:209], v[166:169], v[104:107]
	v_mfma_f32_16x16x32_bf16 v[100:103], v[218:221], v[140:143], v[100:103]
	v_mfma_f32_16x16x32_bf16 v[96:99], v[218:221], v[170:173], v[96:99]
	v_mfma_f32_16x16x32_bf16 v[92:95], v[194:197], v[178:181], v[92:95]
	v_mfma_f32_16x16x32_bf16 v[88:91], v[194:197], v[186:189], v[88:91]
	v_mfma_f32_16x16x32_bf16 v[84:87], v[198:201], v[174:177], v[84:87]
	v_mfma_f32_16x16x32_bf16 v[80:83], v[202:205], v[186:189], v[80:83]
	v_mfma_f32_16x16x32_bf16 v[76:79], v[210:213], v[178:181], v[76:79]
	v_mfma_f32_16x16x32_bf16 v[72:75], v[206:209], v[182:185], v[72:75]
	v_mfma_f32_16x16x32_bf16 v[68:71], v[214:217], v[174:177], v[68:71]
	v_mfma_f32_16x16x32_bf16 v[64:67], v[214:217], v[182:185], v[64:67]
	v_mfma_f32_16x16x32_bf16 v[222:225], v[194:197], v[170:173], v[120:123]
	v_mfma_f32_16x16x32_bf16 v[226:229], v[202:205], v[170:173], v[112:115]
	v_mfma_f32_16x16x32_bf16 v[230:233], v[210:213], v[170:173], v[104:107]
	v_mfma_f32_16x16x32_bf16 v[190:193], v[202:205], v[178:181], v[84:87]
	v_mfma_f32_16x16x32_bf16 v[194:197], v[210:213], v[186:189], v[72:75]
	v_mfma_f32_16x16x32_bf16 v[198:201], v[218:221], v[178:181], v[68:71]
	v_mfma_f32_16x16x32_bf16 v[202:205], v[218:221], v[186:189], v[64:67]
	s_setprio 0
	s_barrier
	s_nop 0
	ds_read_b128 v[64:67], v144 offset:16384
	ds_read_b128 v[68:71], v144 offset:17408
	ds_read_b128 v[72:75], v144 offset:18432
	ds_read_b128 v[84:87], v144 offset:19456
	ds_read_b128 v[104:107], v144 offset:20480
	ds_read_b128 v[112:115], v144 offset:21504
	ds_read_b128 v[120:123], v144 offset:22528
	ds_read_b128 v[206:209], v144 offset:23552
	s_waitcnt vmcnt(0)
	s_waitcnt lgkmcnt(0)
	s_barrier
	s_setprio 1
	s_waitcnt lgkmcnt(0)
	v_mfma_f32_16x16x32_bf16 v[60:63], v[64:67], v[136:139], v[60:63]
	v_mfma_f32_16x16x32_bf16 v[56:59], v[64:67], v[166:169], v[56:59]
	v_mfma_f32_16x16x32_bf16 v[52:55], v[72:75], v[136:139], v[52:55]
	v_mfma_f32_16x16x32_bf16 v[48:51], v[72:75], v[166:169], v[48:51]
	v_mfma_f32_16x16x32_bf16 v[44:47], v[104:107], v[136:139], v[44:47]
	v_mfma_f32_16x16x32_bf16 v[40:43], v[104:107], v[166:169], v[40:43]
	v_mfma_f32_16x16x32_bf16 v[28:31], v[64:67], v[174:177], v[28:31]
	v_mfma_f32_16x16x32_bf16 v[24:27], v[64:67], v[182:185], v[24:27]
	v_mfma_f32_16x16x32_bf16 v[20:23], v[72:75], v[174:177], v[20:23]
	v_mfma_f32_16x16x32_bf16 v[60:63], v[68:71], v[140:143], v[60:63]
	v_mfma_f32_16x16x32_bf16 v[56:59], v[68:71], v[170:173], v[56:59]
	v_mfma_f32_16x16x32_bf16 v[52:55], v[84:87], v[140:143], v[52:55]
	v_mfma_f32_16x16x32_bf16 v[48:51], v[84:87], v[170:173], v[48:51]
	v_mfma_f32_16x16x32_bf16 v[44:47], v[112:115], v[140:143], v[44:47]
	v_mfma_f32_16x16x32_bf16 v[40:43], v[112:115], v[170:173], v[40:43]
	v_mfma_f32_16x16x32_bf16 v[36:39], v[120:123], v[136:139], v[36:39]
	v_mfma_f32_16x16x32_bf16 v[32:35], v[120:123], v[166:169], v[32:35]
	v_mfma_f32_16x16x32_bf16 v[28:31], v[68:71], v[178:181], v[28:31]
	v_mfma_f32_16x16x32_bf16 v[24:27], v[68:71], v[186:189], v[24:27]
	v_mfma_f32_16x16x32_bf16 v[20:23], v[84:87], v[178:181], v[20:23]
	v_mfma_f32_16x16x32_bf16 v[16:19], v[72:75], v[182:185], v[16:19]
	v_mfma_f32_16x16x32_bf16 v[12:15], v[104:107], v[174:177], v[12:15]
	v_mfma_f32_16x16x32_bf16 v[8:11], v[104:107], v[182:185], v[8:11]
	v_mfma_f32_16x16x32_bf16 v[4:7], v[120:123], v[174:177], v[4:7]
	v_mfma_f32_16x16x32_bf16 v[0:3], v[120:123], v[182:185], v[0:3]
	v_mfma_f32_16x16x32_bf16 v[136:139], v[206:209], v[140:143], v[36:39]
	v_mfma_f32_16x16x32_bf16 v[140:143], v[206:209], v[170:173], v[32:35]
	v_mfma_f32_16x16x32_bf16 v[166:169], v[84:87], v[186:189], v[16:19]
	v_mfma_f32_16x16x32_bf16 v[170:173], v[112:115], v[178:181], v[12:15]
	v_mfma_f32_16x16x32_bf16 v[210:213], v[112:115], v[186:189], v[8:11]
	v_mfma_f32_16x16x32_bf16 v[174:177], v[206:209], v[178:181], v[4:7]
	v_mfma_f32_16x16x32_bf16 v[178:181], v[206:209], v[186:189], v[0:3]
	s_setprio 0
	s_barrier
; #define LDA(dst, b, h) _Pragma("unroll") for (int m = 0; m < 4; ++m) _Pragma("unroll") for (int k = 0; k < 2; ++k) \
;     dst[m][k] = *reinterpret_cast<const bf16x8*>((const char*)shm + aB + (((b) * 2 + (h)) * 16384 + (m * 2 + k) * 1024))
; #define LDB(dst, b, h) _Pragma("unroll") for (int n = 0; n < 2; ++n) _Pragma("unroll") for (int k = 0; k < 2; ++k) \
;     dst[n][k] = *reinterpret_cast<const bf16x8*>((const char*)shm + bB + (((b) * 2 + (h)) * 16384 + (n * 2 + k) * 1024))
; #define WAIT_L(n) asm volatile("s_waitcnt lgkmcnt(" #n ")" ::: "memory")
; #define BAR __builtin_amdgcn_s_barrier()
; #define SCHED __builtin_amdgcn_sched_barrier(0)
; template <int MODE> ...
;     ...
;       LDB(B0, 1, 0); LDB(B1, 1, 1); LDA(At, 1, 0); WAIT_L(0); BAR; MMA2(0, 0, 0, 1); BAR; SCHED;
;       LDA(At, 1, 1); WAIT_L(0); BAR; MMA2(1, 0, 1, 1); BAR; SCHED;
;     }
;     ...
;     if (wr == 0) BAR;
	ds_read_b128 v[12:15], v145 offset:32768
	ds_read_b128 v[16:19], v145 offset:33792
	ds_read_b128 v[182:185], v145 offset:34816
	ds_read_b128 v[186:189], v145 offset:35840
	ds_read_b128 v[206:209], v145 offset:49152
	ds_read_b128 v[214:217], v145 offset:50176
	ds_read_b128 v[218:221], v145 offset:51200
	ds_read_b128 v[234:237], v145 offset:52224
	ds_read_b128 v[0:3], v144 offset:32768
	ds_read_b128 v[4:7], v144 offset:33792
	ds_read_b128 v[8:11], v144 offset:34816
	ds_read_b128 v[32:35], v144 offset:35840
	ds_read_b128 v[36:39], v144 offset:36864
	ds_read_b128 v[238:241], v144 offset:37888
	ds_read_b128 v[242:245], v144 offset:38912
	ds_read_b128 v[246:249], v144 offset:39936
	s_waitcnt lgkmcnt(0)
	s_barrier
	s_setprio 1
	s_waitcnt lgkmcnt(0)
	v_mfma_f32_16x16x32_bf16 v[64:67], v[0:3], v[12:15], v[124:127]
	v_mfma_f32_16x16x32_bf16 v[68:71], v[242:245], v[182:185], v[96:99]
	v_mfma_f32_16x16x32_bf16 v[120:123], v[4:7], v[16:19], v[64:67]
	v_mfma_f32_16x16x32_bf16 v[64:67], v[0:3], v[182:185], v[222:225]
	v_mfma_f32_16x16x32_bf16 v[84:87], v[246:249], v[186:189], v[68:71]
	v_mfma_f32_16x16x32_bf16 v[68:71], v[0:3], v[206:209], v[92:95]
	v_mfma_f32_16x16x32_bf16 v[0:3], v[0:3], v[218:221], v[88:91]
	v_mfma_f32_16x16x32_bf16 v[88:91], v[4:7], v[234:237], v[0:3]
	v_mfma_f32_16x16x32_bf16 v[0:3], v[8:11], v[206:209], v[190:193]
	v_mfma_f32_16x16x32_bf16 v[124:127], v[4:7], v[186:189], v[64:67]
	v_mfma_f32_16x16x32_bf16 v[64:67], v[8:11], v[12:15], v[116:119]
	v_mfma_f32_16x16x32_bf16 v[72:75], v[32:35], v[214:217], v[0:3]
	v_mfma_f32_16x16x32_bf16 v[0:3], v[8:11], v[218:221], v[80:83]
	v_mfma_f32_16x16x32_bf16 v[112:115], v[32:35], v[16:19], v[64:67]
	v_mfma_f32_16x16x32_bf16 v[64:67], v[8:11], v[182:185], v[226:229]
	v_mfma_f32_16x16x32_bf16 v[92:95], v[32:35], v[234:237], v[0:3]
	v_mfma_f32_16x16x32_bf16 v[0:3], v[36:39], v[206:209], v[76:79]
	v_mfma_f32_16x16x32_bf16 v[116:119], v[32:35], v[186:189], v[64:67]
	v_mfma_f32_16x16x32_bf16 v[64:67], v[36:39], v[12:15], v[108:111]
	v_mfma_f32_16x16x32_bf16 v[76:79], v[238:241], v[214:217], v[0:3]
	v_mfma_f32_16x16x32_bf16 v[0:3], v[36:39], v[218:221], v[194:197]
	v_mfma_f32_16x16x32_bf16 v[104:107], v[238:241], v[16:19], v[64:67]
	v_mfma_f32_16x16x32_bf16 v[64:67], v[36:39], v[182:185], v[230:233]
	v_mfma_f32_16x16x32_bf16 v[96:99], v[238:241], v[234:237], v[0:3]
	v_mfma_f32_16x16x32_bf16 v[0:3], v[242:245], v[206:209], v[198:201]
	v_mfma_f32_16x16x32_bf16 v[108:111], v[238:241], v[186:189], v[64:67]
	v_mfma_f32_16x16x32_bf16 v[64:67], v[242:245], v[12:15], v[100:103]
	v_mfma_f32_16x16x32_bf16 v[80:83], v[246:249], v[214:217], v[0:3]
	v_mfma_f32_16x16x32_bf16 v[0:3], v[242:245], v[218:221], v[202:205]
	v_mfma_f32_16x16x32_bf16 v[64:67], v[246:249], v[16:19], v[64:67]
	v_mfma_f32_16x16x32_bf16 v[68:71], v[4:7], v[214:217], v[68:71]
	v_mfma_f32_16x16x32_bf16 v[100:103], v[246:249], v[234:237], v[0:3]
	s_setprio 0
	s_barrier
	ds_read_b128 v[190:193], v144 offset:49152
	ds_read_b128 v[194:197], v144 offset:50176
	ds_read_b128 v[198:201], v144 offset:51200
	ds_read_b128 v[202:205], v144 offset:52224
	ds_read_b128 v[222:225], v144 offset:53248
	ds_read_b128 v[226:229], v144 offset:54272
	ds_read_b128 v[230:233], v144 offset:55296
	ds_read_b128 v[238:241], v144 offset:56320
	s_waitcnt lgkmcnt(0)
	s_barrier
	s_setprio 1
	s_waitcnt lgkmcnt(0)
	v_mfma_f32_16x16x32_bf16 v[4:7], v[190:193], v[182:185], v[56:59]
	v_mfma_f32_16x16x32_bf16 v[8:11], v[198:201], v[182:185], v[48:51]
	v_mfma_f32_16x16x32_bf16 v[0:3], v[190:193], v[12:15], v[60:63]
	v_mfma_f32_16x16x32_bf16 v[32:35], v[194:197], v[186:189], v[4:7]
	v_mfma_f32_16x16x32_bf16 v[4:7], v[198:201], v[12:15], v[52:55]
	v_mfma_f32_16x16x32_bf16 v[36:39], v[202:205], v[186:189], v[8:11]
	v_mfma_f32_16x16x32_bf16 v[8:11], v[222:225], v[12:15], v[44:47]
	v_mfma_f32_16x16x32_bf16 v[12:15], v[230:233], v[12:15], v[136:139]
	v_mfma_f32_16x16x32_bf16 v[0:3], v[194:197], v[16:19], v[0:3]
	v_mfma_f32_16x16x32_bf16 v[4:7], v[202:205], v[16:19], v[4:7]
	v_mfma_f32_16x16x32_bf16 v[8:11], v[226:229], v[16:19], v[8:11]
	v_mfma_f32_16x16x32_bf16 v[12:15], v[238:241], v[16:19], v[12:15]
	v_mfma_f32_16x16x32_bf16 v[16:19], v[230:233], v[182:185], v[140:143]
	v_mfma_f32_16x16x32_bf16 v[24:27], v[190:193], v[218:221], v[24:27]
	v_mfma_f32_16x16x32_bf16 v[44:47], v[238:241], v[186:189], v[16:19]
	v_mfma_f32_16x16x32_bf16 v[16:19], v[190:193], v[206:209], v[28:31]
	v_mfma_f32_16x16x32_bf16 v[48:51], v[194:197], v[234:237], v[24:27]
	v_mfma_f32_16x16x32_bf16 v[24:27], v[198:201], v[218:221], v[166:169]
	v_mfma_f32_16x16x32_bf16 v[28:31], v[222:225], v[218:221], v[210:213]
	v_mfma_f32_16x16x32_bf16 v[40:43], v[222:225], v[182:185], v[40:43]
	v_mfma_f32_16x16x32_bf16 v[20:23], v[198:201], v[206:209], v[20:23]
	v_mfma_f32_16x16x32_bf16 v[52:55], v[202:205], v[234:237], v[24:27]
	v_mfma_f32_16x16x32_bf16 v[24:27], v[222:225], v[206:209], v[170:173]
	v_mfma_f32_16x16x32_bf16 v[56:59], v[226:229], v[234:237], v[28:31]
	v_mfma_f32_16x16x32_bf16 v[28:31], v[230:233], v[206:209], v[174:177]
	v_mfma_f32_16x16x32_bf16 v[60:63], v[230:233], v[218:221], v[178:181]
	v_mfma_f32_16x16x32_bf16 v[40:43], v[226:229], v[186:189], v[40:43]
	v_mfma_f32_16x16x32_bf16 v[16:19], v[194:197], v[214:217], v[16:19]
	v_mfma_f32_16x16x32_bf16 v[20:23], v[202:205], v[214:217], v[20:23]
	v_mfma_f32_16x16x32_bf16 v[24:27], v[226:229], v[214:217], v[24:27]
	v_mfma_f32_16x16x32_bf16 v[28:31], v[238:241], v[214:217], v[28:31]
	v_mfma_f32_16x16x32_bf16 v[60:63], v[238:241], v[234:237], v[60:63]
	s_setprio 0
	s_barrier
	s_and_saveexec_b64 s[70:71], s[6:7]
	s_cbranch_execz .LBB0_489
	s_barrier

; #define STAGE(Pp, BASE, br, kt) do { const u16* _g = (BASE) + ((long)(br) * K + (long)(kt) * BK); \
;     __builtin_amdgcn_global_load_lds((const unsigned*)(_g + voff0), (unsigned*)((char*)(Pp) + tb16), 16, 0, 0); \
;     __builtin_amdgcn_global_load_lds((const unsigned*)(_g + voff1), (unsigned*)((char*)(Pp) + tb16 + 8192), 16, 0, 0); } while (0)
; #define LDA(dst, b, h) _Pragma("unroll") for (int m = 0; m < 4; ++m) _Pragma("unroll") for (int k = 0; k < 2; ++k) \
;     dst[m][k] = *reinterpret_cast<const bf16x8*>((const char*)shm + aB + (((b) * 2 + (h)) * 16384 + (m * 2 + k) * 1024))
; #define LDB(dst, b, h) _Pragma("unroll") for (int n = 0; n < 2; ++n) _Pragma("unroll") for (int k = 0; k < 2; ++k) \
;     dst[n][k] = *reinterpret_cast<const bf16x8*>((const char*)shm + bB + (((b) * 2 + (h)) * 16384 + (n * 2 + k) * 1024))
; #define WAIT_V(n) asm volatile("s_waitcnt vmcnt(" #n ")" ::: "memory")
; #define WAIT_L(n) asm volatile("s_waitcnt lgkmcnt(" #n ")" ::: "memory")
; #define BAR __builtin_amdgcn_s_barrier()
; #define SCHED __builtin_amdgcn_sched_barrier(0)
; template <int MODE> ...
;     ...
;       LDB(B0, 0, 0); LDB(B1, 0, 1); LDA(At, 0, 0); STAGE(SA(1, 1), A, brow + HALF, t + 1);
;       WAIT_L(0); BAR; MMA2(0, 0, 0, 1); BAR; SCHED;
;       LDA(At, 0, 1); STAGE(SB(0, 0), Bt, bcol, t + 2); STAGE(SB(0, 1), Bt, bcol + HALF, t + 2); STAGE(SA(0, 0), A, brow, t + 2);
;       WAIT_V(6); WAIT_L(0); BAR; MMA2(1, 0, 1, 1); BAR; SCHED;
.LBB0_591:
	s_add_u32 m0, s32, 0xc000
	ds_read_b128 v[168:171], v149
	ds_read_b128 v[172:175], v149 offset:1024
	ds_read_b128 v[176:179], v149 offset:2048
	ds_read_b128 v[180:183], v149 offset:3072
	ds_read_b128 v[184:187], v149 offset:16384
	ds_read_b128 v[188:191], v149 offset:17408
	ds_read_b128 v[192:195], v149 offset:18432
	ds_read_b128 v[196:199], v149 offset:19456
	ds_read_b128 v[200:203], v148
	ds_read_b128 v[204:207], v148 offset:1024
	ds_read_b128 v[208:211], v148 offset:2048
	ds_read_b128 v[212:215], v148 offset:3072
	ds_read_b128 v[216:219], v148 offset:4096
	ds_read_b128 v[220:223], v148 offset:5120
	ds_read_b128 v[224:227], v148 offset:6144
	ds_read_b128 v[228:231], v148 offset:7168
	s_add_u32 s88, s10, s38
	s_addc_u32 s89, s11, s39
	global_load_lds_dwordx4 v142, s[88:89]
	s_add_u32 m0, s32, 0xe000
	s_nop 0
	global_load_lds_dwordx4 v144, s[88:89]
	s_waitcnt lgkmcnt(0)
	s_barrier
	s_setprio 1
	s_waitcnt lgkmcnt(0)
	v_mfma_f32_16x16x32_bf16 v[124:127], v[200:203], v[168:171], v[124:127]
	v_mfma_f32_16x16x32_bf16 v[120:123], v[200:203], v[176:179], v[120:123]
	v_mfma_f32_16x16x32_bf16 v[116:119], v[208:211], v[168:171], v[116:119]
	v_mfma_f32_16x16x32_bf16 v[112:115], v[208:211], v[176:179], v[112:115]
	v_mfma_f32_16x16x32_bf16 v[108:111], v[216:219], v[168:171], v[108:111]
	v_mfma_f32_16x16x32_bf16 v[104:107], v[216:219], v[176:179], v[104:107]
	v_mfma_f32_16x16x32_bf16 v[100:103], v[224:227], v[168:171], v[100:103]
	v_mfma_f32_16x16x32_bf16 v[96:99], v[224:227], v[176:179], v[96:99]
	v_mfma_f32_16x16x32_bf16 v[88:91], v[200:203], v[184:187], v[88:91]
	v_mfma_f32_16x16x32_bf16 v[72:75], v[200:203], v[192:195], v[72:75]
	v_mfma_f32_16x16x32_bf16 v[56:59], v[208:211], v[184:187], v[56:59]
	v_mfma_f32_16x16x32_bf16 v[48:51], v[208:211], v[192:195], v[48:51]
	v_mfma_f32_16x16x32_bf16 v[44:47], v[216:219], v[184:187], v[44:47]
	v_mfma_f32_16x16x32_bf16 v[40:43], v[216:219], v[192:195], v[40:43]
	v_mfma_f32_16x16x32_bf16 v[36:39], v[224:227], v[184:187], v[36:39]
	v_mfma_f32_16x16x32_bf16 v[32:35], v[224:227], v[192:195], v[32:35]
	v_mfma_f32_16x16x32_bf16 v[124:127], v[204:207], v[172:175], v[124:127]
	v_mfma_f32_16x16x32_bf16 v[120:123], v[204:207], v[180:183], v[120:123]
	v_mfma_f32_16x16x32_bf16 v[116:119], v[212:215], v[172:175], v[116:119]
	v_mfma_f32_16x16x32_bf16 v[112:115], v[212:215], v[180:183], v[112:115]
	v_mfma_f32_16x16x32_bf16 v[108:111], v[220:223], v[172:175], v[108:111]
	v_mfma_f32_16x16x32_bf16 v[104:107], v[220:223], v[180:183], v[104:107]
	v_mfma_f32_16x16x32_bf16 v[100:103], v[228:231], v[172:175], v[100:103]
	v_mfma_f32_16x16x32_bf16 v[96:99], v[228:231], v[180:183], v[96:99]
	v_mfma_f32_16x16x32_bf16 v[88:91], v[204:207], v[188:191], v[88:91]
	v_mfma_f32_16x16x32_bf16 v[72:75], v[204:207], v[196:199], v[72:75]
	v_mfma_f32_16x16x32_bf16 v[56:59], v[212:215], v[188:191], v[56:59]
	v_mfma_f32_16x16x32_bf16 v[48:51], v[212:215], v[196:199], v[48:51]
	v_mfma_f32_16x16x32_bf16 v[44:47], v[220:223], v[188:191], v[44:47]
	v_mfma_f32_16x16x32_bf16 v[40:43], v[220:223], v[196:199], v[40:43]
	v_mfma_f32_16x16x32_bf16 v[36:39], v[228:231], v[188:191], v[36:39]
	v_mfma_f32_16x16x32_bf16 v[32:35], v[228:231], v[196:199], v[32:35]
	s_setprio 0
	s_barrier
	s_add_u32 m0, s32, 0x10000
	ds_read_b128 v[200:203], v148 offset:16384
	ds_read_b128 v[204:207], v148 offset:17408
	ds_read_b128 v[208:211], v148 offset:18432
	ds_read_b128 v[212:215], v148 offset:19456
	ds_read_b128 v[216:219], v148 offset:20480
	ds_read_b128 v[220:223], v148 offset:21504
	ds_read_b128 v[224:227], v148 offset:22528
	ds_read_b128 v[228:231], v148 offset:23552
	s_add_u32 s88, s10, s40
	s_addc_u32 s89, s11, s41
	global_load_lds_dwordx4 v138, s[88:89]
	s_add_u32 m0, s32, 0x12000
	s_add_u32 s90, s10, s42
	s_addc_u32 s91, s11, s43
	global_load_lds_dwordx4 v140, s[88:89]
	s_add_u32 m0, s32, 0x14000
	s_add_u32 s92, s10, s44
	s_addc_u32 s93, s11, s45
	global_load_lds_dwordx4 v138, s[90:91]
	s_add_u32 m0, s32, 0x16000
	s_nop 0
	global_load_lds_dwordx4 v140, s[90:91]
	s_mov_b32 m0, s32
	s_nop 0
	global_load_lds_dwordx4 v142, s[92:93]
	s_add_u32 m0, s32, 0x2000
	s_nop 0
	global_load_lds_dwordx4 v144, s[92:93]
	s_waitcnt vmcnt(6)
	s_waitcnt lgkmcnt(0)
	s_barrier
	s_setprio 1
	s_waitcnt lgkmcnt(0)
	v_mfma_f32_16x16x32_bf16 v[28:31], v[200:203], v[168:171], v[28:31]
	v_mfma_f32_16x16x32_bf16 v[24:27], v[200:203], v[176:179], v[24:27]
	v_mfma_f32_16x16x32_bf16 v[20:23], v[208:211], v[168:171], v[20:23]
	v_mfma_f32_16x16x32_bf16 v[16:19], v[208:211], v[176:179], v[16:19]
	v_mfma_f32_16x16x32_bf16 v[12:15], v[216:219], v[168:171], v[12:15]
	v_mfma_f32_16x16x32_bf16 v[8:11], v[216:219], v[176:179], v[8:11]
	v_mfma_f32_16x16x32_bf16 v[4:7], v[224:227], v[168:171], v[4:7]
	v_mfma_f32_16x16x32_bf16 v[0:3], v[224:227], v[176:179], v[0:3]
	v_mfma_f32_16x16x32_bf16 v[52:55], v[200:203], v[184:187], v[52:55]
	v_mfma_f32_16x16x32_bf16 v[60:63], v[200:203], v[192:195], v[60:63]
	v_mfma_f32_16x16x32_bf16 v[64:67], v[208:211], v[184:187], v[64:67]
	v_mfma_f32_16x16x32_bf16 v[68:71], v[208:211], v[192:195], v[68:71]
	v_mfma_f32_16x16x32_bf16 v[76:79], v[216:219], v[184:187], v[76:79]
	v_mfma_f32_16x16x32_bf16 v[80:83], v[216:219], v[192:195], v[80:83]
	v_mfma_f32_16x16x32_bf16 v[84:87], v[224:227], v[184:187], v[84:87]
	v_mfma_f32_16x16x32_bf16 v[92:95], v[224:227], v[192:195], v[92:95]
	v_mfma_f32_16x16x32_bf16 v[28:31], v[204:207], v[172:175], v[28:31]
	v_mfma_f32_16x16x32_bf16 v[24:27], v[204:207], v[180:183], v[24:27]
	v_mfma_f32_16x16x32_bf16 v[20:23], v[212:215], v[172:175], v[20:23]
	v_mfma_f32_16x16x32_bf16 v[16:19], v[212:215], v[180:183], v[16:19]
	v_mfma_f32_16x16x32_bf16 v[12:15], v[220:223], v[172:175], v[12:15]
	v_mfma_f32_16x16x32_bf16 v[8:11], v[220:223], v[180:183], v[8:11]
	v_mfma_f32_16x16x32_bf16 v[4:7], v[228:231], v[172:175], v[4:7]
	v_mfma_f32_16x16x32_bf16 v[0:3], v[228:231], v[180:183], v[0:3]
	v_mfma_f32_16x16x32_bf16 v[52:55], v[204:207], v[188:191], v[52:55]
	v_mfma_f32_16x16x32_bf16 v[60:63], v[204:207], v[196:199], v[60:63]
	v_mfma_f32_16x16x32_bf16 v[64:67], v[212:215], v[188:191], v[64:67]
	v_mfma_f32_16x16x32_bf16 v[68:71], v[212:215], v[196:199], v[68:71]
	v_mfma_f32_16x16x32_bf16 v[76:79], v[220:223], v[188:191], v[76:79]
	v_mfma_f32_16x16x32_bf16 v[80:83], v[220:223], v[196:199], v[80:83]
	v_mfma_f32_16x16x32_bf16 v[84:87], v[228:231], v[188:191], v[84:87]
	v_mfma_f32_16x16x32_bf16 v[92:95], v[228:231], v[196:199], v[92:95]
	s_setprio 0
	s_barrier
; #define STAGE(Pp, BASE, br, kt) do { const u16* _g = (BASE) + ((long)(br) * K + (long)(kt) * BK); \
;     __builtin_amdgcn_global_load_lds((const unsigned*)(_g + voff0), (unsigned*)((char*)(Pp) + tb16), 16, 0, 0); \
;     __builtin_amdgcn_global_load_lds((const unsigned*)(_g + voff1), (unsigned*)((char*)(Pp) + tb16 + 8192), 16, 0, 0); } while (0)
; #define LDA(dst, b, h) _Pragma("unroll") for (int m = 0; m < 4; ++m) _Pragma("unroll") for (int k = 0; k < 2; ++k) \
;     dst[m][k] = *reinterpret_cast<const bf16x8*>((const char*)shm + aB + (((b) * 2 + (h)) * 16384 + (m * 2 + k) * 1024))
; #define LDB(dst, b, h) _Pragma("unroll") for (int n = 0; n < 2; ++n) _Pragma("unroll") for (int k = 0; k < 2; ++k) \
;     dst[n][k] = *reinterpret_cast<const bf16x8*>((const char*)shm + bB + (((b) * 2 + (h)) * 16384 + (n * 2 + k) * 1024))
; #define WAIT_V(n) asm volatile("s_waitcnt vmcnt(" #n ")" ::: "memory")
; #define WAIT_L(n) asm volatile("s_waitcnt lgkmcnt(" #n ")" ::: "memory")
; #define BAR __builtin_amdgcn_s_barrier()
; #define SCHED __builtin_amdgcn_sched_barrier(0)
; template <int MODE> ...
;     ...
;       LDB(B0, 1, 0); LDB(B1, 1, 1); LDA(At, 1, 0); STAGE(SA(0, 1), A, brow + HALF, t + 2);
;       WAIT_L(0); BAR; MMA2(0, 0, 0, 1); BAR; SCHED;
;       LDA(At, 1, 1); STAGE(SB(1, 0), Bt, bcol, t + 3); STAGE(SB(1, 1), Bt, bcol + HALF, t + 3); STAGE(SA(1, 0), A, brow, t + 3);
;       WAIT_V(6); WAIT_L(0); BAR; MMA2(1, 0, 1, 1); BAR; SCHED;
	s_add_u32 m0, s32, 0x4000
	ds_read_b128 v[168:171], v149 offset:32768
	ds_read_b128 v[172:175], v149 offset:33792
	ds_read_b128 v[176:179], v149 offset:34816
	ds_read_b128 v[180:183], v149 offset:35840
	ds_read_b128 v[184:187], v149 offset:49152
	ds_read_b128 v[188:191], v149 offset:50176
	ds_read_b128 v[192:195], v149 offset:51200
	ds_read_b128 v[196:199], v149 offset:52224
	ds_read_b128 v[200:203], v148 offset:32768
	ds_read_b128 v[204:207], v148 offset:33792
	ds_read_b128 v[208:211], v148 offset:34816
	ds_read_b128 v[212:215], v148 offset:35840
	ds_read_b128 v[216:219], v148 offset:36864
	ds_read_b128 v[220:223], v148 offset:37888
	ds_read_b128 v[224:227], v148 offset:38912
	ds_read_b128 v[228:231], v148 offset:39936
	s_add_u32 s88, s10, s48
	s_addc_u32 s89, s11, s49
	global_load_lds_dwordx4 v142, s[88:89]
	s_add_u32 m0, s32, 0x6000
	s_nop 0
	global_load_lds_dwordx4 v144, s[88:89]
	s_waitcnt lgkmcnt(0)
	s_barrier
	s_setprio 1
	s_waitcnt lgkmcnt(0)
	v_mfma_f32_16x16x32_bf16 v[124:127], v[200:203], v[168:171], v[124:127]
	v_mfma_f32_16x16x32_bf16 v[120:123], v[200:203], v[176:179], v[120:123]
	v_mfma_f32_16x16x32_bf16 v[116:119], v[208:211], v[168:171], v[116:119]
	v_mfma_f32_16x16x32_bf16 v[112:115], v[208:211], v[176:179], v[112:115]
	v_mfma_f32_16x16x32_bf16 v[108:111], v[216:219], v[168:171], v[108:111]
	v_mfma_f32_16x16x32_bf16 v[104:107], v[216:219], v[176:179], v[104:107]
	v_mfma_f32_16x16x32_bf16 v[100:103], v[224:227], v[168:171], v[100:103]
	v_mfma_f32_16x16x32_bf16 v[96:99], v[224:227], v[176:179], v[96:99]
	v_mfma_f32_16x16x32_bf16 v[88:91], v[200:203], v[184:187], v[88:91]
	v_mfma_f32_16x16x32_bf16 v[72:75], v[200:203], v[192:195], v[72:75]
	v_mfma_f32_16x16x32_bf16 v[56:59], v[208:211], v[184:187], v[56:59]
	v_mfma_f32_16x16x32_bf16 v[48:51], v[208:211], v[192:195], v[48:51]
	v_mfma_f32_16x16x32_bf16 v[44:47], v[216:219], v[184:187], v[44:47]
	v_mfma_f32_16x16x32_bf16 v[40:43], v[216:219], v[192:195], v[40:43]
	v_mfma_f32_16x16x32_bf16 v[36:39], v[224:227], v[184:187], v[36:39]
	v_mfma_f32_16x16x32_bf16 v[32:35], v[224:227], v[192:195], v[32:35]
	v_mfma_f32_16x16x32_bf16 v[124:127], v[204:207], v[172:175], v[124:127]
	v_mfma_f32_16x16x32_bf16 v[120:123], v[204:207], v[180:183], v[120:123]
	v_mfma_f32_16x16x32_bf16 v[116:119], v[212:215], v[172:175], v[116:119]
	v_mfma_f32_16x16x32_bf16 v[112:115], v[212:215], v[180:183], v[112:115]
	v_mfma_f32_16x16x32_bf16 v[108:111], v[220:223], v[172:175], v[108:111]
	v_mfma_f32_16x16x32_bf16 v[104:107], v[220:223], v[180:183], v[104:107]
	v_mfma_f32_16x16x32_bf16 v[100:103], v[228:231], v[172:175], v[100:103]
	v_mfma_f32_16x16x32_bf16 v[96:99], v[228:231], v[180:183], v[96:99]
	v_mfma_f32_16x16x32_bf16 v[88:91], v[204:207], v[188:191], v[88:91]
	v_mfma_f32_16x16x32_bf16 v[72:75], v[204:207], v[196:199], v[72:75]
	v_mfma_f32_16x16x32_bf16 v[56:59], v[212:215], v[188:191], v[56:59]
	v_mfma_f32_16x16x32_bf16 v[48:51], v[212:215], v[196:199], v[48:51]
	v_mfma_f32_16x16x32_bf16 v[44:47], v[220:223], v[188:191], v[44:47]
	v_mfma_f32_16x16x32_bf16 v[40:43], v[220:223], v[196:199], v[40:43]
	v_mfma_f32_16x16x32_bf16 v[36:39], v[228:231], v[188:191], v[36:39]
	v_mfma_f32_16x16x32_bf16 v[32:35], v[228:231], v[196:199], v[32:35]
	s_setprio 0
	s_barrier
	s_add_u32 m0, s32, 0x18000
	ds_read_b128 v[200:203], v148 offset:49152
	ds_read_b128 v[204:207], v148 offset:50176
	ds_read_b128 v[208:211], v148 offset:51200
	ds_read_b128 v[212:215], v148 offset:52224
	ds_read_b128 v[216:219], v148 offset:53248
	ds_read_b128 v[220:223], v148 offset:54272
	ds_read_b128 v[224:227], v148 offset:55296
	ds_read_b128 v[228:231], v148 offset:56320
	s_add_u32 s88, s10, s50
	s_addc_u32 s89, s11, s51
	global_load_lds_dwordx4 v138, s[88:89]
	s_add_u32 m0, s32, 0x1a000
	s_add_u32 s90, s10, s60
	s_addc_u32 s91, s11, s61
	global_load_lds_dwordx4 v140, s[88:89]
	s_add_u32 m0, s32, 0x1c000
	s_add_u32 s92, s10, s62
	s_addc_u32 s93, s11, s63
	global_load_lds_dwordx4 v138, s[90:91]
	s_add_u32 m0, s32, 0x1e000
	s_nop 0
	global_load_lds_dwordx4 v140, s[90:91]
	s_add_u32 m0, s32, 0x8000
	s_nop 0
	global_load_lds_dwordx4 v142, s[92:93]
	s_add_u32 m0, s32, 0xa000
	s_nop 0
	global_load_lds_dwordx4 v144, s[92:93]
	s_waitcnt vmcnt(6)
	s_waitcnt lgkmcnt(0)
	s_barrier
	s_setprio 1
	s_waitcnt lgkmcnt(0)
	v_mfma_f32_16x16x32_bf16 v[28:31], v[200:203], v[168:171], v[28:31]
	v_mfma_f32_16x16x32_bf16 v[24:27], v[200:203], v[176:179], v[24:27]
	v_mfma_f32_16x16x32_bf16 v[20:23], v[208:211], v[168:171], v[20:23]
	v_mfma_f32_16x16x32_bf16 v[16:19], v[208:211], v[176:179], v[16:19]
	v_mfma_f32_16x16x32_bf16 v[12:15], v[216:219], v[168:171], v[12:15]
	v_mfma_f32_16x16x32_bf16 v[8:11], v[216:219], v[176:179], v[8:11]
	v_mfma_f32_16x16x32_bf16 v[4:7], v[224:227], v[168:171], v[4:7]
	v_mfma_f32_16x16x32_bf16 v[0:3], v[224:227], v[176:179], v[0:3]
	v_mfma_f32_16x16x32_bf16 v[52:55], v[200:203], v[184:187], v[52:55]
	v_mfma_f32_16x16x32_bf16 v[60:63], v[200:203], v[192:195], v[60:63]
	v_mfma_f32_16x16x32_bf16 v[64:67], v[208:211], v[184:187], v[64:67]
	v_mfma_f32_16x16x32_bf16 v[68:71], v[208:211], v[192:195], v[68:71]
	v_mfma_f32_16x16x32_bf16 v[76:79], v[216:219], v[184:187], v[76:79]
	v_mfma_f32_16x16x32_bf16 v[80:83], v[216:219], v[192:195], v[80:83]
	v_mfma_f32_16x16x32_bf16 v[84:87], v[224:227], v[184:187], v[84:87]
	v_mfma_f32_16x16x32_bf16 v[92:95], v[224:227], v[192:195], v[92:95]
	v_mfma_f32_16x16x32_bf16 v[28:31], v[204:207], v[172:175], v[28:31]
	v_mfma_f32_16x16x32_bf16 v[24:27], v[204:207], v[180:183], v[24:27]
	v_mfma_f32_16x16x32_bf16 v[20:23], v[212:215], v[172:175], v[20:23]
	v_mfma_f32_16x16x32_bf16 v[16:19], v[212:215], v[180:183], v[16:19]
	v_mfma_f32_16x16x32_bf16 v[12:15], v[220:223], v[172:175], v[12:15]
	v_mfma_f32_16x16x32_bf16 v[8:11], v[220:223], v[180:183], v[8:11]
	v_mfma_f32_16x16x32_bf16 v[4:7], v[228:231], v[172:175], v[4:7]
	v_mfma_f32_16x16x32_bf16 v[0:3], v[228:231], v[180:183], v[0:3]
	v_mfma_f32_16x16x32_bf16 v[52:55], v[204:207], v[188:191], v[52:55]
	v_mfma_f32_16x16x32_bf16 v[60:63], v[204:207], v[196:199], v[60:63]
	v_mfma_f32_16x16x32_bf16 v[64:67], v[212:215], v[188:191], v[64:67]
	v_mfma_f32_16x16x32_bf16 v[68:71], v[212:215], v[196:199], v[68:71]
	v_mfma_f32_16x16x32_bf16 v[76:79], v[220:223], v[188:191], v[76:79]
	v_mfma_f32_16x16x32_bf16 v[80:83], v[220:223], v[196:199], v[80:83]
	v_mfma_f32_16x16x32_bf16 v[84:87], v[228:231], v[188:191], v[84:87]
	v_mfma_f32_16x16x32_bf16 v[92:95], v[228:231], v[196:199], v[92:95]
	s_setprio 0
	s_barrier
; #define STAGE(Pp, BASE, br, kt) do { const u16* _g = (BASE) + ((long)(br) * K + (long)(kt) * BK); \
;     __builtin_amdgcn_global_load_lds((const unsigned*)(_g + voff0), (unsigned*)((char*)(Pp) + tb16), 16, 0, 0); \
;     __builtin_amdgcn_global_load_lds((const unsigned*)(_g + voff1), (unsigned*)((char*)(Pp) + tb16 + 8192), 16, 0, 0); } while (0)
; #define LDA(dst, b, h) _Pragma("unroll") for (int m = 0; m < 4; ++m) _Pragma("unroll") for (int k = 0; k < 2; ++k) \
;     dst[m][k] = *reinterpret_cast<const bf16x8*>((const char*)shm + aB + (((b) * 2 + (h)) * 16384 + (m * 2 + k) * 1024))
; #define LDB(dst, b, h) _Pragma("unroll") for (int n = 0; n < 2; ++n) _Pragma("unroll") for (int k = 0; k < 2; ++k) \
;     dst[n][k] = *reinterpret_cast<const bf16x8*>((const char*)shm + bB + (((b) * 2 + (h)) * 16384 + (n * 2 + k) * 1024))
; #define WAIT_V(n) asm volatile("s_waitcnt vmcnt(" #n ")" ::: "memory")
; #define WAIT_L(n) asm volatile("s_waitcnt lgkmcnt(" #n ")" ::: "memory")
; #define BAR __builtin_amdgcn_s_barrier()
; #define SCHED __builtin_amdgcn_sched_barrier(0)
; template <int MODE> ...
;     ...
;     for (int t = 0; t < nt - 2; t += 2) {
;       LDB(B0, 0, 0); LDB(B1, 0, 1); LDA(At, 0, 0); STAGE(SA(1, 1), A, brow + HALF, t + 1);
;       WAIT_L(0); BAR; MMA2(0, 0, 0, 1); BAR; SCHED;
;       LDA(At, 0, 1); STAGE(SB(0, 0), Bt, bcol, t + 2); STAGE(SB(0, 1), Bt, bcol + HALF, t + 2); STAGE(SA(0, 0), A, brow, t + 2);
;       WAIT_V(6); WAIT_L(0); BAR; MMA2(1, 0, 1, 1); BAR; SCHED;
;       LDB(B0, 1, 0); LDB(B1, 1, 1); LDA(At, 1, 0); STAGE(SA(0, 1), A, brow + HALF, t + 2);
;       WAIT_L(0); BAR; MMA2(0, 0, 0, 1); BAR; SCHED;
;       LDA(At, 1, 1); STAGE(SB(1, 0), Bt, bcol, t + 3); STAGE(SB(1, 1), Bt, bcol + HALF, t + 3); STAGE(SA(1, 0), A, brow, t + 3);
;       WAIT_V(6); WAIT_L(0); BAR; MMA2(1, 0, 1, 1); BAR; SCHED;
;     }
;     {
;       LDB(B0, 0, 0); LDB(B1, 0, 1); LDA(At, 0, 0); STAGE(SA(1, 1), A, brow + HALF, nt - 1);
;       WAIT_L(0); BAR; MMA2(0, 0, 0, 1); BAR; SCHED;
;       LDA(At, 0, 1); WAIT_V(0); WAIT_L(0); BAR; MMA2(1, 0, 1, 1); BAR; SCHED;
	s_add_i32 s35, s35, 2
	s_add_u32 s10, s10, 0x100
	s_addc_u32 s11, s11, 0
	s_cmp_lt_u32 s35, 60
	s_cbranch_scc1 .LBB0_591
	s_add_u32 s8, s8, 0x1f80
	v_readfirstlane_b32 s10, v165
	s_addc_u32 s9, s9, 0
	s_mov_b32 m0, s10
	v_readfirstlane_b32 s10, v166
	ds_read_b128 v[138:141], v149
	ds_read_b128 v[142:145], v149 offset:1024
	ds_read_b128 v[168:171], v149 offset:2048
	ds_read_b128 v[172:175], v149 offset:3072
	ds_read_b128 v[176:179], v149 offset:16384
	ds_read_b128 v[180:183], v149 offset:17408
	ds_read_b128 v[184:187], v149 offset:18432
	ds_read_b128 v[188:191], v149 offset:19456
	ds_read_b128 v[192:195], v148
	ds_read_b128 v[196:199], v148 offset:1024
	ds_read_b128 v[200:203], v148 offset:2048
	ds_read_b128 v[204:207], v148 offset:3072
	ds_read_b128 v[208:211], v148 offset:4096
	ds_read_b128 v[212:215], v148 offset:5120
	ds_read_b128 v[216:219], v148 offset:6144
	ds_read_b128 v[220:223], v148 offset:7168
	global_load_lds_dwordx4 v134, s[8:9]
	s_mov_b32 m0, s10
	s_nop 0
	global_load_lds_dwordx4 v136, s[8:9]
	s_waitcnt lgkmcnt(0)
	s_barrier
	s_setprio 1
	s_waitcnt lgkmcnt(0)
	v_mfma_f32_16x16x32_bf16 v[124:127], v[192:195], v[138:141], v[124:127]
	v_mfma_f32_16x16x32_bf16 v[120:123], v[192:195], v[168:171], v[120:123]
	v_mfma_f32_16x16x32_bf16 v[116:119], v[200:203], v[138:141], v[116:119]
	v_mfma_f32_16x16x32_bf16 v[112:115], v[200:203], v[168:171], v[112:115]
	v_mfma_f32_16x16x32_bf16 v[108:111], v[208:211], v[138:141], v[108:111]
	v_mfma_f32_16x16x32_bf16 v[104:107], v[208:211], v[168:171], v[104:107]
	v_mfma_f32_16x16x32_bf16 v[96:99], v[216:219], v[168:171], v[96:99]
	v_mfma_f32_16x16x32_bf16 v[88:91], v[192:195], v[176:179], v[88:91]
	v_mfma_f32_16x16x32_bf16 v[72:75], v[192:195], v[184:187], v[72:75]
	v_mfma_f32_16x16x32_bf16 v[56:59], v[200:203], v[176:179], v[56:59]
	v_mfma_f32_16x16x32_bf16 v[48:51], v[200:203], v[184:187], v[48:51]
	v_mfma_f32_16x16x32_bf16 v[44:47], v[208:211], v[176:179], v[44:47]
	v_mfma_f32_16x16x32_bf16 v[40:43], v[208:211], v[184:187], v[40:43]
	v_mfma_f32_16x16x32_bf16 v[36:39], v[216:219], v[176:179], v[36:39]
	v_mfma_f32_16x16x32_bf16 v[32:35], v[216:219], v[184:187], v[32:35]
	v_mfma_f32_16x16x32_bf16 v[124:127], v[196:199], v[142:145], v[124:127]
	v_mfma_f32_16x16x32_bf16 v[120:123], v[196:199], v[172:175], v[120:123]
	v_mfma_f32_16x16x32_bf16 v[116:119], v[204:207], v[142:145], v[116:119]
	v_mfma_f32_16x16x32_bf16 v[112:115], v[204:207], v[172:175], v[112:115]
	v_mfma_f32_16x16x32_bf16 v[108:111], v[212:215], v[142:145], v[108:111]
	v_mfma_f32_16x16x32_bf16 v[104:107], v[212:215], v[172:175], v[104:107]
	v_mfma_f32_16x16x32_bf16 v[100:103], v[216:219], v[138:141], v[100:103]
	v_mfma_f32_16x16x32_bf16 v[96:99], v[220:223], v[172:175], v[96:99]
	v_mfma_f32_16x16x32_bf16 v[88:91], v[196:199], v[180:183], v[88:91]
	v_mfma_f32_16x16x32_bf16 v[72:75], v[196:199], v[188:191], v[72:75]
	v_mfma_f32_16x16x32_bf16 v[56:59], v[204:207], v[180:183], v[56:59]
	v_mfma_f32_16x16x32_bf16 v[48:51], v[204:207], v[188:191], v[48:51]
	v_mfma_f32_16x16x32_bf16 v[44:47], v[212:215], v[180:183], v[44:47]
	v_mfma_f32_16x16x32_bf16 v[40:43], v[212:215], v[188:191], v[40:43]
	v_mfma_f32_16x16x32_bf16 v[36:39], v[220:223], v[180:183], v[36:39]
	v_mfma_f32_16x16x32_bf16 v[32:35], v[220:223], v[188:191], v[32:35]
	v_mfma_f32_16x16x32_bf16 v[224:227], v[220:223], v[142:145], v[100:103]
	s_setprio 0
	s_barrier
	s_nop 0
	ds_read_b128 v[100:103], v148 offset:16384
	ds_read_b128 v[192:195], v148 offset:17408
	ds_read_b128 v[196:199], v148 offset:18432
	ds_read_b128 v[200:203], v148 offset:19456
	ds_read_b128 v[204:207], v148 offset:20480
	ds_read_b128 v[208:211], v148 offset:21504
	ds_read_b128 v[212:215], v148 offset:22528
	ds_read_b128 v[216:219], v148 offset:23552
	s_waitcnt vmcnt(0)
	s_waitcnt lgkmcnt(0)
	s_barrier
	s_setprio 1
	s_waitcnt lgkmcnt(0)
	v_mfma_f32_16x16x32_bf16 v[28:31], v[100:103], v[138:141], v[28:31]
	v_mfma_f32_16x16x32_bf16 v[20:23], v[196:199], v[138:141], v[20:23]
	v_mfma_f32_16x16x32_bf16 v[12:15], v[204:207], v[138:141], v[12:15]
	v_mfma_f32_16x16x32_bf16 v[4:7], v[212:215], v[138:141], v[4:7]
	v_mfma_f32_16x16x32_bf16 v[0:3], v[212:215], v[168:171], v[0:3]
	v_mfma_f32_16x16x32_bf16 v[28:31], v[192:195], v[142:145], v[28:31]
	v_mfma_f32_16x16x32_bf16 v[20:23], v[200:203], v[142:145], v[20:23]
	v_mfma_f32_16x16x32_bf16 v[220:223], v[208:211], v[142:145], v[12:15]
	v_mfma_f32_16x16x32_bf16 v[138:141], v[216:219], v[142:145], v[4:7]
	v_mfma_f32_16x16x32_bf16 v[142:145], v[216:219], v[172:175], v[0:3]
	v_mfma_f32_16x16x32_bf16 v[0:3], v[100:103], v[176:179], v[52:55]
	v_mfma_f32_16x16x32_bf16 v[24:27], v[100:103], v[168:171], v[24:27]
	v_mfma_f32_16x16x32_bf16 v[16:19], v[196:199], v[168:171], v[16:19]
	v_mfma_f32_16x16x32_bf16 v[8:11], v[204:207], v[168:171], v[8:11]
	v_mfma_f32_16x16x32_bf16 v[168:171], v[192:195], v[180:183], v[0:3]
	v_mfma_f32_16x16x32_bf16 v[0:3], v[100:103], v[184:187], v[60:63]
	v_mfma_f32_16x16x32_bf16 v[24:27], v[192:195], v[172:175], v[24:27]
	v_mfma_f32_16x16x32_bf16 v[16:19], v[200:203], v[172:175], v[16:19]
	v_mfma_f32_16x16x32_bf16 v[228:231], v[208:211], v[172:175], v[8:11]
	v_mfma_f32_16x16x32_bf16 v[172:175], v[192:195], v[188:191], v[0:3]
	v_mfma_f32_16x16x32_bf16 v[0:3], v[196:199], v[176:179], v[64:67]
	v_mfma_f32_16x16x32_bf16 v[192:195], v[200:203], v[180:183], v[0:3]
	v_mfma_f32_16x16x32_bf16 v[0:3], v[196:199], v[184:187], v[68:71]
	v_mfma_f32_16x16x32_bf16 v[196:199], v[200:203], v[188:191], v[0:3]
	v_mfma_f32_16x16x32_bf16 v[0:3], v[204:207], v[176:179], v[76:79]
	v_mfma_f32_16x16x32_bf16 v[200:203], v[208:211], v[180:183], v[0:3]
	v_mfma_f32_16x16x32_bf16 v[0:3], v[204:207], v[184:187], v[80:83]
	v_mfma_f32_16x16x32_bf16 v[204:207], v[208:211], v[188:191], v[0:3]
	v_mfma_f32_16x16x32_bf16 v[0:3], v[212:215], v[176:179], v[84:87]
	v_mfma_f32_16x16x32_bf16 v[176:179], v[216:219], v[180:183], v[0:3]
	v_mfma_f32_16x16x32_bf16 v[0:3], v[212:215], v[184:187], v[92:95]
	v_mfma_f32_16x16x32_bf16 v[180:183], v[216:219], v[188:191], v[0:3]
	s_setprio 0
	s_barrier
; #define LDA(dst, b, h) _Pragma("unroll") for (int m = 0; m < 4; ++m) _Pragma("unroll") for (int k = 0; k < 2; ++k) \
;     dst[m][k] = *reinterpret_cast<const bf16x8*>((const char*)shm + aB + (((b) * 2 + (h)) * 16384 + (m * 2 + k) * 1024))
; #define LDB(dst, b, h) _Pragma("unroll") for (int n = 0; n < 2; ++n) _Pragma("unroll") for (int k = 0; k < 2; ++k) \
;     dst[n][k] = *reinterpret_cast<const bf16x8*>((const char*)shm + bB + (((b) * 2 + (h)) * 16384 + (n * 2 + k) * 1024))
; #define WAIT_L(n) asm volatile("s_waitcnt lgkmcnt(" #n ")" ::: "memory")
; #define BAR __builtin_amdgcn_s_barrier()
; #define SCHED __builtin_amdgcn_sched_barrier(0)
; template <int MODE> ...
;     ...
;       LDB(B0, 1, 0); LDB(B1, 1, 1); LDA(At, 1, 0); WAIT_L(0); BAR; MMA2(0, 0, 0, 1); BAR; SCHED;
;       LDA(At, 1, 1); WAIT_L(0); BAR; MMA2(1, 0, 1, 1); BAR; SCHED;
;     }
;     ...
;     if (wr == 0) BAR;
	ds_read_b128 v[64:67], v149 offset:32768
	ds_read_b128 v[184:187], v149 offset:33792
	ds_read_b128 v[188:191], v149 offset:34816
	ds_read_b128 v[208:211], v149 offset:35840
	ds_read_b128 v[212:215], v149 offset:49152
	ds_read_b128 v[216:219], v149 offset:50176
	ds_read_b128 v[232:235], v149 offset:51200
	ds_read_b128 v[236:239], v149 offset:52224
	ds_read_b128 v[8:11], v148 offset:32768
	ds_read_b128 v[52:55], v148 offset:33792
	ds_read_b128 v[60:63], v148 offset:34816
	ds_read_b128 v[68:71], v148 offset:35840
	ds_read_b128 v[76:79], v148 offset:36864
	ds_read_b128 v[80:83], v148 offset:37888
	ds_read_b128 v[240:243], v148 offset:38912
	ds_read_b128 v[244:247], v148 offset:39936
	s_waitcnt lgkmcnt(0)
	s_barrier
	s_setprio 1
	s_waitcnt lgkmcnt(0)
	v_mfma_f32_16x16x32_bf16 v[12:15], v[60:63], v[64:67], v[116:119]
	v_mfma_f32_16x16x32_bf16 v[0:3], v[8:11], v[64:67], v[124:127]
	v_mfma_f32_16x16x32_bf16 v[124:127], v[68:71], v[184:187], v[12:15]
	v_mfma_f32_16x16x32_bf16 v[12:15], v[60:63], v[188:191], v[112:115]
	v_mfma_f32_16x16x32_bf16 v[116:119], v[68:71], v[208:211], v[12:15]
	v_mfma_f32_16x16x32_bf16 v[12:15], v[76:79], v[64:67], v[108:111]
	v_mfma_f32_16x16x32_bf16 v[108:111], v[80:83], v[184:187], v[12:15]
	v_mfma_f32_16x16x32_bf16 v[12:15], v[76:79], v[188:191], v[104:107]
	v_mfma_f32_16x16x32_bf16 v[100:103], v[80:83], v[208:211], v[12:15]
	v_mfma_f32_16x16x32_bf16 v[12:15], v[240:243], v[64:67], v[224:227]
	v_mfma_f32_16x16x32_bf16 v[92:95], v[244:247], v[184:187], v[12:15]
	v_mfma_f32_16x16x32_bf16 v[12:15], v[240:243], v[188:191], v[96:99]
	v_mfma_f32_16x16x32_bf16 v[4:7], v[52:55], v[184:187], v[0:3]
	v_mfma_f32_16x16x32_bf16 v[0:3], v[8:11], v[188:191], v[120:123]
	v_mfma_f32_16x16x32_bf16 v[84:87], v[244:247], v[208:211], v[12:15]
	v_mfma_f32_16x16x32_bf16 v[12:15], v[8:11], v[212:215], v[88:91]
	v_mfma_f32_16x16x32_bf16 v[8:11], v[8:11], v[232:235], v[72:75]
	v_mfma_f32_16x16x32_bf16 v[0:3], v[52:55], v[208:211], v[0:3]
	v_mfma_f32_16x16x32_bf16 v[12:15], v[52:55], v[216:219], v[12:15]
	v_mfma_f32_16x16x32_bf16 v[8:11], v[52:55], v[236:239], v[8:11]
	v_mfma_f32_16x16x32_bf16 v[52:55], v[60:63], v[212:215], v[56:59]
	v_mfma_f32_16x16x32_bf16 v[48:51], v[60:63], v[232:235], v[48:51]
	v_mfma_f32_16x16x32_bf16 v[44:47], v[76:79], v[212:215], v[44:47]
	v_mfma_f32_16x16x32_bf16 v[40:43], v[76:79], v[232:235], v[40:43]
	v_mfma_f32_16x16x32_bf16 v[36:39], v[240:243], v[212:215], v[36:39]
	v_mfma_f32_16x16x32_bf16 v[32:35], v[240:243], v[232:235], v[32:35]
	v_mfma_f32_16x16x32_bf16 v[120:123], v[68:71], v[216:219], v[52:55]
	v_mfma_f32_16x16x32_bf16 v[112:115], v[68:71], v[236:239], v[48:51]
	v_mfma_f32_16x16x32_bf16 v[104:107], v[80:83], v[216:219], v[44:47]
	v_mfma_f32_16x16x32_bf16 v[96:99], v[80:83], v[236:239], v[40:43]
	v_mfma_f32_16x16x32_bf16 v[88:91], v[244:247], v[216:219], v[36:39]
	v_mfma_f32_16x16x32_bf16 v[80:83], v[244:247], v[236:239], v[32:35]
	s_setprio 0
	s_barrier
	s_nop 0
	ds_read_b128 v[32:35], v148 offset:49152
	ds_read_b128 v[40:43], v148 offset:50176
	ds_read_b128 v[48:51], v148 offset:51200
	ds_read_b128 v[224:227], v148 offset:52224
	ds_read_b128 v[240:243], v148 offset:53248
	ds_read_b128 v[244:247], v148 offset:54272
	ds_read_b128 v[248:251], v148 offset:55296
	ds_read_b128 v[130:133], v148 offset:56320
	s_waitcnt lgkmcnt(0)
	s_barrier
	s_setprio 1
	s_waitcnt lgkmcnt(0)
	v_mfma_f32_16x16x32_bf16 v[24:27], v[32:35], v[188:191], v[24:27]
	v_mfma_f32_16x16x32_bf16 v[16:19], v[48:51], v[188:191], v[16:19]
	v_mfma_f32_16x16x32_bf16 v[68:71], v[40:43], v[208:211], v[24:27]
	v_mfma_f32_16x16x32_bf16 v[52:55], v[224:227], v[208:211], v[16:19]
	v_mfma_f32_16x16x32_bf16 v[16:19], v[240:243], v[64:67], v[220:223]
	v_mfma_f32_16x16x32_bf16 v[24:27], v[32:35], v[212:215], v[168:171]
	v_mfma_f32_16x16x32_bf16 v[44:47], v[244:247], v[184:187], v[16:19]
	v_mfma_f32_16x16x32_bf16 v[16:19], v[240:243], v[188:191], v[228:231]
	v_mfma_f32_16x16x32_bf16 v[72:75], v[40:43], v[216:219], v[24:27]
	v_mfma_f32_16x16x32_bf16 v[24:27], v[32:35], v[232:235], v[172:175]
	v_mfma_f32_16x16x32_bf16 v[28:31], v[32:35], v[64:67], v[28:31]
	v_mfma_f32_16x16x32_bf16 v[20:23], v[48:51], v[64:67], v[20:23]
	v_mfma_f32_16x16x32_bf16 v[36:39], v[244:247], v[208:211], v[16:19]
	v_mfma_f32_16x16x32_bf16 v[16:19], v[248:251], v[64:67], v[138:141]
	v_mfma_f32_16x16x32_bf16 v[64:67], v[40:43], v[236:239], v[24:27]
	v_mfma_f32_16x16x32_bf16 v[24:27], v[48:51], v[212:215], v[192:195]
	v_mfma_f32_16x16x32_bf16 v[56:59], v[224:227], v[216:219], v[24:27]
	v_mfma_f32_16x16x32_bf16 v[24:27], v[48:51], v[232:235], v[196:199]
	v_mfma_f32_16x16x32_bf16 v[48:51], v[224:227], v[236:239], v[24:27]
	v_mfma_f32_16x16x32_bf16 v[24:27], v[240:243], v[212:215], v[200:203]
	v_mfma_f32_16x16x32_bf16 v[76:79], v[40:43], v[184:187], v[28:31]
	v_mfma_f32_16x16x32_bf16 v[40:43], v[244:247], v[216:219], v[24:27]
	v_mfma_f32_16x16x32_bf16 v[24:27], v[240:243], v[232:235], v[204:207]
	v_mfma_f32_16x16x32_bf16 v[32:35], v[244:247], v[236:239], v[24:27]
	v_mfma_f32_16x16x32_bf16 v[24:27], v[248:251], v[212:215], v[176:179]
	v_mfma_f32_16x16x32_bf16 v[60:63], v[224:227], v[184:187], v[20:23]
	v_mfma_f32_16x16x32_bf16 v[20:23], v[130:133], v[184:187], v[16:19]
	v_mfma_f32_16x16x32_bf16 v[16:19], v[248:251], v[188:191], v[142:145]
	v_mfma_f32_16x16x32_bf16 v[28:31], v[130:133], v[216:219], v[24:27]
	v_mfma_f32_16x16x32_bf16 v[24:27], v[248:251], v[232:235], v[180:183]
	v_mfma_f32_16x16x32_bf16 v[16:19], v[130:133], v[208:211], v[16:19]
	v_mfma_f32_16x16x32_bf16 v[24:27], v[130:133], v[236:239], v[24:27]
	s_setprio 0
	s_barrier
	s_and_saveexec_b64 s[8:9], s[6:7]
	s_cbranch_execz .LBB0_594
	s_barrier

; #define STAGE(Pp, BASE, br, kt) do { const u16* _g = (BASE) + ((long)(br) * K + (long)(kt) * BK); \
;     __builtin_amdgcn_global_load_lds((const unsigned*)(_g + voff0), (unsigned*)((char*)(Pp) + tb16), 16, 0, 0); \
;     __builtin_amdgcn_global_load_lds((const unsigned*)(_g + voff1), (unsigned*)((char*)(Pp) + tb16 + 8192), 16, 0, 0); } while (0)
; #define LDA(dst, b, h) _Pragma("unroll") for (int m = 0; m < 4; ++m) _Pragma("unroll") for (int k = 0; k < 2; ++k) \
;     dst[m][k] = *reinterpret_cast<const bf16x8*>((const char*)shm + aB + (((b) * 2 + (h)) * 16384 + (m * 2 + k) * 1024))
; #define LDB(dst, b, h) _Pragma("unroll") for (int n = 0; n < 2; ++n) _Pragma("unroll") for (int k = 0; k < 2; ++k) \
;     dst[n][k] = *reinterpret_cast<const bf16x8*>((const char*)shm + bB + (((b) * 2 + (h)) * 16384 + (n * 2 + k) * 1024))
; #define WAIT_V(n) asm volatile("s_waitcnt vmcnt(" #n ")" ::: "memory")
; #define WAIT_L(n) asm volatile("s_waitcnt lgkmcnt(" #n ")" ::: "memory")
; #define BAR __builtin_amdgcn_s_barrier()
; #define SCHED __builtin_amdgcn_sched_barrier(0)
; template <int MODE> ...
;     ...
;       LDB(B0, 0, 0); LDB(B1, 0, 1); LDA(At, 0, 0); STAGE(SA(1, 1), A, brow + HALF, t + 1);
;       WAIT_L(0); BAR; MMA2(0, 0, 0, 1); BAR; SCHED;
;       LDA(At, 0, 1); STAGE(SB(0, 0), Bt, bcol, t + 2); STAGE(SB(0, 1), Bt, bcol + HALF, t + 2); STAGE(SA(0, 0), A, brow, t + 2);
;       WAIT_V(6); WAIT_L(0); BAR; MMA2(1, 0, 1, 1); BAR; SCHED;
.LBB0_848:
	s_add_u32 m0, s32, 0xc000
	ds_read_b128 v[170:173], v151
	ds_read_b128 v[174:177], v151 offset:1024
	ds_read_b128 v[178:181], v151 offset:2048
	ds_read_b128 v[182:185], v151 offset:3072
	ds_read_b128 v[186:189], v151 offset:16384
	ds_read_b128 v[190:193], v151 offset:17408
	ds_read_b128 v[194:197], v151 offset:18432
	ds_read_b128 v[198:201], v151 offset:19456
	ds_read_b128 v[202:205], v150
	ds_read_b128 v[206:209], v150 offset:1024
	ds_read_b128 v[210:213], v150 offset:2048
	ds_read_b128 v[214:217], v150 offset:3072
	ds_read_b128 v[218:221], v150 offset:4096
	ds_read_b128 v[222:225], v150 offset:5120
	ds_read_b128 v[226:229], v150 offset:6144
	ds_read_b128 v[230:233], v150 offset:7168
	s_add_u32 s88, s62, s22
	s_addc_u32 s89, s63, s23
	global_load_lds_dwordx4 v146, s[88:89]
	s_add_u32 m0, s32, 0xe000
	s_nop 0
	global_load_lds_dwordx4 v148, s[88:89]
	s_waitcnt lgkmcnt(0)
	s_barrier
	s_setprio 1
	s_waitcnt lgkmcnt(0)
	v_mfma_f32_16x16x32_bf16 v[124:127], v[202:205], v[170:173], v[124:127]
	v_mfma_f32_16x16x32_bf16 v[120:123], v[202:205], v[178:181], v[120:123]
	v_mfma_f32_16x16x32_bf16 v[116:119], v[210:213], v[170:173], v[116:119]
	v_mfma_f32_16x16x32_bf16 v[112:115], v[210:213], v[178:181], v[112:115]
	v_mfma_f32_16x16x32_bf16 v[108:111], v[218:221], v[170:173], v[108:111]
	v_mfma_f32_16x16x32_bf16 v[104:107], v[218:221], v[178:181], v[104:107]
	v_mfma_f32_16x16x32_bf16 v[100:103], v[226:229], v[170:173], v[100:103]
	v_mfma_f32_16x16x32_bf16 v[96:99], v[226:229], v[178:181], v[96:99]
	v_mfma_f32_16x16x32_bf16 v[92:95], v[202:205], v[186:189], v[92:95]
	v_mfma_f32_16x16x32_bf16 v[88:91], v[202:205], v[194:197], v[88:91]
	v_mfma_f32_16x16x32_bf16 v[84:87], v[210:213], v[186:189], v[84:87]
	v_mfma_f32_16x16x32_bf16 v[80:83], v[210:213], v[194:197], v[80:83]
	v_mfma_f32_16x16x32_bf16 v[76:79], v[218:221], v[186:189], v[76:79]
	v_mfma_f32_16x16x32_bf16 v[72:75], v[218:221], v[194:197], v[72:75]
	v_mfma_f32_16x16x32_bf16 v[68:71], v[226:229], v[186:189], v[68:71]
	v_mfma_f32_16x16x32_bf16 v[64:67], v[226:229], v[194:197], v[64:67]
	v_mfma_f32_16x16x32_bf16 v[124:127], v[206:209], v[174:177], v[124:127]
	v_mfma_f32_16x16x32_bf16 v[120:123], v[206:209], v[182:185], v[120:123]
	v_mfma_f32_16x16x32_bf16 v[116:119], v[214:217], v[174:177], v[116:119]
	v_mfma_f32_16x16x32_bf16 v[112:115], v[214:217], v[182:185], v[112:115]
	v_mfma_f32_16x16x32_bf16 v[108:111], v[222:225], v[174:177], v[108:111]
	v_mfma_f32_16x16x32_bf16 v[104:107], v[222:225], v[182:185], v[104:107]
	v_mfma_f32_16x16x32_bf16 v[100:103], v[230:233], v[174:177], v[100:103]
	v_mfma_f32_16x16x32_bf16 v[96:99], v[230:233], v[182:185], v[96:99]
	v_mfma_f32_16x16x32_bf16 v[92:95], v[206:209], v[190:193], v[92:95]
	v_mfma_f32_16x16x32_bf16 v[88:91], v[206:209], v[198:201], v[88:91]
	v_mfma_f32_16x16x32_bf16 v[84:87], v[214:217], v[190:193], v[84:87]
	v_mfma_f32_16x16x32_bf16 v[80:83], v[214:217], v[198:201], v[80:83]
	v_mfma_f32_16x16x32_bf16 v[76:79], v[222:225], v[190:193], v[76:79]
	v_mfma_f32_16x16x32_bf16 v[72:75], v[222:225], v[198:201], v[72:75]
	v_mfma_f32_16x16x32_bf16 v[68:71], v[230:233], v[190:193], v[68:71]
	v_mfma_f32_16x16x32_bf16 v[64:67], v[230:233], v[198:201], v[64:67]
	s_setprio 0
	s_barrier
	s_add_u32 m0, s32, 0x10000
	ds_read_b128 v[202:205], v150 offset:16384
	ds_read_b128 v[206:209], v150 offset:17408
	ds_read_b128 v[210:213], v150 offset:18432
	ds_read_b128 v[214:217], v150 offset:19456
	ds_read_b128 v[218:221], v150 offset:20480
	ds_read_b128 v[222:225], v150 offset:21504
	ds_read_b128 v[226:229], v150 offset:22528
	ds_read_b128 v[230:233], v150 offset:23552
	s_add_u32 s88, s62, s24
	s_addc_u32 s89, s63, s25
	global_load_lds_dwordx4 v138, s[88:89]
	s_add_u32 m0, s32, 0x12000
	s_add_u32 s90, s62, s26
	s_addc_u32 s91, s63, s27
	global_load_lds_dwordx4 v140, s[88:89]
	s_add_u32 m0, s32, 0x14000
	s_add_u32 s92, s62, s28
	s_addc_u32 s93, s63, s29
	global_load_lds_dwordx4 v142, s[90:91]
	s_add_u32 m0, s32, 0x16000
	s_nop 0
	global_load_lds_dwordx4 v144, s[90:91]
	s_mov_b32 m0, s32
	s_nop 0
	global_load_lds_dwordx4 v146, s[92:93]
	s_add_u32 m0, s32, 0x2000
	s_nop 0
	global_load_lds_dwordx4 v148, s[92:93]
	s_waitcnt vmcnt(6)
	s_waitcnt lgkmcnt(0)
	s_barrier
	s_setprio 1
	s_waitcnt lgkmcnt(0)
	v_mfma_f32_16x16x32_bf16 v[60:63], v[202:205], v[170:173], v[60:63]
	v_mfma_f32_16x16x32_bf16 v[56:59], v[202:205], v[178:181], v[56:59]
	v_mfma_f32_16x16x32_bf16 v[52:55], v[210:213], v[170:173], v[52:55]
	v_mfma_f32_16x16x32_bf16 v[48:51], v[210:213], v[178:181], v[48:51]
	v_mfma_f32_16x16x32_bf16 v[44:47], v[218:221], v[170:173], v[44:47]
	v_mfma_f32_16x16x32_bf16 v[40:43], v[218:221], v[178:181], v[40:43]
	v_mfma_f32_16x16x32_bf16 v[36:39], v[226:229], v[170:173], v[36:39]
	v_mfma_f32_16x16x32_bf16 v[32:35], v[226:229], v[178:181], v[32:35]
	v_mfma_f32_16x16x32_bf16 v[28:31], v[202:205], v[186:189], v[28:31]
	v_mfma_f32_16x16x32_bf16 v[24:27], v[202:205], v[194:197], v[24:27]
	v_mfma_f32_16x16x32_bf16 v[20:23], v[210:213], v[186:189], v[20:23]
	v_mfma_f32_16x16x32_bf16 v[16:19], v[210:213], v[194:197], v[16:19]
	v_mfma_f32_16x16x32_bf16 v[12:15], v[218:221], v[186:189], v[12:15]
	v_mfma_f32_16x16x32_bf16 v[8:11], v[218:221], v[194:197], v[8:11]
	v_mfma_f32_16x16x32_bf16 v[4:7], v[226:229], v[186:189], v[4:7]
	v_mfma_f32_16x16x32_bf16 v[0:3], v[226:229], v[194:197], v[0:3]
	v_mfma_f32_16x16x32_bf16 v[60:63], v[206:209], v[174:177], v[60:63]
	v_mfma_f32_16x16x32_bf16 v[56:59], v[206:209], v[182:185], v[56:59]
	v_mfma_f32_16x16x32_bf16 v[52:55], v[214:217], v[174:177], v[52:55]
	v_mfma_f32_16x16x32_bf16 v[48:51], v[214:217], v[182:185], v[48:51]
	v_mfma_f32_16x16x32_bf16 v[44:47], v[222:225], v[174:177], v[44:47]
	v_mfma_f32_16x16x32_bf16 v[40:43], v[222:225], v[182:185], v[40:43]
	v_mfma_f32_16x16x32_bf16 v[36:39], v[230:233], v[174:177], v[36:39]
	v_mfma_f32_16x16x32_bf16 v[32:35], v[230:233], v[182:185], v[32:35]
	v_mfma_f32_16x16x32_bf16 v[28:31], v[206:209], v[190:193], v[28:31]
	v_mfma_f32_16x16x32_bf16 v[24:27], v[206:209], v[198:201], v[24:27]
	v_mfma_f32_16x16x32_bf16 v[20:23], v[214:217], v[190:193], v[20:23]
	v_mfma_f32_16x16x32_bf16 v[16:19], v[214:217], v[198:201], v[16:19]
	v_mfma_f32_16x16x32_bf16 v[12:15], v[222:225], v[190:193], v[12:15]
	v_mfma_f32_16x16x32_bf16 v[8:11], v[222:225], v[198:201], v[8:11]
	v_mfma_f32_16x16x32_bf16 v[4:7], v[230:233], v[190:193], v[4:7]
	v_mfma_f32_16x16x32_bf16 v[0:3], v[230:233], v[198:201], v[0:3]
	s_setprio 0
	s_barrier
; #define STAGE(Pp, BASE, br, kt) do { const u16* _g = (BASE) + ((long)(br) * K + (long)(kt) * BK); \
;     __builtin_amdgcn_global_load_lds((const unsigned*)(_g + voff0), (unsigned*)((char*)(Pp) + tb16), 16, 0, 0); \
;     __builtin_amdgcn_global_load_lds((const unsigned*)(_g + voff1), (unsigned*)((char*)(Pp) + tb16 + 8192), 16, 0, 0); } while (0)
; #define LDA(dst, b, h) _Pragma("unroll") for (int m = 0; m < 4; ++m) _Pragma("unroll") for (int k = 0; k < 2; ++k) \
;     dst[m][k] = *reinterpret_cast<const bf16x8*>((const char*)shm + aB + (((b) * 2 + (h)) * 16384 + (m * 2 + k) * 1024))
; #define LDB(dst, b, h) _Pragma("unroll") for (int n = 0; n < 2; ++n) _Pragma("unroll") for (int k = 0; k < 2; ++k) \
;     dst[n][k] = *reinterpret_cast<const bf16x8*>((const char*)shm + bB + (((b) * 2 + (h)) * 16384 + (n * 2 + k) * 1024))
; #define WAIT_V(n) asm volatile("s_waitcnt vmcnt(" #n ")" ::: "memory")
; #define WAIT_L(n) asm volatile("s_waitcnt lgkmcnt(" #n ")" ::: "memory")
; #define BAR __builtin_amdgcn_s_barrier()
; #define SCHED __builtin_amdgcn_sched_barrier(0)
; template <int MODE> ...
;     ...
;       LDB(B0, 1, 0); LDB(B1, 1, 1); LDA(At, 1, 0); STAGE(SA(0, 1), A, brow + HALF, t + 2);
;       WAIT_L(0); BAR; MMA2(0, 0, 0, 1); BAR; SCHED;
;       LDA(At, 1, 1); STAGE(SB(1, 0), Bt, bcol, t + 3); STAGE(SB(1, 1), Bt, bcol + HALF, t + 3); STAGE(SA(1, 0), A, brow, t + 3);
;       WAIT_V(6); WAIT_L(0); BAR; MMA2(1, 0, 1, 1); BAR; SCHED;
	s_add_u32 m0, s32, 0x4000
	ds_read_b128 v[170:173], v151 offset:32768
	ds_read_b128 v[174:177], v151 offset:33792
	ds_read_b128 v[178:181], v151 offset:34816
	ds_read_b128 v[182:185], v151 offset:35840
	ds_read_b128 v[186:189], v151 offset:49152
	ds_read_b128 v[190:193], v151 offset:50176
	ds_read_b128 v[194:197], v151 offset:51200
	ds_read_b128 v[198:201], v151 offset:52224
	ds_read_b128 v[202:205], v150 offset:32768
	ds_read_b128 v[206:209], v150 offset:33792
	ds_read_b128 v[210:213], v150 offset:34816
	ds_read_b128 v[214:217], v150 offset:35840
	ds_read_b128 v[218:221], v150 offset:36864
	ds_read_b128 v[222:225], v150 offset:37888
	ds_read_b128 v[226:229], v150 offset:38912
	ds_read_b128 v[230:233], v150 offset:39936
	s_add_u32 s88, s62, s36
	s_addc_u32 s89, s63, s37
	global_load_lds_dwordx4 v146, s[88:89]
	s_add_u32 m0, s32, 0x6000
	s_nop 0
	global_load_lds_dwordx4 v148, s[88:89]
	s_waitcnt lgkmcnt(0)
	s_barrier
	s_setprio 1
	s_waitcnt lgkmcnt(0)
	v_mfma_f32_16x16x32_bf16 v[124:127], v[202:205], v[170:173], v[124:127]
	v_mfma_f32_16x16x32_bf16 v[120:123], v[202:205], v[178:181], v[120:123]
	v_mfma_f32_16x16x32_bf16 v[116:119], v[210:213], v[170:173], v[116:119]
	v_mfma_f32_16x16x32_bf16 v[112:115], v[210:213], v[178:181], v[112:115]
	v_mfma_f32_16x16x32_bf16 v[108:111], v[218:221], v[170:173], v[108:111]
	v_mfma_f32_16x16x32_bf16 v[104:107], v[218:221], v[178:181], v[104:107]
	v_mfma_f32_16x16x32_bf16 v[100:103], v[226:229], v[170:173], v[100:103]
	v_mfma_f32_16x16x32_bf16 v[96:99], v[226:229], v[178:181], v[96:99]
	v_mfma_f32_16x16x32_bf16 v[92:95], v[202:205], v[186:189], v[92:95]
	v_mfma_f32_16x16x32_bf16 v[88:91], v[202:205], v[194:197], v[88:91]
	v_mfma_f32_16x16x32_bf16 v[84:87], v[210:213], v[186:189], v[84:87]
	v_mfma_f32_16x16x32_bf16 v[80:83], v[210:213], v[194:197], v[80:83]
	v_mfma_f32_16x16x32_bf16 v[76:79], v[218:221], v[186:189], v[76:79]
	v_mfma_f32_16x16x32_bf16 v[72:75], v[218:221], v[194:197], v[72:75]
	v_mfma_f32_16x16x32_bf16 v[68:71], v[226:229], v[186:189], v[68:71]
	v_mfma_f32_16x16x32_bf16 v[64:67], v[226:229], v[194:197], v[64:67]
	v_mfma_f32_16x16x32_bf16 v[124:127], v[206:209], v[174:177], v[124:127]
	v_mfma_f32_16x16x32_bf16 v[120:123], v[206:209], v[182:185], v[120:123]
	v_mfma_f32_16x16x32_bf16 v[116:119], v[214:217], v[174:177], v[116:119]
	v_mfma_f32_16x16x32_bf16 v[112:115], v[214:217], v[182:185], v[112:115]
	v_mfma_f32_16x16x32_bf16 v[108:111], v[222:225], v[174:177], v[108:111]
	v_mfma_f32_16x16x32_bf16 v[104:107], v[222:225], v[182:185], v[104:107]
	v_mfma_f32_16x16x32_bf16 v[100:103], v[230:233], v[174:177], v[100:103]
	v_mfma_f32_16x16x32_bf16 v[96:99], v[230:233], v[182:185], v[96:99]
	v_mfma_f32_16x16x32_bf16 v[92:95], v[206:209], v[190:193], v[92:95]
	v_mfma_f32_16x16x32_bf16 v[88:91], v[206:209], v[198:201], v[88:91]
	v_mfma_f32_16x16x32_bf16 v[84:87], v[214:217], v[190:193], v[84:87]
	v_mfma_f32_16x16x32_bf16 v[80:83], v[214:217], v[198:201], v[80:83]
	v_mfma_f32_16x16x32_bf16 v[76:79], v[222:225], v[190:193], v[76:79]
	v_mfma_f32_16x16x32_bf16 v[72:75], v[222:225], v[198:201], v[72:75]
	v_mfma_f32_16x16x32_bf16 v[68:71], v[230:233], v[190:193], v[68:71]
	v_mfma_f32_16x16x32_bf16 v[64:67], v[230:233], v[198:201], v[64:67]
	s_setprio 0
	s_barrier
	s_add_u32 m0, s32, 0x18000
	ds_read_b128 v[202:205], v150 offset:49152
	ds_read_b128 v[206:209], v150 offset:50176
	ds_read_b128 v[210:213], v150 offset:51200
	ds_read_b128 v[214:217], v150 offset:52224
	ds_read_b128 v[218:221], v150 offset:53248
	ds_read_b128 v[222:225], v150 offset:54272
	ds_read_b128 v[226:229], v150 offset:55296
	ds_read_b128 v[230:233], v150 offset:56320
	s_add_u32 s88, s62, s38
	s_addc_u32 s89, s63, s39
	global_load_lds_dwordx4 v138, s[88:89]
	s_add_u32 m0, s32, 0x1a000
	s_add_u32 s90, s62, s40
	s_addc_u32 s91, s63, s41
	global_load_lds_dwordx4 v140, s[88:89]
	s_add_u32 m0, s32, 0x1c000
	s_add_u32 s92, s62, s42
	s_addc_u32 s93, s63, s43
	global_load_lds_dwordx4 v142, s[90:91]
	s_add_u32 m0, s32, 0x1e000
	s_nop 0
	global_load_lds_dwordx4 v144, s[90:91]
	s_add_u32 m0, s32, 0x8000
	s_nop 0
	global_load_lds_dwordx4 v146, s[92:93]
	s_add_u32 m0, s32, 0xa000
	s_nop 0
	global_load_lds_dwordx4 v148, s[92:93]
	s_waitcnt vmcnt(6)
	s_waitcnt lgkmcnt(0)
	s_barrier
	s_setprio 1
	s_waitcnt lgkmcnt(0)
	v_mfma_f32_16x16x32_bf16 v[60:63], v[202:205], v[170:173], v[60:63]
	v_mfma_f32_16x16x32_bf16 v[56:59], v[202:205], v[178:181], v[56:59]
	v_mfma_f32_16x16x32_bf16 v[52:55], v[210:213], v[170:173], v[52:55]
	v_mfma_f32_16x16x32_bf16 v[48:51], v[210:213], v[178:181], v[48:51]
	v_mfma_f32_16x16x32_bf16 v[44:47], v[218:221], v[170:173], v[44:47]
	v_mfma_f32_16x16x32_bf16 v[40:43], v[218:221], v[178:181], v[40:43]
	v_mfma_f32_16x16x32_bf16 v[36:39], v[226:229], v[170:173], v[36:39]
	v_mfma_f32_16x16x32_bf16 v[32:35], v[226:229], v[178:181], v[32:35]
	v_mfma_f32_16x16x32_bf16 v[28:31], v[202:205], v[186:189], v[28:31]
	v_mfma_f32_16x16x32_bf16 v[24:27], v[202:205], v[194:197], v[24:27]
	v_mfma_f32_16x16x32_bf16 v[20:23], v[210:213], v[186:189], v[20:23]
	v_mfma_f32_16x16x32_bf16 v[16:19], v[210:213], v[194:197], v[16:19]
	v_mfma_f32_16x16x32_bf16 v[12:15], v[218:221], v[186:189], v[12:15]
	v_mfma_f32_16x16x32_bf16 v[8:11], v[218:221], v[194:197], v[8:11]
	v_mfma_f32_16x16x32_bf16 v[4:7], v[226:229], v[186:189], v[4:7]
	v_mfma_f32_16x16x32_bf16 v[0:3], v[226:229], v[194:197], v[0:3]
	v_mfma_f32_16x16x32_bf16 v[60:63], v[206:209], v[174:177], v[60:63]
	v_mfma_f32_16x16x32_bf16 v[56:59], v[206:209], v[182:185], v[56:59]
	v_mfma_f32_16x16x32_bf16 v[52:55], v[214:217], v[174:177], v[52:55]
	v_mfma_f32_16x16x32_bf16 v[48:51], v[214:217], v[182:185], v[48:51]
	v_mfma_f32_16x16x32_bf16 v[44:47], v[222:225], v[174:177], v[44:47]
	v_mfma_f32_16x16x32_bf16 v[40:43], v[222:225], v[182:185], v[40:43]
	v_mfma_f32_16x16x32_bf16 v[36:39], v[230:233], v[174:177], v[36:39]
	v_mfma_f32_16x16x32_bf16 v[32:35], v[230:233], v[182:185], v[32:35]
	v_mfma_f32_16x16x32_bf16 v[28:31], v[206:209], v[190:193], v[28:31]
	v_mfma_f32_16x16x32_bf16 v[24:27], v[206:209], v[198:201], v[24:27]
	v_mfma_f32_16x16x32_bf16 v[20:23], v[214:217], v[190:193], v[20:23]
	v_mfma_f32_16x16x32_bf16 v[16:19], v[214:217], v[198:201], v[16:19]
	v_mfma_f32_16x16x32_bf16 v[12:15], v[222:225], v[190:193], v[12:15]
	v_mfma_f32_16x16x32_bf16 v[8:11], v[222:225], v[198:201], v[8:11]
	v_mfma_f32_16x16x32_bf16 v[4:7], v[230:233], v[190:193], v[4:7]
	v_mfma_f32_16x16x32_bf16 v[0:3], v[230:233], v[198:201], v[0:3]
	s_setprio 0
	s_barrier
; #define STAGE(Pp, BASE, br, kt) do { const u16* _g = (BASE) + ((long)(br) * K + (long)(kt) * BK); \
;     __builtin_amdgcn_global_load_lds((const unsigned*)(_g + voff0), (unsigned*)((char*)(Pp) + tb16), 16, 0, 0); \
;     __builtin_amdgcn_global_load_lds((const unsigned*)(_g + voff1), (unsigned*)((char*)(Pp) + tb16 + 8192), 16, 0, 0); } while (0)
; #define LDA(dst, b, h) _Pragma("unroll") for (int m = 0; m < 4; ++m) _Pragma("unroll") for (int k = 0; k < 2; ++k) \
;     dst[m][k] = *reinterpret_cast<const bf16x8*>((const char*)shm + aB + (((b) * 2 + (h)) * 16384 + (m * 2 + k) * 1024))
; #define LDB(dst, b, h) _Pragma("unroll") for (int n = 0; n < 2; ++n) _Pragma("unroll") for (int k = 0; k < 2; ++k) \
;     dst[n][k] = *reinterpret_cast<const bf16x8*>((const char*)shm + bB + (((b) * 2 + (h)) * 16384 + (n * 2 + k) * 1024))
; #define WAIT_V(n) asm volatile("s_waitcnt vmcnt(" #n ")" ::: "memory")
; #define WAIT_L(n) asm volatile("s_waitcnt lgkmcnt(" #n ")" ::: "memory")
; #define BAR __builtin_amdgcn_s_barrier()
; #define SCHED __builtin_amdgcn_sched_barrier(0)
; template <int MODE> ...
;     ...
;     for (int t = 0; t < nt - 2; t += 2) {
;       LDB(B0, 0, 0); LDB(B1, 0, 1); LDA(At, 0, 0); STAGE(SA(1, 1), A, brow + HALF, t + 1);
;       WAIT_L(0); BAR; MMA2(0, 0, 0, 1); BAR; SCHED;
;       LDA(At, 0, 1); STAGE(SB(0, 0), Bt, bcol, t + 2); STAGE(SB(0, 1), Bt, bcol + HALF, t + 2); STAGE(SA(0, 0), A, brow, t + 2);
;       WAIT_V(6); WAIT_L(0); BAR; MMA2(1, 0, 1, 1); BAR; SCHED;
;       LDB(B0, 1, 0); LDB(B1, 1, 1); LDA(At, 1, 0); STAGE(SA(0, 1), A, brow + HALF, t + 2);
;       WAIT_L(0); BAR; MMA2(0, 0, 0, 1); BAR; SCHED;
;       LDA(At, 1, 1); STAGE(SB(1, 0), Bt, bcol, t + 3); STAGE(SB(1, 1), Bt, bcol + HALF, t + 3); STAGE(SA(1, 0), A, brow, t + 3);
;       WAIT_V(6); WAIT_L(0); BAR; MMA2(1, 0, 1, 1); BAR; SCHED;
;     }
;     {
;       LDB(B0, 0, 0); LDB(B1, 0, 1); LDA(At, 0, 0); STAGE(SA(1, 1), A, brow + HALF, nt - 1);
;       WAIT_L(0); BAR; MMA2(0, 0, 0, 1); BAR; SCHED;
;       LDA(At, 0, 1); WAIT_V(0); WAIT_L(0); BAR; MMA2(1, 0, 1, 1); BAR; SCHED;
	s_add_i32 s45, s45, 2
	s_add_u32 s62, s62, 0x100
	s_addc_u32 s63, s63, 0
	s_cmpk_lt_u32 s45, 0xa8
	s_cbranch_scc1 .LBB0_848
	s_add_u32 s60, s60, 0x5580
	v_readfirstlane_b32 s45, v167
	s_addc_u32 s61, s61, 0
	s_mov_b32 m0, s45
	v_readfirstlane_b32 s45, v168
	ds_read_b128 v[138:141], v151
	ds_read_b128 v[142:145], v151 offset:1024
	ds_read_b128 v[146:149], v151 offset:2048
	ds_read_b128 v[170:173], v151 offset:3072
	ds_read_b128 v[174:177], v151 offset:16384
	ds_read_b128 v[178:181], v151 offset:17408
	ds_read_b128 v[182:185], v151 offset:18432
	ds_read_b128 v[186:189], v151 offset:19456
	ds_read_b128 v[190:193], v150
	ds_read_b128 v[194:197], v150 offset:1024
	ds_read_b128 v[198:201], v150 offset:2048
	ds_read_b128 v[202:205], v150 offset:3072
	ds_read_b128 v[206:209], v150 offset:4096
	ds_read_b128 v[210:213], v150 offset:5120
	ds_read_b128 v[214:217], v150 offset:6144
	ds_read_b128 v[218:221], v150 offset:7168
	global_load_lds_dwordx4 v134, s[60:61]
	s_mov_b32 m0, s45
	s_nop 0
	global_load_lds_dwordx4 v136, s[60:61]
	s_waitcnt lgkmcnt(0)
	s_barrier
	s_setprio 1
	s_waitcnt lgkmcnt(0)
	v_mfma_f32_16x16x32_bf16 v[124:127], v[190:193], v[138:141], v[124:127]
	v_mfma_f32_16x16x32_bf16 v[116:119], v[198:201], v[138:141], v[116:119]
	v_mfma_f32_16x16x32_bf16 v[108:111], v[206:209], v[138:141], v[108:111]
	v_mfma_f32_16x16x32_bf16 v[100:103], v[214:217], v[138:141], v[100:103]
	v_mfma_f32_16x16x32_bf16 v[96:99], v[214:217], v[146:149], v[96:99]
	v_mfma_f32_16x16x32_bf16 v[92:95], v[190:193], v[174:177], v[92:95]
	v_mfma_f32_16x16x32_bf16 v[88:91], v[190:193], v[182:185], v[88:91]
	v_mfma_f32_16x16x32_bf16 v[80:83], v[198:201], v[182:185], v[80:83]
	v_mfma_f32_16x16x32_bf16 v[76:79], v[206:209], v[174:177], v[76:79]
	v_mfma_f32_16x16x32_bf16 v[124:127], v[194:197], v[142:145], v[124:127]
	v_mfma_f32_16x16x32_bf16 v[120:123], v[190:193], v[146:149], v[120:123]
	v_mfma_f32_16x16x32_bf16 v[116:119], v[202:205], v[142:145], v[116:119]
	v_mfma_f32_16x16x32_bf16 v[112:115], v[198:201], v[146:149], v[112:115]
	v_mfma_f32_16x16x32_bf16 v[108:111], v[210:213], v[142:145], v[108:111]
	v_mfma_f32_16x16x32_bf16 v[104:107], v[206:209], v[146:149], v[104:107]
	v_mfma_f32_16x16x32_bf16 v[100:103], v[218:221], v[142:145], v[100:103]
	v_mfma_f32_16x16x32_bf16 v[96:99], v[218:221], v[170:173], v[96:99]
	v_mfma_f32_16x16x32_bf16 v[92:95], v[194:197], v[178:181], v[92:95]
	v_mfma_f32_16x16x32_bf16 v[88:91], v[194:197], v[186:189], v[88:91]
	v_mfma_f32_16x16x32_bf16 v[84:87], v[198:201], v[174:177], v[84:87]
	v_mfma_f32_16x16x32_bf16 v[80:83], v[202:205], v[186:189], v[80:83]
	v_mfma_f32_16x16x32_bf16 v[76:79], v[210:213], v[178:181], v[76:79]
	v_mfma_f32_16x16x32_bf16 v[72:75], v[206:209], v[182:185], v[72:75]
	v_mfma_f32_16x16x32_bf16 v[68:71], v[214:217], v[174:177], v[68:71]
	v_mfma_f32_16x16x32_bf16 v[64:67], v[214:217], v[182:185], v[64:67]
	v_mfma_f32_16x16x32_bf16 v[222:225], v[194:197], v[170:173], v[120:123]
	v_mfma_f32_16x16x32_bf16 v[226:229], v[202:205], v[170:173], v[112:115]
	v_mfma_f32_16x16x32_bf16 v[230:233], v[210:213], v[170:173], v[104:107]
	v_mfma_f32_16x16x32_bf16 v[190:193], v[202:205], v[178:181], v[84:87]
	v_mfma_f32_16x16x32_bf16 v[194:197], v[210:213], v[186:189], v[72:75]
	v_mfma_f32_16x16x32_bf16 v[198:201], v[218:221], v[178:181], v[68:71]
	v_mfma_f32_16x16x32_bf16 v[202:205], v[218:221], v[186:189], v[64:67]
	s_setprio 0
	s_barrier
	s_nop 0
	ds_read_b128 v[64:67], v150 offset:16384
	ds_read_b128 v[68:71], v150 offset:17408
	ds_read_b128 v[72:75], v150 offset:18432
	ds_read_b128 v[84:87], v150 offset:19456
	ds_read_b128 v[104:107], v150 offset:20480
	ds_read_b128 v[112:115], v150 offset:21504
	ds_read_b128 v[120:123], v150 offset:22528
	ds_read_b128 v[206:209], v150 offset:23552
	s_waitcnt vmcnt(0)
	s_waitcnt lgkmcnt(0)
	s_barrier
	s_setprio 1
	s_waitcnt lgkmcnt(0)
	v_mfma_f32_16x16x32_bf16 v[60:63], v[64:67], v[138:141], v[60:63]
	v_mfma_f32_16x16x32_bf16 v[56:59], v[64:67], v[146:149], v[56:59]
	v_mfma_f32_16x16x32_bf16 v[52:55], v[72:75], v[138:141], v[52:55]
	v_mfma_f32_16x16x32_bf16 v[48:51], v[72:75], v[146:149], v[48:51]
	v_mfma_f32_16x16x32_bf16 v[44:47], v[104:107], v[138:141], v[44:47]
	v_mfma_f32_16x16x32_bf16 v[40:43], v[104:107], v[146:149], v[40:43]
	v_mfma_f32_16x16x32_bf16 v[28:31], v[64:67], v[174:177], v[28:31]
	v_mfma_f32_16x16x32_bf16 v[24:27], v[64:67], v[182:185], v[24:27]
	v_mfma_f32_16x16x32_bf16 v[20:23], v[72:75], v[174:177], v[20:23]
	v_mfma_f32_16x16x32_bf16 v[60:63], v[68:71], v[142:145], v[60:63]
	v_mfma_f32_16x16x32_bf16 v[56:59], v[68:71], v[170:173], v[56:59]
	v_mfma_f32_16x16x32_bf16 v[52:55], v[84:87], v[142:145], v[52:55]
	v_mfma_f32_16x16x32_bf16 v[48:51], v[84:87], v[170:173], v[48:51]
	v_mfma_f32_16x16x32_bf16 v[44:47], v[112:115], v[142:145], v[44:47]
	v_mfma_f32_16x16x32_bf16 v[40:43], v[112:115], v[170:173], v[40:43]
	v_mfma_f32_16x16x32_bf16 v[36:39], v[120:123], v[138:141], v[36:39]
	v_mfma_f32_16x16x32_bf16 v[32:35], v[120:123], v[146:149], v[32:35]
	v_mfma_f32_16x16x32_bf16 v[28:31], v[68:71], v[178:181], v[28:31]
	v_mfma_f32_16x16x32_bf16 v[24:27], v[68:71], v[186:189], v[24:27]
	v_mfma_f32_16x16x32_bf16 v[20:23], v[84:87], v[178:181], v[20:23]
	v_mfma_f32_16x16x32_bf16 v[16:19], v[72:75], v[182:185], v[16:19]
	v_mfma_f32_16x16x32_bf16 v[12:15], v[104:107], v[174:177], v[12:15]
	v_mfma_f32_16x16x32_bf16 v[8:11], v[104:107], v[182:185], v[8:11]
	v_mfma_f32_16x16x32_bf16 v[4:7], v[120:123], v[174:177], v[4:7]
	v_mfma_f32_16x16x32_bf16 v[0:3], v[120:123], v[182:185], v[0:3]
	v_mfma_f32_16x16x32_bf16 v[138:141], v[206:209], v[142:145], v[36:39]
	v_mfma_f32_16x16x32_bf16 v[142:145], v[206:209], v[170:173], v[32:35]
	v_mfma_f32_16x16x32_bf16 v[146:149], v[84:87], v[186:189], v[16:19]
	v_mfma_f32_16x16x32_bf16 v[170:173], v[112:115], v[178:181], v[12:15]
	v_mfma_f32_16x16x32_bf16 v[210:213], v[112:115], v[186:189], v[8:11]
	v_mfma_f32_16x16x32_bf16 v[174:177], v[206:209], v[178:181], v[4:7]
	v_mfma_f32_16x16x32_bf16 v[178:181], v[206:209], v[186:189], v[0:3]
	s_setprio 0
	s_barrier
; #define LDA(dst, b, h) _Pragma("unroll") for (int m = 0; m < 4; ++m) _Pragma("unroll") for (int k = 0; k < 2; ++k) \
;     dst[m][k] = *reinterpret_cast<const bf16x8*>((const char*)shm + aB + (((b) * 2 + (h)) * 16384 + (m * 2 + k) * 1024))
; #define LDB(dst, b, h) _Pragma("unroll") for (int n = 0; n < 2; ++n) _Pragma("unroll") for (int k = 0; k < 2; ++k) \
;     dst[n][k] = *reinterpret_cast<const bf16x8*>((const char*)shm + bB + (((b) * 2 + (h)) * 16384 + (n * 2 + k) * 1024))
; #define WAIT_L(n) asm volatile("s_waitcnt lgkmcnt(" #n ")" ::: "memory")
; #define BAR __builtin_amdgcn_s_barrier()
; #define SCHED __builtin_amdgcn_sched_barrier(0)
; template <int MODE> ...
;     ...
;       LDB(B0, 1, 0); LDB(B1, 1, 1); LDA(At, 1, 0); WAIT_L(0); BAR; MMA2(0, 0, 0, 1); BAR; SCHED;
;       LDA(At, 1, 1); WAIT_L(0); BAR; MMA2(1, 0, 1, 1); BAR; SCHED;
;     }
;     ...
;     if (wr == 0) BAR;
	ds_read_b128 v[12:15], v151 offset:32768
	ds_read_b128 v[16:19], v151 offset:33792
	ds_read_b128 v[182:185], v151 offset:34816
	ds_read_b128 v[186:189], v151 offset:35840
	ds_read_b128 v[206:209], v151 offset:49152
	ds_read_b128 v[214:217], v151 offset:50176
	ds_read_b128 v[218:221], v151 offset:51200
	ds_read_b128 v[234:237], v151 offset:52224
	ds_read_b128 v[0:3], v150 offset:32768
	ds_read_b128 v[4:7], v150 offset:33792
	ds_read_b128 v[8:11], v150 offset:34816
	ds_read_b128 v[32:35], v150 offset:35840
	ds_read_b128 v[36:39], v150 offset:36864
	ds_read_b128 v[238:241], v150 offset:37888
	ds_read_b128 v[242:245], v150 offset:38912
	ds_read_b128 v[246:249], v150 offset:39936
	s_waitcnt lgkmcnt(0)
	s_barrier
	s_setprio 1
	s_waitcnt lgkmcnt(0)
	v_mfma_f32_16x16x32_bf16 v[64:67], v[0:3], v[12:15], v[124:127]
	v_mfma_f32_16x16x32_bf16 v[68:71], v[242:245], v[182:185], v[96:99]
	v_mfma_f32_16x16x32_bf16 v[120:123], v[4:7], v[16:19], v[64:67]
	v_mfma_f32_16x16x32_bf16 v[64:67], v[0:3], v[182:185], v[222:225]
	v_mfma_f32_16x16x32_bf16 v[84:87], v[246:249], v[186:189], v[68:71]
	v_mfma_f32_16x16x32_bf16 v[68:71], v[0:3], v[206:209], v[92:95]
	v_mfma_f32_16x16x32_bf16 v[0:3], v[0:3], v[218:221], v[88:91]
	v_mfma_f32_16x16x32_bf16 v[88:91], v[4:7], v[234:237], v[0:3]
	v_mfma_f32_16x16x32_bf16 v[0:3], v[8:11], v[206:209], v[190:193]
	v_mfma_f32_16x16x32_bf16 v[124:127], v[4:7], v[186:189], v[64:67]
	v_mfma_f32_16x16x32_bf16 v[64:67], v[8:11], v[12:15], v[116:119]
	v_mfma_f32_16x16x32_bf16 v[72:75], v[32:35], v[214:217], v[0:3]
	v_mfma_f32_16x16x32_bf16 v[0:3], v[8:11], v[218:221], v[80:83]
	v_mfma_f32_16x16x32_bf16 v[112:115], v[32:35], v[16:19], v[64:67]
	v_mfma_f32_16x16x32_bf16 v[64:67], v[8:11], v[182:185], v[226:229]
	v_mfma_f32_16x16x32_bf16 v[92:95], v[32:35], v[234:237], v[0:3]
	v_mfma_f32_16x16x32_bf16 v[0:3], v[36:39], v[206:209], v[76:79]
	v_mfma_f32_16x16x32_bf16 v[116:119], v[32:35], v[186:189], v[64:67]
	v_mfma_f32_16x16x32_bf16 v[64:67], v[36:39], v[12:15], v[108:111]
	v_mfma_f32_16x16x32_bf16 v[76:79], v[238:241], v[214:217], v[0:3]
	v_mfma_f32_16x16x32_bf16 v[0:3], v[36:39], v[218:221], v[194:197]
	v_mfma_f32_16x16x32_bf16 v[104:107], v[238:241], v[16:19], v[64:67]
	v_mfma_f32_16x16x32_bf16 v[64:67], v[36:39], v[182:185], v[230:233]
	v_mfma_f32_16x16x32_bf16 v[96:99], v[238:241], v[234:237], v[0:3]
	v_mfma_f32_16x16x32_bf16 v[0:3], v[242:245], v[206:209], v[198:201]
	v_mfma_f32_16x16x32_bf16 v[108:111], v[238:241], v[186:189], v[64:67]
	v_mfma_f32_16x16x32_bf16 v[64:67], v[242:245], v[12:15], v[100:103]
	v_mfma_f32_16x16x32_bf16 v[80:83], v[246:249], v[214:217], v[0:3]
	v_mfma_f32_16x16x32_bf16 v[0:3], v[242:245], v[218:221], v[202:205]
	v_mfma_f32_16x16x32_bf16 v[64:67], v[246:249], v[16:19], v[64:67]
	v_mfma_f32_16x16x32_bf16 v[68:71], v[4:7], v[214:217], v[68:71]
	v_mfma_f32_16x16x32_bf16 v[100:103], v[246:249], v[234:237], v[0:3]
	s_setprio 0
	s_barrier
	ds_read_b128 v[190:193], v150 offset:49152
	ds_read_b128 v[194:197], v150 offset:50176
	ds_read_b128 v[198:201], v150 offset:51200
	ds_read_b128 v[202:205], v150 offset:52224
	ds_read_b128 v[222:225], v150 offset:53248
	ds_read_b128 v[226:229], v150 offset:54272
	ds_read_b128 v[230:233], v150 offset:55296
	ds_read_b128 v[238:241], v150 offset:56320
	s_waitcnt lgkmcnt(0)
	s_barrier
	s_setprio 1
	s_waitcnt lgkmcnt(0)
	v_mfma_f32_16x16x32_bf16 v[4:7], v[190:193], v[182:185], v[56:59]
	v_mfma_f32_16x16x32_bf16 v[8:11], v[198:201], v[182:185], v[48:51]
	v_mfma_f32_16x16x32_bf16 v[0:3], v[190:193], v[12:15], v[60:63]
	v_mfma_f32_16x16x32_bf16 v[32:35], v[194:197], v[186:189], v[4:7]
	v_mfma_f32_16x16x32_bf16 v[4:7], v[198:201], v[12:15], v[52:55]
	v_mfma_f32_16x16x32_bf16 v[36:39], v[202:205], v[186:189], v[8:11]
	v_mfma_f32_16x16x32_bf16 v[8:11], v[222:225], v[12:15], v[44:47]
	v_mfma_f32_16x16x32_bf16 v[12:15], v[230:233], v[12:15], v[138:141]
	v_mfma_f32_16x16x32_bf16 v[0:3], v[194:197], v[16:19], v[0:3]
	v_mfma_f32_16x16x32_bf16 v[4:7], v[202:205], v[16:19], v[4:7]
	v_mfma_f32_16x16x32_bf16 v[8:11], v[226:229], v[16:19], v[8:11]
	v_mfma_f32_16x16x32_bf16 v[12:15], v[238:241], v[16:19], v[12:15]
	v_mfma_f32_16x16x32_bf16 v[16:19], v[230:233], v[182:185], v[142:145]
	v_mfma_f32_16x16x32_bf16 v[24:27], v[190:193], v[218:221], v[24:27]
	v_mfma_f32_16x16x32_bf16 v[44:47], v[238:241], v[186:189], v[16:19]
	v_mfma_f32_16x16x32_bf16 v[16:19], v[190:193], v[206:209], v[28:31]
	v_mfma_f32_16x16x32_bf16 v[48:51], v[194:197], v[234:237], v[24:27]
	v_mfma_f32_16x16x32_bf16 v[24:27], v[198:201], v[218:221], v[146:149]
	v_mfma_f32_16x16x32_bf16 v[28:31], v[222:225], v[218:221], v[210:213]
	v_mfma_f32_16x16x32_bf16 v[40:43], v[222:225], v[182:185], v[40:43]
	v_mfma_f32_16x16x32_bf16 v[20:23], v[198:201], v[206:209], v[20:23]
	v_mfma_f32_16x16x32_bf16 v[52:55], v[202:205], v[234:237], v[24:27]
	v_mfma_f32_16x16x32_bf16 v[24:27], v[222:225], v[206:209], v[170:173]
	v_mfma_f32_16x16x32_bf16 v[56:59], v[226:229], v[234:237], v[28:31]
	v_mfma_f32_16x16x32_bf16 v[28:31], v[230:233], v[206:209], v[174:177]
	v_mfma_f32_16x16x32_bf16 v[60:63], v[230:233], v[218:221], v[178:181]
	v_mfma_f32_16x16x32_bf16 v[40:43], v[226:229], v[186:189], v[40:43]
	v_mfma_f32_16x16x32_bf16 v[16:19], v[194:197], v[214:217], v[16:19]
	v_mfma_f32_16x16x32_bf16 v[20:23], v[202:205], v[214:217], v[20:23]
	v_mfma_f32_16x16x32_bf16 v[24:27], v[226:229], v[214:217], v[24:27]
	v_mfma_f32_16x16x32_bf16 v[28:31], v[238:241], v[214:217], v[28:31]
	v_mfma_f32_16x16x32_bf16 v[60:63], v[238:241], v[234:237], v[60:63]
	s_setprio 0
	s_barrier
	s_and_saveexec_b64 s[60:61], s[6:7]
	s_cbranch_execz .LBB0_851
	s_barrier
